# attention steady loops unrolled x6: K and V ring slots static, all fragment ds_read addresses as immediate offsets (16 address VALU per step pair removed)
# baseline (speedup 1.0000x reference)
; __device__ __forceinline__ unsigned cvt_pk_bf16(float lo, float hi) { unsigned r; asm volatile("v_cvt_pk_bf16_f32 %0, %1, %2" : "=v"(r) : "v"(lo), "v"(hi)); return r; }
; __device__ __forceinline__ float silu_f(float g) { return g * __builtin_amdgcn_rcpf(1.0f + __builtin_amdgcn_exp2f(-1.4426950408889634f * g)); }
;     __device__ __forceinline__ void operator()(const f32x4 (&acc)[2][2][4][2], const Unit& u, int wr, int wc, int fr, int fq) const {
;         const int row0 = u.pm * BM + wr * 64 + fr, col0 = u.pn * 128 + wc * 32 + 8 * fq;
; #pragma unroll
;         for (int ai = 0; ai < 2; ++ai)
; #pragma unroll
;             for (int m = 0; m < 4; ++m) {
;                 bf16_t* rowp = H + (size_t)(row0 + ai * HALF + m * 16) * DFF + col0;
;                 const f32x4 g0 = acc[ai][0][m][0], g1 = acc[ai][0][m][1], u0 = acc[ai][1][m][0], u1 = acc[ai][1][m][1];
;                 u32x4 w;
;                 w.x = cvt_pk_bf16(silu_f(g0[0]) * u0[0], silu_f(g0[1]) * u0[1]); w.y = cvt_pk_bf16(silu_f(g0[2]) * u0[2], silu_f(g0[3]) * u0[3]);
;                 w.z = cvt_pk_bf16(silu_f(g1[0]) * u1[0], silu_f(g1[1]) * u1[1]); w.w = cvt_pk_bf16(silu_f(g1[2]) * u1[2], silu_f(g1[3]) * u1[3]);
;                 *(u32x4*)rowp = w;
.LBB0_327:
	v_exp_f32_e64 v154, -v125
	v_lshl_or_b32 v144, s42, 7, v148
	v_lshl_add_u32 v150, s6, 8, v146
	v_add_f32_e32 v154, 1.0, v154
	v_rcp_f32_e32 v154, v154
	v_exp_f32_e64 v151, -v124
	v_mul_lo_u32 v156, v150, s47
	v_lshl_add_u32 v156, v144, 1, v156
	v_mul_f32_e32 v152, v125, v154
	v_exp_f32_e64 v153, -v126
	v_exp_f32_e64 v154, -v127
	v_add_f32_e32 v151, 1.0, v151
	v_rcp_f32_e32 v151, v151
	v_add_f32_e32 v153, 1.0, v153
	v_add_f32_e32 v154, 1.0, v154
	v_rcp_f32_e32 v153, v153
	v_rcp_f32_e32 v154, v154
	v_mul_f32_e32 v151, v124, v151
	v_mul_f32_e32 v151, v151, v92
	v_mul_f32_e32 v152, v152, v93
	v_cvt_pk_bf16_f32 v152, v151, v152
	v_mul_f32_e32 v151, v126, v153
	v_mul_f32_e32 v153, v127, v154
	v_exp_f32_e64 v154, -v120
	v_exp_f32_e64 v155, -v121
	v_mul_f32_e32 v151, v151, v94
	v_mul_f32_e32 v153, v153, v95
	v_add_f32_e32 v154, 1.0, v154
	v_add_f32_e32 v155, 1.0, v155
	v_rcp_f32_e32 v154, v154
	v_rcp_f32_e32 v155, v155
	v_cvt_pk_bf16_f32 v153, v151, v153
	v_mul_f32_e32 v151, v120, v154
	v_mul_f32_e32 v154, v121, v155
	v_exp_f32_e64 v155, -v122
	v_exp_f32_e64 v158, -v123
	v_mul_f32_e32 v151, v151, v88
	v_mul_f32_e32 v154, v154, v89
	v_add_f32_e32 v155, 1.0, v155
	v_add_f32_e32 v158, 1.0, v158
	v_rcp_f32_e32 v155, v155
	v_rcp_f32_e32 v158, v158
	v_cvt_pk_bf16_f32 v154, v151, v154
	s_add_u32 s34, s25, 0xffffff00
	v_mul_f32_e32 v151, v122, v155
	v_mul_f32_e32 v155, v123, v158
	v_mul_f32_e32 v155, v155, v91
	v_mul_f32_e32 v151, v151, v90
	v_cvt_pk_bf16_f32 v155, v151, v155
	global_store_dwordx4 v156, v[152:155], s[16:17]
	s_nop 1
	v_exp_f32_e64 v154, -v116
	v_exp_f32_e64 v155, -v117
	v_add_f32_e32 v151, 1.0, v154
	v_add_f32_e32 v154, 1.0, v155
	v_rcp_f32_e32 v154, v154
	v_exp_f32_e64 v153, -v118
	v_mul_f32_e32 v152, v117, v154
	v_exp_f32_e64 v154, -v119
	v_rcp_f32_e32 v151, v151
	v_add_f32_e32 v153, 1.0, v153
	v_rcp_f32_e32 v153, v153
	v_add_f32_e32 v154, 1.0, v154
	v_rcp_f32_e32 v154, v154
	v_mul_f32_e32 v151, v116, v151
	v_mul_f32_e32 v151, v151, v84
	v_mul_f32_e32 v152, v152, v85
	v_cvt_pk_bf16_f32 v152, v151, v152
	v_mul_f32_e32 v151, v118, v153
	v_mul_f32_e32 v153, v119, v154
	v_exp_f32_e64 v154, -v112
	v_exp_f32_e64 v155, -v113
	v_mul_f32_e32 v151, v151, v86
	v_mul_f32_e32 v153, v153, v87
	v_add_f32_e32 v154, 1.0, v154
	v_add_f32_e32 v155, 1.0, v155
	v_rcp_f32_e32 v154, v154
	v_rcp_f32_e32 v155, v155
	v_cvt_pk_bf16_f32 v153, v151, v153
	v_exp_f32_e64 v158, -v115
	v_mul_f32_e32 v151, v112, v154
	v_mul_f32_e32 v154, v113, v155
	v_exp_f32_e64 v155, -v114
	v_add_f32_e32 v158, 1.0, v158
	v_rcp_f32_e32 v158, v158
	v_mul_f32_e32 v151, v151, v80
	v_add_f32_e32 v155, 1.0, v155
	v_rcp_f32_e32 v155, v155
	v_mul_f32_e32 v154, v154, v81
	v_cvt_pk_bf16_f32 v154, v151, v154
	s_addc_u32 s35, s51, -1
	v_mul_f32_e32 v151, v114, v155
	v_mul_f32_e32 v155, v115, v158
	v_mul_f32_e32 v155, v155, v83
	v_mul_f32_e32 v151, v151, v82
	v_cvt_pk_bf16_f32 v155, v151, v155
	s_mul_i32 s98, s47, 16
	s_add_u32 s98, s16, s98
	s_addc_u32 s99, s17, 0
	global_store_dwordx4 v156, v[152:155], s[98:99]
	s_nop 1
	v_exp_f32_e64 v154, -v108
	v_exp_f32_e64 v155, -v109
	v_add_f32_e32 v151, 1.0, v154
	v_add_f32_e32 v154, 1.0, v155
	v_rcp_f32_e32 v154, v154
	v_exp_f32_e64 v153, -v110
	v_mul_f32_e32 v152, v109, v154
	v_exp_f32_e64 v154, -v111
	v_rcp_f32_e32 v151, v151
	v_add_f32_e32 v153, 1.0, v153
	v_rcp_f32_e32 v153, v153
	v_add_f32_e32 v154, 1.0, v154
	v_rcp_f32_e32 v154, v154
	v_mul_f32_e32 v151, v108, v151
	v_mul_f32_e32 v151, v151, v76
	v_mul_f32_e32 v152, v152, v77
	v_cvt_pk_bf16_f32 v152, v151, v152
	v_mul_f32_e32 v151, v110, v153
	v_mul_f32_e32 v153, v111, v154
	v_exp_f32_e64 v154, -v104
	v_exp_f32_e64 v155, -v105
	v_mul_f32_e32 v151, v151, v78
	v_mul_f32_e32 v153, v153, v79
	v_add_f32_e32 v154, 1.0, v154
	v_add_f32_e32 v155, 1.0, v155
	v_rcp_f32_e32 v154, v154
	v_rcp_f32_e32 v155, v155
	v_cvt_pk_bf16_f32 v153, v151, v153
	v_exp_f32_e64 v158, -v107
	v_mul_f32_e32 v151, v104, v154
	v_mul_f32_e32 v154, v105, v155
	v_exp_f32_e64 v155, -v106
	v_add_f32_e32 v158, 1.0, v158
	v_rcp_f32_e32 v158, v158
	v_mul_f32_e32 v151, v151, v72
	v_add_f32_e32 v155, 1.0, v155
	v_rcp_f32_e32 v155, v155
	v_mul_f32_e32 v154, v154, v73
	v_cvt_pk_bf16_f32 v154, v151, v154
	s_andn2_b64 vcc, exec, s[36:37]
	v_mul_f32_e32 v151, v106, v155
	v_mul_f32_e32 v155, v107, v158
	v_mul_f32_e32 v155, v155, v75
	v_mul_f32_e32 v151, v151, v74
	v_cvt_pk_bf16_f32 v155, v151, v155
	s_mul_i32 s98, s47, 32
	s_add_u32 s98, s16, s98
	s_addc_u32 s99, s17, 0
	global_store_dwordx4 v156, v[152:155], s[98:99]
	s_nop 1
	v_exp_f32_e64 v154, -v100
	v_exp_f32_e64 v155, -v101
	v_add_f32_e32 v151, 1.0, v154
	v_add_f32_e32 v154, 1.0, v155
	v_rcp_f32_e32 v154, v154
	v_exp_f32_e64 v153, -v102
	v_mul_f32_e32 v152, v101, v154
	v_exp_f32_e64 v154, -v103
	v_rcp_f32_e32 v151, v151
	v_add_f32_e32 v153, 1.0, v153
	v_rcp_f32_e32 v153, v153
	v_add_f32_e32 v154, 1.0, v154
	v_rcp_f32_e32 v154, v154
	v_mul_f32_e32 v151, v100, v151
	v_mul_f32_e32 v151, v151, v68
	v_mul_f32_e32 v152, v152, v69
	v_cvt_pk_bf16_f32 v152, v151, v152
	v_mul_f32_e32 v151, v102, v153
	v_mul_f32_e32 v153, v103, v154
	v_exp_f32_e64 v154, -v96
	v_exp_f32_e64 v155, -v97
	v_mul_f32_e32 v151, v151, v70
	v_mul_f32_e32 v153, v153, v71
	v_add_f32_e32 v154, 1.0, v154
	v_add_f32_e32 v155, 1.0, v155
	v_rcp_f32_e32 v154, v154
	v_rcp_f32_e32 v155, v155
	v_cvt_pk_bf16_f32 v153, v151, v153
	v_exp_f32_e64 v158, -v99
	v_mul_f32_e32 v151, v96, v154
	v_mul_f32_e32 v154, v97, v155
	v_exp_f32_e64 v155, -v98
	v_add_f32_e32 v158, 1.0, v158
	v_rcp_f32_e32 v158, v158
	v_mul_f32_e32 v151, v151, v64
	v_add_f32_e32 v155, 1.0, v155
	v_rcp_f32_e32 v155, v155
	v_mul_f32_e32 v154, v154, v65
; __device__ __forceinline__ unsigned cvt_pk_bf16(float lo, float hi) { unsigned r; asm volatile("v_cvt_pk_bf16_f32 %0, %1, %2" : "=v"(r) : "v"(lo), "v"(hi)); return r; }
; __device__ __forceinline__ float silu_f(float g) { return g * __builtin_amdgcn_rcpf(1.0f + __builtin_amdgcn_exp2f(-1.4426950408889634f * g)); }
;     __device__ __forceinline__ void operator()(const f32x4 (&acc)[2][2][4][2], const Unit& u, int wr, int wc, int fr, int fq) const {
;     ...
; #pragma unroll
;         for (int ai = 0; ai < 2; ++ai)
; #pragma unroll
;             for (int m = 0; m < 4; ++m) {
;                 bf16_t* rowp = H + (size_t)(row0 + ai * HALF + m * 16) * DFF + col0;
;                 const f32x4 g0 = acc[ai][0][m][0], g1 = acc[ai][0][m][1], u0 = acc[ai][1][m][0], u1 = acc[ai][1][m][1];
;                 u32x4 w;
;                 w.x = cvt_pk_bf16(silu_f(g0[0]) * u0[0], silu_f(g0[1]) * u0[1]); w.y = cvt_pk_bf16(silu_f(g0[2]) * u0[2], silu_f(g0[3]) * u0[3]);
;                 w.z = cvt_pk_bf16(silu_f(g1[0]) * u1[0], silu_f(g1[1]) * u1[1]); w.w = cvt_pk_bf16(silu_f(g1[2]) * u1[2], silu_f(g1[3]) * u1[3]);
;                 *(u32x4*)rowp = w;
;             }
	v_cvt_pk_bf16_f32 v154, v151, v154
	v_mul_f32_e32 v151, v98, v155
	v_mul_f32_e32 v155, v99, v158
	v_mul_f32_e32 v155, v155, v67
	v_mul_f32_e32 v151, v151, v66
	v_cvt_pk_bf16_f32 v155, v151, v155
	s_mul_i32 s98, s47, 48
	s_add_u32 s98, s16, s98
	s_addc_u32 s99, s17, 0
	global_store_dwordx4 v156, v[152:155], s[98:99]
	s_nop 1
	v_exp_f32_e64 v154, -v60
	v_exp_f32_e64 v155, -v61
	v_add_f32_e32 v151, 1.0, v154
	v_add_f32_e32 v154, 1.0, v155
	v_rcp_f32_e32 v154, v154
	v_exp_f32_e64 v153, -v62
	v_mul_f32_e32 v152, v61, v154
	v_exp_f32_e64 v154, -v63
	v_rcp_f32_e32 v151, v151
	v_add_f32_e32 v153, 1.0, v153
	v_rcp_f32_e32 v153, v153
	v_add_f32_e32 v154, 1.0, v154
	v_rcp_f32_e32 v154, v154
	v_mul_f32_e32 v151, v60, v151
	v_mul_f32_e32 v151, v151, v28
	v_mul_f32_e32 v152, v152, v29
	v_cvt_pk_bf16_f32 v152, v151, v152
	v_mul_f32_e32 v151, v62, v153
	v_mul_f32_e32 v153, v63, v154
	v_exp_f32_e64 v154, -v56
	v_exp_f32_e64 v155, -v57
	v_mul_f32_e32 v151, v151, v30
	v_mul_f32_e32 v153, v153, v31
	v_add_f32_e32 v154, 1.0, v154
	v_add_f32_e32 v155, 1.0, v155
	v_rcp_f32_e32 v154, v154
	v_rcp_f32_e32 v155, v155
	v_cvt_pk_bf16_f32 v153, v151, v153
	v_exp_f32_e64 v158, -v59
	v_mul_f32_e32 v151, v56, v154
	v_mul_f32_e32 v154, v57, v155
	v_exp_f32_e64 v155, -v58
	v_add_f32_e32 v158, 1.0, v158
	v_rcp_f32_e32 v158, v158
	v_mul_f32_e32 v151, v151, v24
	v_add_f32_e32 v155, 1.0, v155
	v_rcp_f32_e32 v155, v155
	v_mul_f32_e32 v154, v154, v25
	v_cvt_pk_bf16_f32 v154, v151, v154
	v_mul_f32_e32 v151, v58, v155
	v_mul_f32_e32 v155, v59, v158
	v_mul_f32_e32 v155, v155, v27
	v_mul_f32_e32 v151, v151, v26
	v_cvt_pk_bf16_f32 v155, v151, v155
	s_mul_i32 s98, s47, 128
	s_add_u32 s98, s16, s98
	s_addc_u32 s99, s17, 0
	global_store_dwordx4 v156, v[152:155], s[98:99]
	s_nop 1
	v_exp_f32_e64 v154, -v52
	v_exp_f32_e64 v155, -v53
	v_add_f32_e32 v151, 1.0, v154
	v_add_f32_e32 v154, 1.0, v155
	v_rcp_f32_e32 v154, v154
	v_exp_f32_e64 v153, -v54
	v_mul_f32_e32 v152, v53, v154
	v_exp_f32_e64 v154, -v55
	v_rcp_f32_e32 v151, v151
	v_add_f32_e32 v153, 1.0, v153
	v_rcp_f32_e32 v153, v153
	v_add_f32_e32 v154, 1.0, v154
	v_rcp_f32_e32 v154, v154
	v_mul_f32_e32 v151, v52, v151
	v_mul_f32_e32 v151, v151, v20
	v_mul_f32_e32 v152, v152, v21
	v_cvt_pk_bf16_f32 v152, v151, v152
	v_mul_f32_e32 v151, v54, v153
	v_mul_f32_e32 v153, v55, v154
	v_exp_f32_e64 v154, -v48
	v_exp_f32_e64 v155, -v49
	v_mul_f32_e32 v151, v151, v22
	v_mul_f32_e32 v153, v153, v23
	v_add_f32_e32 v154, 1.0, v154
	v_add_f32_e32 v155, 1.0, v155
	v_rcp_f32_e32 v154, v154
	v_rcp_f32_e32 v155, v155
	v_cvt_pk_bf16_f32 v153, v151, v153
	v_exp_f32_e64 v158, -v51
	v_mul_f32_e32 v151, v48, v154
	v_mul_f32_e32 v154, v49, v155
	v_exp_f32_e64 v155, -v50
	v_add_f32_e32 v158, 1.0, v158
	v_rcp_f32_e32 v158, v158
	v_mul_f32_e32 v151, v151, v16
	v_add_f32_e32 v155, 1.0, v155
	v_rcp_f32_e32 v155, v155
	v_mul_f32_e32 v154, v154, v17
	v_cvt_pk_bf16_f32 v154, v151, v154
	v_mul_f32_e32 v151, v50, v155
	v_mul_f32_e32 v155, v51, v158
	v_mul_f32_e32 v155, v155, v19
	v_mul_f32_e32 v151, v151, v18
	v_cvt_pk_bf16_f32 v155, v151, v155
	s_mul_i32 s98, s47, 144
	s_add_u32 s98, s16, s98
	s_addc_u32 s99, s17, 0
	global_store_dwordx4 v156, v[152:155], s[98:99]
	s_nop 1
	v_exp_f32_e64 v154, -v44
	v_exp_f32_e64 v155, -v45
	v_add_f32_e32 v151, 1.0, v154
	v_add_f32_e32 v154, 1.0, v155
	v_rcp_f32_e32 v154, v154
	v_exp_f32_e64 v153, -v46
	v_mul_f32_e32 v152, v45, v154
	v_exp_f32_e64 v154, -v47
	v_rcp_f32_e32 v151, v151
	v_add_f32_e32 v153, 1.0, v153
	v_rcp_f32_e32 v153, v153
	v_add_f32_e32 v154, 1.0, v154
	v_rcp_f32_e32 v154, v154
	v_mul_f32_e32 v151, v44, v151
	v_mul_f32_e32 v151, v151, v12
	v_mul_f32_e32 v152, v152, v13
	v_cvt_pk_bf16_f32 v152, v151, v152
	v_mul_f32_e32 v151, v46, v153
	v_mul_f32_e32 v153, v47, v154
	v_exp_f32_e64 v154, -v40
	v_exp_f32_e64 v155, -v41
	v_mul_f32_e32 v151, v151, v14
	v_mul_f32_e32 v153, v153, v15
	v_add_f32_e32 v154, 1.0, v154
	v_add_f32_e32 v155, 1.0, v155
	v_rcp_f32_e32 v154, v154
	v_rcp_f32_e32 v155, v155
	v_cvt_pk_bf16_f32 v153, v151, v153
	v_exp_f32_e64 v158, -v43
	v_mul_f32_e32 v151, v40, v154
	v_mul_f32_e32 v154, v41, v155
	v_exp_f32_e64 v155, -v42
	v_add_f32_e32 v158, 1.0, v158
	v_rcp_f32_e32 v158, v158
	v_mul_f32_e32 v151, v151, v8
	v_add_f32_e32 v155, 1.0, v155
	v_rcp_f32_e32 v155, v155
	v_mul_f32_e32 v154, v154, v9
	v_cvt_pk_bf16_f32 v154, v151, v154
	v_mul_f32_e32 v151, v42, v155
	v_mul_f32_e32 v155, v43, v158
	v_mul_f32_e32 v151, v151, v10
	v_mul_f32_e32 v155, v155, v11
	v_cvt_pk_bf16_f32 v155, v151, v155
	s_mul_i32 s98, s47, 160
	s_add_u32 s98, s16, s98
	s_addc_u32 s99, s17, 0
	global_store_dwordx4 v156, v[152:155], s[98:99]
	s_nop 0
	v_exp_f32_e64 v151, -v36
	v_exp_f32_e64 v152, -v37
	v_add_f32_e32 v150, 1.0, v151
	v_rcp_f32_e32 v153, v150
	v_add_f32_e32 v150, 1.0, v152
	v_rcp_f32_e32 v152, v150
	v_exp_f32_e64 v144, -v38
	v_exp_f32_e64 v145, -v39
	v_mul_f32_e32 v142, v36, v153
	v_mul_f32_e32 v143, v37, v152
	v_add_f32_e32 v144, 1.0, v144
	v_add_f32_e32 v145, 1.0, v145
	v_rcp_f32_e32 v144, v144
	v_rcp_f32_e32 v145, v145
	v_mul_f32_e32 v142, v142, v4
	v_mul_f32_e32 v143, v143, v5
	v_cvt_pk_bf16_f32 v142, v142, v143
	v_mul_f32_e32 v143, v38, v144
	v_mul_f32_e32 v144, v39, v145
	v_exp_f32_e64 v145, -v32
	v_exp_f32_e64 v152, -v33
	v_mul_f32_e32 v143, v143, v6
	v_mul_f32_e32 v144, v144, v7
	v_add_f32_e32 v145, 1.0, v145
	v_add_f32_e32 v152, 1.0, v152
	v_rcp_f32_e32 v145, v145
	v_rcp_f32_e32 v152, v152
	v_cvt_pk_bf16_f32 v143, v143, v144
	v_mul_f32_e32 v144, v32, v145
	v_mul_f32_e32 v145, v33, v152
	v_exp_f32_e64 v152, -v34
	v_exp_f32_e64 v153, -v35
	v_mul_f32_e32 v144, v144, v0
	v_mul_f32_e32 v145, v145, v1
	v_add_f32_e32 v152, 1.0, v152
	v_rcp_f32_e32 v152, v152
	v_add_f32_e32 v153, 1.0, v153
	v_rcp_f32_e32 v153, v153
	v_cvt_pk_bf16_f32 v144, v144, v145
	v_mul_f32_e32 v145, v34, v152
	v_mul_f32_e32 v145, v145, v2
	v_mul_f32_e32 v152, v35, v153
	v_mul_f32_e32 v152, v152, v3
	v_cvt_pk_bf16_f32 v145, v145, v152
	s_mul_i32 s98, s47, 176
	s_add_u32 s98, s16, s98
	s_addc_u32 s99, s17, 0
	global_store_dwordx4 v156, v[142:145], s[98:99]
	s_cbranch_vccnz .LBB0_318
	s_andn2_b64 vcc, exec, s[10:11]
	s_cbranch_vccnz .LBB0_317
	s_barrier
	s_branch .LBB0_317

.Lst0_loop:
	s_cmp_lg_u32 s41, 0
	s_cbranch_scc1 .Lst0_single
	s_and_b32 s2, s20, 0xffff
	s_cmp_lg_u32 s2, 0xc000
	s_cbranch_scc1 .Lst0_single
	s_cmp_lt_u32 s21, 50
	s_cbranch_scc1 .Lst0_u6

.Lst0_u6:
	v_add_u32_e32 v236, 0x10000, v206
	v_add_u32_e32 v237, 0x10000, v207
	v_add_u32_e32 v238, 0x10000, v208
	v_add_u32_e32 v239, 0x10000, v209
.Lst0_u6_loop:
	s_lshl_b32 s46, s41, 14
	s_add_i32 s46, s58, s46
	s_mov_b32 m0, s46
	s_nop 0
	global_load_lds_dwordx4 v198, s[98:99]
	s_add_i32 m0, s46, 0x400
	s_nop 0
	global_load_lds_dwordx4 v194, s[98:99]
	s_add_i32 s48, s20, 0xffffc000
	s_and_b32 s48, s48, 0x8000
	s_add_i32 s48, s58, s48
	s_add_i32 m0, s48, 0xc000
	s_nop 0
	global_load_lds_dwordx4 v196, s[100:101]
	s_add_i32 m0, s48, 0xc400
	s_nop 0
	global_load_lds_dwordx4 v192, s[100:101]
	s_add_i32 s46, s41, 1
	s_cmp_lg_u32 s41, 2
	s_cselect_b32 s41, s46, 0
	s_lshl_b32 s46, s41, 14
	s_add_i32 s49, s46, 0
	s_add_i32 s46, s20, 0xffff4000
	ds_read_b128 v[96:99], v205 offset:16384
	ds_read_b128 v[100:103], v205 offset:24576
	s_waitcnt lgkmcnt(0)
	v_mfma_f32_32x32x16_bf16 v[112:127], v[96:99], v[160:163], 0
	ds_read_b128 v[128:131], v211 offset:16384
	ds_read_b128 v[132:135], v211 offset:24576
	ds_read_b128 v[136:139], v212 offset:16384
	s_and_b32 s46, s46, 0x8000
	s_add_i32 s48, s46, 0
	v_exp_f32_e32 v140, v48
	v_exp_f32_e32 v141, v49
	v_exp_f32_e32 v142, v50
	v_exp_f32_e32 v143, v51
	ds_read_b128 v[48:51], v212 offset:24576
	v_mfma_f32_32x32x16_bf16 v[96:111], v[100:103], v[160:163], 0
	v_exp_f32_e32 v144, v52
	v_exp_f32_e32 v145, v53
	v_exp_f32_e32 v146, v54
	v_exp_f32_e32 v147, v55
	s_waitcnt lgkmcnt(0)
	v_mfma_f32_32x32x16_bf16 v[112:127], v[128:131], v[164:167], v[112:127]
	ds_read_b128 v[52:55], v213 offset:16384
	v_exp_f32_e32 v148, v56
	v_exp_f32_e32 v149, v57
	v_exp_f32_e32 v150, v58
	v_exp_f32_e32 v151, v59
	v_mfma_f32_32x32x16_bf16 v[96:111], v[132:135], v[164:167], v[96:111]
	ds_read_b128 v[56:59], v213 offset:24576
	v_exp_f32_e32 v128, v60
	v_exp_f32_e32 v129, v61
	v_exp_f32_e32 v130, v62
	v_exp_f32_e32 v131, v63
	v_mfma_f32_32x32x16_bf16 v[112:127], v[136:139], v[168:171], v[112:127]
	ds_read_b128 v[60:63], v206 offset:49152
	v_exp_f32_e32 v132, v32
	v_exp_f32_e32 v133, v33
	v_exp_f32_e32 v134, v34
	v_exp_f32_e32 v135, v35
	v_mfma_f32_32x32x16_bf16 v[96:111], v[48:51], v[168:171], v[96:111]
	ds_read_b128 v[32:35], v206 offset:53248
	v_exp_f32_e32 v136, v36
	v_exp_f32_e32 v137, v37
	v_exp_f32_e32 v138, v38
	v_exp_f32_e32 v139, v39
	s_waitcnt lgkmcnt(0)
	v_mfma_f32_32x32x16_bf16 v[112:127], v[52:55], v[172:175], v[112:127]
	ds_read_b128 v[36:39], v206 offset:57344
	v_exp_f32_e32 v152, v40
	v_exp_f32_e32 v153, v41
	v_exp_f32_e32 v154, v42
	v_exp_f32_e32 v155, v43
	v_mfma_f32_32x32x16_bf16 v[96:111], v[56:59], v[172:175], v[96:111]
	ds_read_b128 v[40:43], v206 offset:61440
	v_exp_f32_e32 v156, v44
	v_exp_f32_e32 v157, v45
	v_exp_f32_e32 v158, v46
	v_exp_f32_e32 v159, v47
	v_cvt_pk_bf16_f32 v44, v140, v141
	v_cvt_pk_bf16_f32 v45, v142, v143
	v_cvt_pk_bf16_f32 v46, v144, v145
	v_cvt_pk_bf16_f32 v47, v146, v147
	s_nop 1
	v_mfma_f32_32x32x16_bf16 v[80:95], v[60:63], v[44:47], v[80:95]
	ds_read_b128 v[48:51], v207 offset:49152
	v_cvt_pk_bf16_f32 v52, v148, v149
	v_cvt_pk_bf16_f32 v53, v150, v151
	v_cvt_pk_bf16_f32 v54, v128, v129
	v_cvt_pk_bf16_f32 v55, v130, v131
	v_mfma_f32_32x32x16_bf16 v[64:79], v[32:35], v[44:47], v[64:79]
	ds_read_b128 v[56:59], v207 offset:53248
	v_pk_add_f32 v[62:63], v[146:147], v[142:143]
	v_pk_add_f32 v[60:61], v[144:145], v[140:141]
	s_waitcnt lgkmcnt(0)
	v_mfma_f32_32x32x16_bf16 v[16:31], v[36:39], v[44:47], v[16:31]
	ds_read_b128 v[32:35], v207 offset:57344
	v_add_f32_e64 v62, v150, v62
	v_add_f32_e64 v63, v151, v63
	v_add_f32_e64 v60, v148, v60
	v_add_f32_e64 v61, v149, v61
	v_pk_add_f32 v[62:63], v[130:131], v[62:63]
	v_pk_add_f32 v[60:61], v[128:129], v[60:61]
	v_mfma_f32_32x32x16_bf16 v[0:15], v[40:43], v[44:47], v[0:15]
	ds_read_b128 v[36:39], v207 offset:61440
	v_mfma_f32_32x32x16_bf16 v[80:95], v[48:51], v[52:55], v[80:95]
	ds_read_b128 v[40:43], v208 offset:49152
	v_cvt_pk_bf16_f32 v44, v132, v133
	v_cvt_pk_bf16_f32 v45, v134, v135
	v_cvt_pk_bf16_f32 v46, v136, v137
	v_cvt_pk_bf16_f32 v47, v138, v139
	v_mfma_f32_32x32x16_bf16 v[64:79], v[56:59], v[52:55], v[64:79]
	ds_read_b128 v[48:51], v208 offset:53248
	v_add_f32_e64 v62, v134, v62
	v_add_f32_e64 v63, v135, v63
	v_add_f32_e64 v60, v132, v60
	v_add_f32_e64 v61, v133, v61
	v_pk_add_f32 v[62:63], v[138:139], v[62:63]
	v_pk_add_f32 v[60:61], v[136:137], v[60:61]
	s_waitcnt lgkmcnt(0)
	v_mfma_f32_32x32x16_bf16 v[16:31], v[32:35], v[52:55], v[16:31]
	ds_read_b128 v[56:59], v208 offset:57344
	v_add_f32_e64 v62, v154, v62
	v_add_f32_e64 v63, v155, v63
	v_add_f32_e64 v60, v152, v60
	v_add_f32_e64 v61, v153, v61
	v_pk_add_f32 v[130:131], v[158:159], v[62:63]
	v_pk_add_f32 v[128:129], v[156:157], v[60:61]
	v_mfma_f32_32x32x16_bf16 v[0:15], v[36:39], v[52:55], v[0:15]
	ds_read_b128 v[32:35], v208 offset:61440
	v_mfma_f32_32x32x16_bf16 v[80:95], v[40:43], v[44:47], v[80:95]
	ds_read_b128 v[36:39], v209 offset:49152
	v_cvt_pk_bf16_f32 v52, v152, v153
	v_cvt_pk_bf16_f32 v53, v154, v155
	v_cvt_pk_bf16_f32 v54, v156, v157
	v_cvt_pk_bf16_f32 v55, v158, v159
	v_mfma_f32_32x32x16_bf16 v[64:79], v[48:51], v[44:47], v[64:79]
	ds_read_b128 v[40:43], v209 offset:53248
	s_waitcnt lgkmcnt(0)
	v_mfma_f32_32x32x16_bf16 v[16:31], v[56:59], v[44:47], v[16:31]
	ds_read_b128 v[48:51], v209 offset:57344
	v_mfma_f32_32x32x16_bf16 v[0:15], v[32:35], v[44:47], v[0:15]
	ds_read_b128 v[56:59], v209 offset:61440
	v_mfma_f32_32x32x16_bf16 v[80:95], v[36:39], v[52:55], v[80:95]
	v_mfma_f32_32x32x16_bf16 v[64:79], v[40:43], v[52:55], v[64:79]
	s_waitcnt lgkmcnt(0)
	v_mfma_f32_32x32x16_bf16 v[16:31], v[48:51], v[52:55], v[16:31]
	v_mfma_f32_32x32x16_bf16 v[0:15], v[56:59], v[52:55], v[0:15]
	s_waitcnt vmcnt(4) lgkmcnt(0)
	s_barrier
	s_add_u32 s68, s98, 0x18000
	s_addc_u32 s69, s99, 0
	s_add_i32 s49, s49, s57
	s_mov_b32 m0, s49
	s_nop 0
	global_load_lds_dwordx4 v198, s[68:69]
	s_add_i32 m0, s49, 0x400
	s_nop 0
	global_load_lds_dwordx4 v194, s[68:69]
	s_add_u32 s44, s100, 0x80
	s_addc_u32 s45, s101, 0
	s_and_b32 s49, s20, 0xc000
	s_add_i32 s49, s58, s49
	s_add_i32 m0, s49, 0xc000
	s_nop 0
	global_load_lds_dwordx4 v196, s[44:45]
	s_add_i32 m0, s49, 0xc400
	s_nop 0
	global_load_lds_dwordx4 v192, s[44:45]
	s_add_i32 s48, s48, 0xc000
	s_add_i32 s44, s41, 1
	s_cmp_lg_u32 s41, 2
	s_cselect_b32 s41, s44, 0
	s_lshl_b32 s44, s41, 14
	s_add_i32 s44, s44, 0
	v_exp_f32_e32 v144, v112
	ds_read_b128 v[32:35], v205 offset:32768
	ds_read_b128 v[36:39], v205 offset:40960
	s_waitcnt lgkmcnt(0)
	v_mfma_f32_32x32x16_bf16 v[48:63], v[32:35], v[160:163], 0
	ds_read_b128 v[132:135], v211 offset:32768
	ds_read_b128 v[136:139], v211 offset:40960
	ds_read_b128 v[140:143], v212 offset:32768
	v_exp_f32_e32 v145, v113
	v_exp_f32_e32 v146, v114
	v_exp_f32_e32 v147, v115
	ds_read_b128 v[112:115], v212 offset:40960
	v_mfma_f32_32x32x16_bf16 v[32:47], v[36:39], v[160:163], 0
	v_exp_f32_e32 v148, v116
	v_exp_f32_e32 v149, v117
	v_exp_f32_e32 v150, v118
	v_exp_f32_e32 v151, v119
	s_waitcnt lgkmcnt(0)
	v_mfma_f32_32x32x16_bf16 v[48:63], v[132:135], v[164:167], v[48:63]
	ds_read_b128 v[116:119], v213 offset:32768
	v_exp_f32_e32 v152, v120
	v_exp_f32_e32 v153, v121
	v_exp_f32_e32 v154, v122
	v_exp_f32_e32 v155, v123
	v_mfma_f32_32x32x16_bf16 v[32:47], v[136:139], v[164:167], v[32:47]
	ds_read_b128 v[120:123], v213 offset:40960
	v_exp_f32_e32 v156, v124
	v_exp_f32_e32 v157, v125
	v_exp_f32_e32 v158, v126
	v_exp_f32_e32 v159, v127
	v_mfma_f32_32x32x16_bf16 v[48:63], v[140:143], v[168:171], v[48:63]
	ds_read_b128 v[124:127], v236
	v_exp_f32_e32 v136, v96
	v_exp_f32_e32 v137, v97
	v_exp_f32_e32 v138, v98
	v_exp_f32_e32 v139, v99
	v_mfma_f32_32x32x16_bf16 v[32:47], v[112:115], v[168:171], v[32:47]
	ds_read_b128 v[96:99], v236 offset:4096
	v_exp_f32_e32 v140, v100
	v_exp_f32_e32 v141, v101
	v_exp_f32_e32 v142, v102
	v_exp_f32_e32 v143, v103
	s_waitcnt lgkmcnt(0)
	v_mfma_f32_32x32x16_bf16 v[48:63], v[116:119], v[172:175], v[48:63]
	ds_read_b128 v[100:103], v236 offset:8192
	v_exp_f32_e32 v178, v104
	v_exp_f32_e32 v179, v105
	v_exp_f32_e32 v180, v106
	v_exp_f32_e32 v181, v107
	v_mfma_f32_32x32x16_bf16 v[32:47], v[120:123], v[172:175], v[32:47]
	ds_read_b128 v[104:107], v236 offset:12288
	v_exp_f32_e32 v182, v108
	v_exp_f32_e32 v183, v109
	v_exp_f32_e32 v184, v110
	v_exp_f32_e32 v185, v111
	v_cvt_pk_bf16_f32 v108, v144, v145
	v_cvt_pk_bf16_f32 v109, v146, v147
	v_cvt_pk_bf16_f32 v110, v148, v149
	v_cvt_pk_bf16_f32 v111, v150, v151
	s_nop 1
	v_mfma_f32_32x32x16_bf16 v[80:95], v[124:127], v[108:111], v[80:95]
	ds_read_b128 v[112:115], v237
	v_cvt_pk_bf16_f32 v116, v152, v153
	v_cvt_pk_bf16_f32 v117, v154, v155
	v_cvt_pk_bf16_f32 v118, v156, v157
	v_cvt_pk_bf16_f32 v119, v158, v159
	v_mfma_f32_32x32x16_bf16 v[64:79], v[96:99], v[108:111], v[64:79]
	ds_read_b128 v[120:123], v237 offset:4096
	v_pk_add_f32 v[126:127], v[150:151], v[146:147]
	v_pk_add_f32 v[124:125], v[148:149], v[144:145]
	s_waitcnt lgkmcnt(0)
	v_mfma_f32_32x32x16_bf16 v[16:31], v[100:103], v[108:111], v[16:31]
	ds_read_b128 v[132:135], v237 offset:8192
	v_add_f32_e64 v98, v154, v126
	v_add_f32_e64 v99, v155, v127
	v_add_f32_e64 v96, v152, v124
	v_add_f32_e64 v97, v153, v125
	v_pk_add_f32 v[98:99], v[158:159], v[98:99]
	v_pk_add_f32 v[96:97], v[156:157], v[96:97]
	v_mfma_f32_32x32x16_bf16 v[0:15], v[104:107], v[108:111], v[0:15]
	ds_read_b128 v[100:103], v237 offset:12288
	v_mfma_f32_32x32x16_bf16 v[80:95], v[112:115], v[116:119], v[80:95]
	ds_read_b128 v[104:107], v238
	v_cvt_pk_bf16_f32 v108, v136, v137
	v_cvt_pk_bf16_f32 v109, v138, v139
	v_cvt_pk_bf16_f32 v110, v140, v141
	v_cvt_pk_bf16_f32 v111, v142, v143
	v_mfma_f32_32x32x16_bf16 v[64:79], v[120:123], v[116:119], v[64:79]
	ds_read_b128 v[112:115], v238 offset:4096
	v_add_f32_e64 v98, v138, v98
	v_add_f32_e64 v99, v139, v99
	v_add_f32_e64 v96, v136, v96
	v_add_f32_e64 v97, v137, v97
	v_pk_add_f32 v[98:99], v[142:143], v[98:99]
	v_pk_add_f32 v[96:97], v[140:141], v[96:97]
	s_waitcnt lgkmcnt(0)
	v_mfma_f32_32x32x16_bf16 v[16:31], v[132:135], v[116:119], v[16:31]
	ds_read_b128 v[120:123], v238 offset:8192
	v_add_f32_e64 v98, v180, v98
	v_add_f32_e64 v99, v181, v99
	v_add_f32_e64 v96, v178, v96
	v_add_f32_e64 v97, v179, v97
	v_pk_add_f32 v[98:99], v[184:185], v[98:99]
	v_pk_add_f32 v[96:97], v[182:183], v[96:97]
	v_mfma_f32_32x32x16_bf16 v[0:15], v[100:103], v[116:119], v[0:15]
	ds_read_b128 v[124:127], v238 offset:12288
	v_mfma_f32_32x32x16_bf16 v[80:95], v[104:107], v[108:111], v[80:95]
	ds_read_b128 v[100:103], v239
	v_cvt_pk_bf16_f32 v116, v178, v179
	v_cvt_pk_bf16_f32 v117, v180, v181
	v_cvt_pk_bf16_f32 v118, v182, v183
	v_cvt_pk_bf16_f32 v119, v184, v185
	v_mfma_f32_32x32x16_bf16 v[64:79], v[112:115], v[108:111], v[64:79]
	ds_read_b128 v[104:107], v239 offset:4096
	s_waitcnt lgkmcnt(0)
	v_mfma_f32_32x32x16_bf16 v[16:31], v[120:123], v[108:111], v[16:31]
	ds_read_b128 v[112:115], v239 offset:8192
	v_mfma_f32_32x32x16_bf16 v[0:15], v[124:127], v[108:111], v[0:15]
	ds_read_b128 v[120:123], v239 offset:12288
	v_mfma_f32_32x32x16_bf16 v[80:95], v[100:103], v[116:119], v[80:95]
	v_mfma_f32_32x32x16_bf16 v[64:79], v[104:107], v[116:119], v[64:79]
	s_waitcnt lgkmcnt(0)
	v_mfma_f32_32x32x16_bf16 v[16:31], v[112:115], v[116:119], v[16:31]
	v_mfma_f32_32x32x16_bf16 v[0:15], v[120:123], v[116:119], v[0:15]
	s_waitcnt vmcnt(4) lgkmcnt(0)
	v_add_f32_e32 v100, v128, v129
	v_add_f32_e32 v101, v130, v131
	v_add_f32_e32 v100, v100, v101
	v_add_f32_e32 v96, v96, v97
	v_add_f32_e32 v97, v98, v99
	s_barrier
	v_add_f32_e32 v100, v177, v100
	v_add_f32_e32 v96, v96, v97
	v_add_f32_e32 v177, v100, v96
	s_add_i32 s21, s21, 2
	s_addk_i32 s15, 0x80
	s_add_i32 s20, s20, 0x8000
	s_add_u32 s98, s98, 0x30000
	s_addc_u32 s99, s99, 0
	s_add_u32 s100, s100, 0x100
	s_addc_u32 s101, s101, 0
	s_lshl_b32 s46, s41, 14
	s_add_i32 s46, s58, s46
	s_mov_b32 m0, s46
	s_nop 0
	global_load_lds_dwordx4 v198, s[98:99]
	s_add_i32 m0, s46, 0x400
	s_nop 0
	global_load_lds_dwordx4 v194, s[98:99]
	s_add_i32 s48, s20, 0xffffc000
	s_and_b32 s48, s48, 0x8000
	s_add_i32 s48, s58, s48
	s_add_i32 m0, s48, 0xc000
	s_nop 0
	global_load_lds_dwordx4 v196, s[100:101]
	s_add_i32 m0, s48, 0xc400
	s_nop 0
	global_load_lds_dwordx4 v192, s[100:101]
	s_add_i32 s46, s41, 1
	s_cmp_lg_u32 s41, 2
	s_cselect_b32 s41, s46, 0
	s_lshl_b32 s46, s41, 14
	s_add_i32 s49, s46, 0
	s_add_i32 s46, s20, 0xffff4000
	ds_read_b128 v[96:99], v205
	ds_read_b128 v[100:103], v205 offset:8192
	s_waitcnt lgkmcnt(0)
	v_mfma_f32_32x32x16_bf16 v[112:127], v[96:99], v[160:163], 0
	ds_read_b128 v[128:131], v211
	ds_read_b128 v[132:135], v211 offset:8192
	ds_read_b128 v[136:139], v212
	s_and_b32 s46, s46, 0x8000
	s_add_i32 s48, s46, 0
	v_exp_f32_e32 v140, v48
	v_exp_f32_e32 v141, v49
	v_exp_f32_e32 v142, v50
	v_exp_f32_e32 v143, v51
	ds_read_b128 v[48:51], v212 offset:8192
	v_mfma_f32_32x32x16_bf16 v[96:111], v[100:103], v[160:163], 0
	v_exp_f32_e32 v144, v52
	v_exp_f32_e32 v145, v53
	v_exp_f32_e32 v146, v54
	v_exp_f32_e32 v147, v55
	s_waitcnt lgkmcnt(0)
	v_mfma_f32_32x32x16_bf16 v[112:127], v[128:131], v[164:167], v[112:127]
	ds_read_b128 v[52:55], v213
	v_exp_f32_e32 v148, v56
	v_exp_f32_e32 v149, v57
	v_exp_f32_e32 v150, v58
	v_exp_f32_e32 v151, v59
	v_mfma_f32_32x32x16_bf16 v[96:111], v[132:135], v[164:167], v[96:111]
	ds_read_b128 v[56:59], v213 offset:8192
	v_exp_f32_e32 v128, v60
	v_exp_f32_e32 v129, v61
	v_exp_f32_e32 v130, v62
	v_exp_f32_e32 v131, v63
	v_mfma_f32_32x32x16_bf16 v[112:127], v[136:139], v[168:171], v[112:127]
	ds_read_b128 v[60:63], v236 offset:16384
	v_exp_f32_e32 v132, v32
	v_exp_f32_e32 v133, v33
	v_exp_f32_e32 v134, v34
	v_exp_f32_e32 v135, v35
	v_mfma_f32_32x32x16_bf16 v[96:111], v[48:51], v[168:171], v[96:111]
	ds_read_b128 v[32:35], v236 offset:20480
	v_exp_f32_e32 v136, v36
	v_exp_f32_e32 v137, v37
	v_exp_f32_e32 v138, v38
	v_exp_f32_e32 v139, v39
	s_waitcnt lgkmcnt(0)
	v_mfma_f32_32x32x16_bf16 v[112:127], v[52:55], v[172:175], v[112:127]
	ds_read_b128 v[36:39], v236 offset:24576
	v_exp_f32_e32 v152, v40
	v_exp_f32_e32 v153, v41
	v_exp_f32_e32 v154, v42
	v_exp_f32_e32 v155, v43
	v_mfma_f32_32x32x16_bf16 v[96:111], v[56:59], v[172:175], v[96:111]
	ds_read_b128 v[40:43], v236 offset:28672
	v_exp_f32_e32 v156, v44
	v_exp_f32_e32 v157, v45
	v_exp_f32_e32 v158, v46
	v_exp_f32_e32 v159, v47
	v_cvt_pk_bf16_f32 v44, v140, v141
	v_cvt_pk_bf16_f32 v45, v142, v143
	v_cvt_pk_bf16_f32 v46, v144, v145
	v_cvt_pk_bf16_f32 v47, v146, v147
	s_nop 1
	v_mfma_f32_32x32x16_bf16 v[80:95], v[60:63], v[44:47], v[80:95]
	ds_read_b128 v[48:51], v237 offset:16384
	v_cvt_pk_bf16_f32 v52, v148, v149
	v_cvt_pk_bf16_f32 v53, v150, v151
	v_cvt_pk_bf16_f32 v54, v128, v129
	v_cvt_pk_bf16_f32 v55, v130, v131
	v_mfma_f32_32x32x16_bf16 v[64:79], v[32:35], v[44:47], v[64:79]
	ds_read_b128 v[56:59], v237 offset:20480
	v_pk_add_f32 v[62:63], v[146:147], v[142:143]
	v_pk_add_f32 v[60:61], v[144:145], v[140:141]
	s_waitcnt lgkmcnt(0)
	v_mfma_f32_32x32x16_bf16 v[16:31], v[36:39], v[44:47], v[16:31]
	ds_read_b128 v[32:35], v237 offset:24576
	v_add_f32_e64 v62, v150, v62
	v_add_f32_e64 v63, v151, v63
	v_add_f32_e64 v60, v148, v60
	v_add_f32_e64 v61, v149, v61
	v_pk_add_f32 v[62:63], v[130:131], v[62:63]
	v_pk_add_f32 v[60:61], v[128:129], v[60:61]
	v_mfma_f32_32x32x16_bf16 v[0:15], v[40:43], v[44:47], v[0:15]
	ds_read_b128 v[36:39], v237 offset:28672
	v_mfma_f32_32x32x16_bf16 v[80:95], v[48:51], v[52:55], v[80:95]
	ds_read_b128 v[40:43], v238 offset:16384
	v_cvt_pk_bf16_f32 v44, v132, v133
	v_cvt_pk_bf16_f32 v45, v134, v135
	v_cvt_pk_bf16_f32 v46, v136, v137
	v_cvt_pk_bf16_f32 v47, v138, v139
	v_mfma_f32_32x32x16_bf16 v[64:79], v[56:59], v[52:55], v[64:79]
	ds_read_b128 v[48:51], v238 offset:20480
	v_add_f32_e64 v62, v134, v62
	v_add_f32_e64 v63, v135, v63
	v_add_f32_e64 v60, v132, v60
	v_add_f32_e64 v61, v133, v61
	v_pk_add_f32 v[62:63], v[138:139], v[62:63]
	v_pk_add_f32 v[60:61], v[136:137], v[60:61]
	s_waitcnt lgkmcnt(0)
	v_mfma_f32_32x32x16_bf16 v[16:31], v[32:35], v[52:55], v[16:31]
	ds_read_b128 v[56:59], v238 offset:24576
	v_add_f32_e64 v62, v154, v62
	v_add_f32_e64 v63, v155, v63
	v_add_f32_e64 v60, v152, v60
	v_add_f32_e64 v61, v153, v61
	v_pk_add_f32 v[130:131], v[158:159], v[62:63]
	v_pk_add_f32 v[128:129], v[156:157], v[60:61]
	v_mfma_f32_32x32x16_bf16 v[0:15], v[36:39], v[52:55], v[0:15]
	ds_read_b128 v[32:35], v238 offset:28672
	v_mfma_f32_32x32x16_bf16 v[80:95], v[40:43], v[44:47], v[80:95]
	ds_read_b128 v[36:39], v239 offset:16384
	v_cvt_pk_bf16_f32 v52, v152, v153
	v_cvt_pk_bf16_f32 v53, v154, v155
	v_cvt_pk_bf16_f32 v54, v156, v157
	v_cvt_pk_bf16_f32 v55, v158, v159
	v_mfma_f32_32x32x16_bf16 v[64:79], v[48:51], v[44:47], v[64:79]
	ds_read_b128 v[40:43], v239 offset:20480
	s_waitcnt lgkmcnt(0)
	v_mfma_f32_32x32x16_bf16 v[16:31], v[56:59], v[44:47], v[16:31]
	ds_read_b128 v[48:51], v239 offset:24576
	v_mfma_f32_32x32x16_bf16 v[0:15], v[32:35], v[44:47], v[0:15]
	ds_read_b128 v[56:59], v239 offset:28672
	v_mfma_f32_32x32x16_bf16 v[80:95], v[36:39], v[52:55], v[80:95]
	v_mfma_f32_32x32x16_bf16 v[64:79], v[40:43], v[52:55], v[64:79]
	s_waitcnt lgkmcnt(0)
	v_mfma_f32_32x32x16_bf16 v[16:31], v[48:51], v[52:55], v[16:31]
	v_mfma_f32_32x32x16_bf16 v[0:15], v[56:59], v[52:55], v[0:15]
	s_waitcnt vmcnt(4) lgkmcnt(0)
	s_barrier
	s_add_u32 s68, s98, 0x18000
	s_addc_u32 s69, s99, 0
	s_add_i32 s49, s49, s57
	s_mov_b32 m0, s49
	s_nop 0
	global_load_lds_dwordx4 v198, s[68:69]
	s_add_i32 m0, s49, 0x400
	s_nop 0
	global_load_lds_dwordx4 v194, s[68:69]
	s_add_u32 s44, s100, 0x80
	s_addc_u32 s45, s101, 0
	s_and_b32 s49, s20, 0xc000
	s_add_i32 s49, s58, s49
	s_add_i32 m0, s49, 0xc000
	s_nop 0
	global_load_lds_dwordx4 v196, s[44:45]
	s_add_i32 m0, s49, 0xc400
	s_nop 0
	global_load_lds_dwordx4 v192, s[44:45]
	s_add_i32 s48, s48, 0xc000
	s_add_i32 s44, s41, 1
	s_cmp_lg_u32 s41, 2
	s_cselect_b32 s41, s44, 0
	s_lshl_b32 s44, s41, 14
	s_add_i32 s44, s44, 0
	v_exp_f32_e32 v144, v112
	ds_read_b128 v[32:35], v205 offset:16384
	ds_read_b128 v[36:39], v205 offset:24576
	s_waitcnt lgkmcnt(0)
	v_mfma_f32_32x32x16_bf16 v[48:63], v[32:35], v[160:163], 0
	ds_read_b128 v[132:135], v211 offset:16384
	ds_read_b128 v[136:139], v211 offset:24576
	ds_read_b128 v[140:143], v212 offset:16384
	v_exp_f32_e32 v145, v113
	v_exp_f32_e32 v146, v114
	v_exp_f32_e32 v147, v115
	ds_read_b128 v[112:115], v212 offset:24576
	v_mfma_f32_32x32x16_bf16 v[32:47], v[36:39], v[160:163], 0
	v_exp_f32_e32 v148, v116
	v_exp_f32_e32 v149, v117
	v_exp_f32_e32 v150, v118
	v_exp_f32_e32 v151, v119
	s_waitcnt lgkmcnt(0)
	v_mfma_f32_32x32x16_bf16 v[48:63], v[132:135], v[164:167], v[48:63]
	ds_read_b128 v[116:119], v213 offset:16384
	v_exp_f32_e32 v152, v120
	v_exp_f32_e32 v153, v121
	v_exp_f32_e32 v154, v122
	v_exp_f32_e32 v155, v123
	v_mfma_f32_32x32x16_bf16 v[32:47], v[136:139], v[164:167], v[32:47]
	ds_read_b128 v[120:123], v213 offset:24576
	v_exp_f32_e32 v156, v124
	v_exp_f32_e32 v157, v125
	v_exp_f32_e32 v158, v126
	v_exp_f32_e32 v159, v127
	v_mfma_f32_32x32x16_bf16 v[48:63], v[140:143], v[168:171], v[48:63]
	ds_read_b128 v[124:127], v236 offset:32768
	v_exp_f32_e32 v136, v96
	v_exp_f32_e32 v137, v97
	v_exp_f32_e32 v138, v98
	v_exp_f32_e32 v139, v99
	v_mfma_f32_32x32x16_bf16 v[32:47], v[112:115], v[168:171], v[32:47]
	ds_read_b128 v[96:99], v236 offset:36864
	v_exp_f32_e32 v140, v100
	v_exp_f32_e32 v141, v101
	v_exp_f32_e32 v142, v102
	v_exp_f32_e32 v143, v103
	s_waitcnt lgkmcnt(0)
	v_mfma_f32_32x32x16_bf16 v[48:63], v[116:119], v[172:175], v[48:63]
	ds_read_b128 v[100:103], v236 offset:40960
	v_exp_f32_e32 v178, v104
	v_exp_f32_e32 v179, v105
	v_exp_f32_e32 v180, v106
	v_exp_f32_e32 v181, v107
	v_mfma_f32_32x32x16_bf16 v[32:47], v[120:123], v[172:175], v[32:47]
	ds_read_b128 v[104:107], v236 offset:45056
	v_exp_f32_e32 v182, v108
	v_exp_f32_e32 v183, v109
	v_exp_f32_e32 v184, v110
	v_exp_f32_e32 v185, v111
	v_cvt_pk_bf16_f32 v108, v144, v145
	v_cvt_pk_bf16_f32 v109, v146, v147
	v_cvt_pk_bf16_f32 v110, v148, v149
	v_cvt_pk_bf16_f32 v111, v150, v151
	s_nop 1
	v_mfma_f32_32x32x16_bf16 v[80:95], v[124:127], v[108:111], v[80:95]
	ds_read_b128 v[112:115], v237 offset:32768
	v_cvt_pk_bf16_f32 v116, v152, v153
	v_cvt_pk_bf16_f32 v117, v154, v155
	v_cvt_pk_bf16_f32 v118, v156, v157
	v_cvt_pk_bf16_f32 v119, v158, v159
	v_mfma_f32_32x32x16_bf16 v[64:79], v[96:99], v[108:111], v[64:79]
	ds_read_b128 v[120:123], v237 offset:36864
	v_pk_add_f32 v[126:127], v[150:151], v[146:147]
	v_pk_add_f32 v[124:125], v[148:149], v[144:145]
	s_waitcnt lgkmcnt(0)
	v_mfma_f32_32x32x16_bf16 v[16:31], v[100:103], v[108:111], v[16:31]
	ds_read_b128 v[132:135], v237 offset:40960
	v_add_f32_e64 v98, v154, v126
	v_add_f32_e64 v99, v155, v127
	v_add_f32_e64 v96, v152, v124
	v_add_f32_e64 v97, v153, v125
	v_pk_add_f32 v[98:99], v[158:159], v[98:99]
	v_pk_add_f32 v[96:97], v[156:157], v[96:97]
	v_mfma_f32_32x32x16_bf16 v[0:15], v[104:107], v[108:111], v[0:15]
	ds_read_b128 v[100:103], v237 offset:45056
	v_mfma_f32_32x32x16_bf16 v[80:95], v[112:115], v[116:119], v[80:95]
	ds_read_b128 v[104:107], v238 offset:32768
	v_cvt_pk_bf16_f32 v108, v136, v137
	v_cvt_pk_bf16_f32 v109, v138, v139
	v_cvt_pk_bf16_f32 v110, v140, v141
	v_cvt_pk_bf16_f32 v111, v142, v143
	v_mfma_f32_32x32x16_bf16 v[64:79], v[120:123], v[116:119], v[64:79]
	ds_read_b128 v[112:115], v238 offset:36864
	v_add_f32_e64 v98, v138, v98
	v_add_f32_e64 v99, v139, v99
	v_add_f32_e64 v96, v136, v96
	v_add_f32_e64 v97, v137, v97
	v_pk_add_f32 v[98:99], v[142:143], v[98:99]
	v_pk_add_f32 v[96:97], v[140:141], v[96:97]
	s_waitcnt lgkmcnt(0)
	v_mfma_f32_32x32x16_bf16 v[16:31], v[132:135], v[116:119], v[16:31]
	ds_read_b128 v[120:123], v238 offset:40960
	v_add_f32_e64 v98, v180, v98
	v_add_f32_e64 v99, v181, v99
	v_add_f32_e64 v96, v178, v96
	v_add_f32_e64 v97, v179, v97
	v_pk_add_f32 v[98:99], v[184:185], v[98:99]
	v_pk_add_f32 v[96:97], v[182:183], v[96:97]
	v_mfma_f32_32x32x16_bf16 v[0:15], v[100:103], v[116:119], v[0:15]
	ds_read_b128 v[124:127], v238 offset:45056
	v_mfma_f32_32x32x16_bf16 v[80:95], v[104:107], v[108:111], v[80:95]
	ds_read_b128 v[100:103], v239 offset:32768
	v_cvt_pk_bf16_f32 v116, v178, v179
	v_cvt_pk_bf16_f32 v117, v180, v181
	v_cvt_pk_bf16_f32 v118, v182, v183
	v_cvt_pk_bf16_f32 v119, v184, v185
	v_mfma_f32_32x32x16_bf16 v[64:79], v[112:115], v[108:111], v[64:79]
	ds_read_b128 v[104:107], v239 offset:36864
	s_waitcnt lgkmcnt(0)
	v_mfma_f32_32x32x16_bf16 v[16:31], v[120:123], v[108:111], v[16:31]
	ds_read_b128 v[112:115], v239 offset:40960
	v_mfma_f32_32x32x16_bf16 v[0:15], v[124:127], v[108:111], v[0:15]
	ds_read_b128 v[120:123], v239 offset:45056
	v_mfma_f32_32x32x16_bf16 v[80:95], v[100:103], v[116:119], v[80:95]
	v_mfma_f32_32x32x16_bf16 v[64:79], v[104:107], v[116:119], v[64:79]
	s_waitcnt lgkmcnt(0)
	v_mfma_f32_32x32x16_bf16 v[16:31], v[112:115], v[116:119], v[16:31]
	v_mfma_f32_32x32x16_bf16 v[0:15], v[120:123], v[116:119], v[0:15]
	s_waitcnt vmcnt(4) lgkmcnt(0)
	v_add_f32_e32 v100, v128, v129
	v_add_f32_e32 v101, v130, v131
	v_add_f32_e32 v100, v100, v101
	v_add_f32_e32 v96, v96, v97
	v_add_f32_e32 v97, v98, v99
	s_barrier
	v_add_f32_e32 v100, v177, v100
	v_add_f32_e32 v96, v96, v97
	v_add_f32_e32 v177, v100, v96
	s_add_i32 s21, s21, 2
	s_addk_i32 s15, 0x80
	s_add_i32 s20, s20, 0x8000
	s_add_u32 s98, s98, 0x30000
	s_addc_u32 s99, s99, 0
	s_add_u32 s100, s100, 0x100
	s_addc_u32 s101, s101, 0
	s_lshl_b32 s46, s41, 14
	s_add_i32 s46, s58, s46
	s_mov_b32 m0, s46
	s_nop 0
	global_load_lds_dwordx4 v198, s[98:99]
	s_add_i32 m0, s46, 0x400
	s_nop 0
	global_load_lds_dwordx4 v194, s[98:99]
	s_add_i32 s48, s20, 0xffffc000
	s_and_b32 s48, s48, 0x8000
	s_add_i32 s48, s58, s48
	s_add_i32 m0, s48, 0xc000
	s_nop 0
	global_load_lds_dwordx4 v196, s[100:101]
	s_add_i32 m0, s48, 0xc400
	s_nop 0
	global_load_lds_dwordx4 v192, s[100:101]
	s_add_i32 s46, s41, 1
	s_cmp_lg_u32 s41, 2
	s_cselect_b32 s41, s46, 0
	s_lshl_b32 s46, s41, 14
	s_add_i32 s49, s46, 0
	s_add_i32 s46, s20, 0xffff4000
	ds_read_b128 v[96:99], v205 offset:32768
	ds_read_b128 v[100:103], v205 offset:40960
	s_waitcnt lgkmcnt(0)
	v_mfma_f32_32x32x16_bf16 v[112:127], v[96:99], v[160:163], 0
	ds_read_b128 v[128:131], v211 offset:32768
	ds_read_b128 v[132:135], v211 offset:40960
	ds_read_b128 v[136:139], v212 offset:32768
	s_and_b32 s46, s46, 0x8000
	s_add_i32 s48, s46, 0
	v_exp_f32_e32 v140, v48
	v_exp_f32_e32 v141, v49
	v_exp_f32_e32 v142, v50
	v_exp_f32_e32 v143, v51
	ds_read_b128 v[48:51], v212 offset:40960
	v_mfma_f32_32x32x16_bf16 v[96:111], v[100:103], v[160:163], 0
	v_exp_f32_e32 v144, v52
	v_exp_f32_e32 v145, v53
	v_exp_f32_e32 v146, v54
	v_exp_f32_e32 v147, v55
	s_waitcnt lgkmcnt(0)
	v_mfma_f32_32x32x16_bf16 v[112:127], v[128:131], v[164:167], v[112:127]
	ds_read_b128 v[52:55], v213 offset:32768
	v_exp_f32_e32 v148, v56
	v_exp_f32_e32 v149, v57
	v_exp_f32_e32 v150, v58
	v_exp_f32_e32 v151, v59
	v_mfma_f32_32x32x16_bf16 v[96:111], v[132:135], v[164:167], v[96:111]
	ds_read_b128 v[56:59], v213 offset:40960
	v_exp_f32_e32 v128, v60
	v_exp_f32_e32 v129, v61
	v_exp_f32_e32 v130, v62
	v_exp_f32_e32 v131, v63
	v_mfma_f32_32x32x16_bf16 v[112:127], v[136:139], v[168:171], v[112:127]
	ds_read_b128 v[60:63], v206 offset:49152
	v_exp_f32_e32 v132, v32
	v_exp_f32_e32 v133, v33
	v_exp_f32_e32 v134, v34
	v_exp_f32_e32 v135, v35
	v_mfma_f32_32x32x16_bf16 v[96:111], v[48:51], v[168:171], v[96:111]
	ds_read_b128 v[32:35], v206 offset:53248
	v_exp_f32_e32 v136, v36
	v_exp_f32_e32 v137, v37
	v_exp_f32_e32 v138, v38
	v_exp_f32_e32 v139, v39
	s_waitcnt lgkmcnt(0)
	v_mfma_f32_32x32x16_bf16 v[112:127], v[52:55], v[172:175], v[112:127]
	ds_read_b128 v[36:39], v206 offset:57344
	v_exp_f32_e32 v152, v40
	v_exp_f32_e32 v153, v41
	v_exp_f32_e32 v154, v42
	v_exp_f32_e32 v155, v43
	v_mfma_f32_32x32x16_bf16 v[96:111], v[56:59], v[172:175], v[96:111]
	ds_read_b128 v[40:43], v206 offset:61440
	v_exp_f32_e32 v156, v44
	v_exp_f32_e32 v157, v45
	v_exp_f32_e32 v158, v46
	v_exp_f32_e32 v159, v47
	v_cvt_pk_bf16_f32 v44, v140, v141
	v_cvt_pk_bf16_f32 v45, v142, v143
	v_cvt_pk_bf16_f32 v46, v144, v145
	v_cvt_pk_bf16_f32 v47, v146, v147
	s_nop 1
	v_mfma_f32_32x32x16_bf16 v[80:95], v[60:63], v[44:47], v[80:95]
	ds_read_b128 v[48:51], v207 offset:49152
	v_cvt_pk_bf16_f32 v52, v148, v149
	v_cvt_pk_bf16_f32 v53, v150, v151
	v_cvt_pk_bf16_f32 v54, v128, v129
	v_cvt_pk_bf16_f32 v55, v130, v131
	v_mfma_f32_32x32x16_bf16 v[64:79], v[32:35], v[44:47], v[64:79]
	ds_read_b128 v[56:59], v207 offset:53248
	v_pk_add_f32 v[62:63], v[146:147], v[142:143]
	v_pk_add_f32 v[60:61], v[144:145], v[140:141]
	s_waitcnt lgkmcnt(0)
	v_mfma_f32_32x32x16_bf16 v[16:31], v[36:39], v[44:47], v[16:31]
	ds_read_b128 v[32:35], v207 offset:57344
	v_add_f32_e64 v62, v150, v62
	v_add_f32_e64 v63, v151, v63
	v_add_f32_e64 v60, v148, v60
	v_add_f32_e64 v61, v149, v61
	v_pk_add_f32 v[62:63], v[130:131], v[62:63]
	v_pk_add_f32 v[60:61], v[128:129], v[60:61]
	v_mfma_f32_32x32x16_bf16 v[0:15], v[40:43], v[44:47], v[0:15]
	ds_read_b128 v[36:39], v207 offset:61440
	v_mfma_f32_32x32x16_bf16 v[80:95], v[48:51], v[52:55], v[80:95]
	ds_read_b128 v[40:43], v208 offset:49152
	v_cvt_pk_bf16_f32 v44, v132, v133
	v_cvt_pk_bf16_f32 v45, v134, v135
	v_cvt_pk_bf16_f32 v46, v136, v137
	v_cvt_pk_bf16_f32 v47, v138, v139
	v_mfma_f32_32x32x16_bf16 v[64:79], v[56:59], v[52:55], v[64:79]
	ds_read_b128 v[48:51], v208 offset:53248
	v_add_f32_e64 v62, v134, v62
	v_add_f32_e64 v63, v135, v63
	v_add_f32_e64 v60, v132, v60
	v_add_f32_e64 v61, v133, v61
	v_pk_add_f32 v[62:63], v[138:139], v[62:63]
	v_pk_add_f32 v[60:61], v[136:137], v[60:61]
	s_waitcnt lgkmcnt(0)
	v_mfma_f32_32x32x16_bf16 v[16:31], v[32:35], v[52:55], v[16:31]
	ds_read_b128 v[56:59], v208 offset:57344
	v_add_f32_e64 v62, v154, v62
	v_add_f32_e64 v63, v155, v63
	v_add_f32_e64 v60, v152, v60
	v_add_f32_e64 v61, v153, v61
	v_pk_add_f32 v[130:131], v[158:159], v[62:63]
	v_pk_add_f32 v[128:129], v[156:157], v[60:61]
	v_mfma_f32_32x32x16_bf16 v[0:15], v[36:39], v[52:55], v[0:15]
	ds_read_b128 v[32:35], v208 offset:61440
	v_mfma_f32_32x32x16_bf16 v[80:95], v[40:43], v[44:47], v[80:95]
	ds_read_b128 v[36:39], v209 offset:49152
	v_cvt_pk_bf16_f32 v52, v152, v153
	v_cvt_pk_bf16_f32 v53, v154, v155
	v_cvt_pk_bf16_f32 v54, v156, v157
	v_cvt_pk_bf16_f32 v55, v158, v159
	v_mfma_f32_32x32x16_bf16 v[64:79], v[48:51], v[44:47], v[64:79]
	ds_read_b128 v[40:43], v209 offset:53248
	s_waitcnt lgkmcnt(0)
	v_mfma_f32_32x32x16_bf16 v[16:31], v[56:59], v[44:47], v[16:31]
	ds_read_b128 v[48:51], v209 offset:57344
	v_mfma_f32_32x32x16_bf16 v[0:15], v[32:35], v[44:47], v[0:15]
	ds_read_b128 v[56:59], v209 offset:61440
	v_mfma_f32_32x32x16_bf16 v[80:95], v[36:39], v[52:55], v[80:95]
	v_mfma_f32_32x32x16_bf16 v[64:79], v[40:43], v[52:55], v[64:79]
	s_waitcnt lgkmcnt(0)
	v_mfma_f32_32x32x16_bf16 v[16:31], v[48:51], v[52:55], v[16:31]
	v_mfma_f32_32x32x16_bf16 v[0:15], v[56:59], v[52:55], v[0:15]
	s_waitcnt vmcnt(4) lgkmcnt(0)
	s_barrier
	s_add_u32 s68, s98, 0x18000
	s_addc_u32 s69, s99, 0
	s_add_i32 s49, s49, s57
	s_mov_b32 m0, s49
	s_nop 0
	global_load_lds_dwordx4 v198, s[68:69]
	s_add_i32 m0, s49, 0x400
	s_nop 0
	global_load_lds_dwordx4 v194, s[68:69]
	s_add_u32 s44, s100, 0x80
	s_addc_u32 s45, s101, 0
	s_and_b32 s49, s20, 0xc000
	s_add_i32 s49, s58, s49
	s_add_i32 m0, s49, 0xc000
	s_nop 0
	global_load_lds_dwordx4 v196, s[44:45]
	s_add_i32 m0, s49, 0xc400
	s_nop 0
	global_load_lds_dwordx4 v192, s[44:45]
	s_add_i32 s48, s48, 0xc000
	s_add_i32 s44, s41, 1
	s_cmp_lg_u32 s41, 2
	s_cselect_b32 s41, s44, 0
	s_lshl_b32 s44, s41, 14
	s_add_i32 s44, s44, 0
	v_exp_f32_e32 v144, v112
	ds_read_b128 v[32:35], v205
	ds_read_b128 v[36:39], v205 offset:8192
	s_waitcnt lgkmcnt(0)
	v_mfma_f32_32x32x16_bf16 v[48:63], v[32:35], v[160:163], 0
	ds_read_b128 v[132:135], v211
	ds_read_b128 v[136:139], v211 offset:8192
	ds_read_b128 v[140:143], v212
	v_exp_f32_e32 v145, v113
	v_exp_f32_e32 v146, v114
	v_exp_f32_e32 v147, v115
	ds_read_b128 v[112:115], v212 offset:8192
	v_mfma_f32_32x32x16_bf16 v[32:47], v[36:39], v[160:163], 0
	v_exp_f32_e32 v148, v116
	v_exp_f32_e32 v149, v117
	v_exp_f32_e32 v150, v118
	v_exp_f32_e32 v151, v119
	s_waitcnt lgkmcnt(0)
	v_mfma_f32_32x32x16_bf16 v[48:63], v[132:135], v[164:167], v[48:63]
	ds_read_b128 v[116:119], v213
	v_exp_f32_e32 v152, v120
	v_exp_f32_e32 v153, v121
	v_exp_f32_e32 v154, v122
	v_exp_f32_e32 v155, v123
	v_mfma_f32_32x32x16_bf16 v[32:47], v[136:139], v[164:167], v[32:47]
	ds_read_b128 v[120:123], v213 offset:8192
	v_exp_f32_e32 v156, v124
	v_exp_f32_e32 v157, v125
	v_exp_f32_e32 v158, v126
	v_exp_f32_e32 v159, v127
	v_mfma_f32_32x32x16_bf16 v[48:63], v[140:143], v[168:171], v[48:63]
	ds_read_b128 v[124:127], v236
	v_exp_f32_e32 v136, v96
	v_exp_f32_e32 v137, v97
	v_exp_f32_e32 v138, v98
	v_exp_f32_e32 v139, v99
	v_mfma_f32_32x32x16_bf16 v[32:47], v[112:115], v[168:171], v[32:47]
	ds_read_b128 v[96:99], v236 offset:4096
	v_exp_f32_e32 v140, v100
	v_exp_f32_e32 v141, v101
	v_exp_f32_e32 v142, v102
	v_exp_f32_e32 v143, v103
	s_waitcnt lgkmcnt(0)
	v_mfma_f32_32x32x16_bf16 v[48:63], v[116:119], v[172:175], v[48:63]
	ds_read_b128 v[100:103], v236 offset:8192
	v_exp_f32_e32 v178, v104
	v_exp_f32_e32 v179, v105
	v_exp_f32_e32 v180, v106
	v_exp_f32_e32 v181, v107
	v_mfma_f32_32x32x16_bf16 v[32:47], v[120:123], v[172:175], v[32:47]
	ds_read_b128 v[104:107], v236 offset:12288
	v_exp_f32_e32 v182, v108
	v_exp_f32_e32 v183, v109
	v_exp_f32_e32 v184, v110
	v_exp_f32_e32 v185, v111
	v_cvt_pk_bf16_f32 v108, v144, v145
	v_cvt_pk_bf16_f32 v109, v146, v147
	v_cvt_pk_bf16_f32 v110, v148, v149
	v_cvt_pk_bf16_f32 v111, v150, v151
	s_nop 1
	v_mfma_f32_32x32x16_bf16 v[80:95], v[124:127], v[108:111], v[80:95]
	ds_read_b128 v[112:115], v237
	v_cvt_pk_bf16_f32 v116, v152, v153
	v_cvt_pk_bf16_f32 v117, v154, v155
	v_cvt_pk_bf16_f32 v118, v156, v157
	v_cvt_pk_bf16_f32 v119, v158, v159
	v_mfma_f32_32x32x16_bf16 v[64:79], v[96:99], v[108:111], v[64:79]
	ds_read_b128 v[120:123], v237 offset:4096
	v_pk_add_f32 v[126:127], v[150:151], v[146:147]
	v_pk_add_f32 v[124:125], v[148:149], v[144:145]
	s_waitcnt lgkmcnt(0)
	v_mfma_f32_32x32x16_bf16 v[16:31], v[100:103], v[108:111], v[16:31]
	ds_read_b128 v[132:135], v237 offset:8192
	v_add_f32_e64 v98, v154, v126
	v_add_f32_e64 v99, v155, v127
	v_add_f32_e64 v96, v152, v124
	v_add_f32_e64 v97, v153, v125
	v_pk_add_f32 v[98:99], v[158:159], v[98:99]
	v_pk_add_f32 v[96:97], v[156:157], v[96:97]
	v_mfma_f32_32x32x16_bf16 v[0:15], v[104:107], v[108:111], v[0:15]
	ds_read_b128 v[100:103], v237 offset:12288
	v_mfma_f32_32x32x16_bf16 v[80:95], v[112:115], v[116:119], v[80:95]
	ds_read_b128 v[104:107], v238
	v_cvt_pk_bf16_f32 v108, v136, v137
	v_cvt_pk_bf16_f32 v109, v138, v139
	v_cvt_pk_bf16_f32 v110, v140, v141
	v_cvt_pk_bf16_f32 v111, v142, v143
	v_mfma_f32_32x32x16_bf16 v[64:79], v[120:123], v[116:119], v[64:79]
	ds_read_b128 v[112:115], v238 offset:4096
	v_add_f32_e64 v98, v138, v98
	v_add_f32_e64 v99, v139, v99
	v_add_f32_e64 v96, v136, v96
	v_add_f32_e64 v97, v137, v97
	v_pk_add_f32 v[98:99], v[142:143], v[98:99]
	v_pk_add_f32 v[96:97], v[140:141], v[96:97]
	s_waitcnt lgkmcnt(0)
	v_mfma_f32_32x32x16_bf16 v[16:31], v[132:135], v[116:119], v[16:31]
	ds_read_b128 v[120:123], v238 offset:8192
	v_add_f32_e64 v98, v180, v98
	v_add_f32_e64 v99, v181, v99
	v_add_f32_e64 v96, v178, v96
	v_add_f32_e64 v97, v179, v97
	v_pk_add_f32 v[98:99], v[184:185], v[98:99]
	v_pk_add_f32 v[96:97], v[182:183], v[96:97]
	v_mfma_f32_32x32x16_bf16 v[0:15], v[100:103], v[116:119], v[0:15]
	ds_read_b128 v[124:127], v238 offset:12288
	v_mfma_f32_32x32x16_bf16 v[80:95], v[104:107], v[108:111], v[80:95]
	ds_read_b128 v[100:103], v239
	v_cvt_pk_bf16_f32 v116, v178, v179
	v_cvt_pk_bf16_f32 v117, v180, v181
	v_cvt_pk_bf16_f32 v118, v182, v183
	v_cvt_pk_bf16_f32 v119, v184, v185
	v_mfma_f32_32x32x16_bf16 v[64:79], v[112:115], v[108:111], v[64:79]
	ds_read_b128 v[104:107], v239 offset:4096
	s_waitcnt lgkmcnt(0)
	v_mfma_f32_32x32x16_bf16 v[16:31], v[120:123], v[108:111], v[16:31]
	ds_read_b128 v[112:115], v239 offset:8192
	v_mfma_f32_32x32x16_bf16 v[0:15], v[124:127], v[108:111], v[0:15]
	ds_read_b128 v[120:123], v239 offset:12288
	v_mfma_f32_32x32x16_bf16 v[80:95], v[100:103], v[116:119], v[80:95]
	v_mfma_f32_32x32x16_bf16 v[64:79], v[104:107], v[116:119], v[64:79]
	s_waitcnt lgkmcnt(0)
	v_mfma_f32_32x32x16_bf16 v[16:31], v[112:115], v[116:119], v[16:31]
	v_mfma_f32_32x32x16_bf16 v[0:15], v[120:123], v[116:119], v[0:15]
	s_waitcnt vmcnt(4) lgkmcnt(0)
	v_add_f32_e32 v100, v128, v129
	v_add_f32_e32 v101, v130, v131
	v_add_f32_e32 v100, v100, v101
	v_add_f32_e32 v96, v96, v97
	v_add_f32_e32 v97, v98, v99
	s_barrier
	v_add_f32_e32 v100, v177, v100
	v_add_f32_e32 v96, v96, v97
	v_add_f32_e32 v177, v100, v96
	s_add_i32 s21, s21, 2
	s_addk_i32 s15, 0x80
	s_add_i32 s20, s20, 0x8000
	s_add_u32 s98, s98, 0x30000
	s_addc_u32 s99, s99, 0
	s_add_u32 s100, s100, 0x100
	s_addc_u32 s101, s101, 0
	s_lshl_b32 s46, s41, 14
	s_add_i32 s46, s58, s46
	s_mov_b32 m0, s46
	s_nop 0
	global_load_lds_dwordx4 v198, s[98:99]
	s_add_i32 m0, s46, 0x400
	s_nop 0
	global_load_lds_dwordx4 v194, s[98:99]
	s_add_i32 s48, s20, 0xffffc000
	s_and_b32 s48, s48, 0x8000
	s_add_i32 s48, s58, s48
	s_add_i32 m0, s48, 0xc000
	s_nop 0
	global_load_lds_dwordx4 v196, s[100:101]
	s_add_i32 m0, s48, 0xc400
	s_nop 0
	global_load_lds_dwordx4 v192, s[100:101]
	s_add_i32 s46, s41, 1
	s_cmp_lg_u32 s41, 2
	s_cselect_b32 s41, s46, 0
	s_lshl_b32 s46, s41, 14
	s_add_i32 s49, s46, 0
	s_add_i32 s46, s20, 0xffff4000
	ds_read_b128 v[96:99], v205 offset:16384
	ds_read_b128 v[100:103], v205 offset:24576
	s_waitcnt lgkmcnt(0)
	v_mfma_f32_32x32x16_bf16 v[112:127], v[96:99], v[160:163], 0
	ds_read_b128 v[128:131], v211 offset:16384
	ds_read_b128 v[132:135], v211 offset:24576
	ds_read_b128 v[136:139], v212 offset:16384
	s_and_b32 s46, s46, 0x8000
	s_add_i32 s48, s46, 0
	v_exp_f32_e32 v140, v48
	v_exp_f32_e32 v141, v49
	v_exp_f32_e32 v142, v50
	v_exp_f32_e32 v143, v51
	ds_read_b128 v[48:51], v212 offset:24576
	v_mfma_f32_32x32x16_bf16 v[96:111], v[100:103], v[160:163], 0
	v_exp_f32_e32 v144, v52
	v_exp_f32_e32 v145, v53
	v_exp_f32_e32 v146, v54
	v_exp_f32_e32 v147, v55
	s_waitcnt lgkmcnt(0)
	v_mfma_f32_32x32x16_bf16 v[112:127], v[128:131], v[164:167], v[112:127]
	ds_read_b128 v[52:55], v213 offset:16384
	v_exp_f32_e32 v148, v56
	v_exp_f32_e32 v149, v57
	v_exp_f32_e32 v150, v58
	v_exp_f32_e32 v151, v59
	v_mfma_f32_32x32x16_bf16 v[96:111], v[132:135], v[164:167], v[96:111]
	ds_read_b128 v[56:59], v213 offset:24576
	v_exp_f32_e32 v128, v60
	v_exp_f32_e32 v129, v61
	v_exp_f32_e32 v130, v62
	v_exp_f32_e32 v131, v63
	v_mfma_f32_32x32x16_bf16 v[112:127], v[136:139], v[168:171], v[112:127]
	ds_read_b128 v[60:63], v236 offset:16384
	v_exp_f32_e32 v132, v32
	v_exp_f32_e32 v133, v33
	v_exp_f32_e32 v134, v34
	v_exp_f32_e32 v135, v35
	v_mfma_f32_32x32x16_bf16 v[96:111], v[48:51], v[168:171], v[96:111]
	ds_read_b128 v[32:35], v236 offset:20480
	v_exp_f32_e32 v136, v36
	v_exp_f32_e32 v137, v37
	v_exp_f32_e32 v138, v38
	v_exp_f32_e32 v139, v39
	s_waitcnt lgkmcnt(0)
	v_mfma_f32_32x32x16_bf16 v[112:127], v[52:55], v[172:175], v[112:127]
	ds_read_b128 v[36:39], v236 offset:24576
	v_exp_f32_e32 v152, v40
	v_exp_f32_e32 v153, v41
	v_exp_f32_e32 v154, v42
	v_exp_f32_e32 v155, v43
	v_mfma_f32_32x32x16_bf16 v[96:111], v[56:59], v[172:175], v[96:111]
	ds_read_b128 v[40:43], v236 offset:28672
	v_exp_f32_e32 v156, v44
	v_exp_f32_e32 v157, v45
	v_exp_f32_e32 v158, v46
	v_exp_f32_e32 v159, v47
	v_cvt_pk_bf16_f32 v44, v140, v141
	v_cvt_pk_bf16_f32 v45, v142, v143
	v_cvt_pk_bf16_f32 v46, v144, v145
	v_cvt_pk_bf16_f32 v47, v146, v147
	s_nop 1
	v_mfma_f32_32x32x16_bf16 v[80:95], v[60:63], v[44:47], v[80:95]
	ds_read_b128 v[48:51], v237 offset:16384
	v_cvt_pk_bf16_f32 v52, v148, v149
	v_cvt_pk_bf16_f32 v53, v150, v151
	v_cvt_pk_bf16_f32 v54, v128, v129
	v_cvt_pk_bf16_f32 v55, v130, v131
	v_mfma_f32_32x32x16_bf16 v[64:79], v[32:35], v[44:47], v[64:79]
	ds_read_b128 v[56:59], v237 offset:20480
	v_pk_add_f32 v[62:63], v[146:147], v[142:143]
	v_pk_add_f32 v[60:61], v[144:145], v[140:141]
	s_waitcnt lgkmcnt(0)
	v_mfma_f32_32x32x16_bf16 v[16:31], v[36:39], v[44:47], v[16:31]
	ds_read_b128 v[32:35], v237 offset:24576
	v_add_f32_e64 v62, v150, v62
	v_add_f32_e64 v63, v151, v63
	v_add_f32_e64 v60, v148, v60
	v_add_f32_e64 v61, v149, v61
	v_pk_add_f32 v[62:63], v[130:131], v[62:63]
	v_pk_add_f32 v[60:61], v[128:129], v[60:61]
	v_mfma_f32_32x32x16_bf16 v[0:15], v[40:43], v[44:47], v[0:15]
	ds_read_b128 v[36:39], v237 offset:28672
	v_mfma_f32_32x32x16_bf16 v[80:95], v[48:51], v[52:55], v[80:95]
	ds_read_b128 v[40:43], v238 offset:16384
	v_cvt_pk_bf16_f32 v44, v132, v133
	v_cvt_pk_bf16_f32 v45, v134, v135
	v_cvt_pk_bf16_f32 v46, v136, v137
	v_cvt_pk_bf16_f32 v47, v138, v139
	v_mfma_f32_32x32x16_bf16 v[64:79], v[56:59], v[52:55], v[64:79]
	ds_read_b128 v[48:51], v238 offset:20480
	v_add_f32_e64 v62, v134, v62
	v_add_f32_e64 v63, v135, v63
	v_add_f32_e64 v60, v132, v60
	v_add_f32_e64 v61, v133, v61
	v_pk_add_f32 v[62:63], v[138:139], v[62:63]
	v_pk_add_f32 v[60:61], v[136:137], v[60:61]
	s_waitcnt lgkmcnt(0)
	v_mfma_f32_32x32x16_bf16 v[16:31], v[32:35], v[52:55], v[16:31]
	ds_read_b128 v[56:59], v238 offset:24576
	v_add_f32_e64 v62, v154, v62
	v_add_f32_e64 v63, v155, v63
	v_add_f32_e64 v60, v152, v60
	v_add_f32_e64 v61, v153, v61
	v_pk_add_f32 v[130:131], v[158:159], v[62:63]
	v_pk_add_f32 v[128:129], v[156:157], v[60:61]
	v_mfma_f32_32x32x16_bf16 v[0:15], v[36:39], v[52:55], v[0:15]
	ds_read_b128 v[32:35], v238 offset:28672
	v_mfma_f32_32x32x16_bf16 v[80:95], v[40:43], v[44:47], v[80:95]
	ds_read_b128 v[36:39], v239 offset:16384
	v_cvt_pk_bf16_f32 v52, v152, v153
	v_cvt_pk_bf16_f32 v53, v154, v155
	v_cvt_pk_bf16_f32 v54, v156, v157
	v_cvt_pk_bf16_f32 v55, v158, v159
	v_mfma_f32_32x32x16_bf16 v[64:79], v[48:51], v[44:47], v[64:79]
	ds_read_b128 v[40:43], v239 offset:20480
	s_waitcnt lgkmcnt(0)
	v_mfma_f32_32x32x16_bf16 v[16:31], v[56:59], v[44:47], v[16:31]
	ds_read_b128 v[48:51], v239 offset:24576
	v_mfma_f32_32x32x16_bf16 v[0:15], v[32:35], v[44:47], v[0:15]
	ds_read_b128 v[56:59], v239 offset:28672
	v_mfma_f32_32x32x16_bf16 v[80:95], v[36:39], v[52:55], v[80:95]
	v_mfma_f32_32x32x16_bf16 v[64:79], v[40:43], v[52:55], v[64:79]
	s_waitcnt lgkmcnt(0)
	v_mfma_f32_32x32x16_bf16 v[16:31], v[48:51], v[52:55], v[16:31]
	v_mfma_f32_32x32x16_bf16 v[0:15], v[56:59], v[52:55], v[0:15]
	s_waitcnt vmcnt(4) lgkmcnt(0)
	s_barrier
	s_add_u32 s68, s98, 0x18000
	s_addc_u32 s69, s99, 0
	s_add_i32 s49, s49, s57
	s_mov_b32 m0, s49
	s_nop 0
	global_load_lds_dwordx4 v198, s[68:69]
	s_add_i32 m0, s49, 0x400
	s_nop 0
	global_load_lds_dwordx4 v194, s[68:69]
	s_add_u32 s44, s100, 0x80
	s_addc_u32 s45, s101, 0
	s_and_b32 s49, s20, 0xc000
	s_add_i32 s49, s58, s49
	s_add_i32 m0, s49, 0xc000
	s_nop 0
	global_load_lds_dwordx4 v196, s[44:45]
	s_add_i32 m0, s49, 0xc400
	s_nop 0
	global_load_lds_dwordx4 v192, s[44:45]
	s_add_i32 s48, s48, 0xc000
	s_add_i32 s44, s41, 1
	s_cmp_lg_u32 s41, 2
	s_cselect_b32 s41, s44, 0
	s_lshl_b32 s44, s41, 14
	s_add_i32 s44, s44, 0
	v_exp_f32_e32 v144, v112
	ds_read_b128 v[32:35], v205 offset:32768
	ds_read_b128 v[36:39], v205 offset:40960
	s_waitcnt lgkmcnt(0)
	v_mfma_f32_32x32x16_bf16 v[48:63], v[32:35], v[160:163], 0
	ds_read_b128 v[132:135], v211 offset:32768
	ds_read_b128 v[136:139], v211 offset:40960
	ds_read_b128 v[140:143], v212 offset:32768
	v_exp_f32_e32 v145, v113
	v_exp_f32_e32 v146, v114
	v_exp_f32_e32 v147, v115
	ds_read_b128 v[112:115], v212 offset:40960
	v_mfma_f32_32x32x16_bf16 v[32:47], v[36:39], v[160:163], 0
	v_exp_f32_e32 v148, v116
	v_exp_f32_e32 v149, v117
	v_exp_f32_e32 v150, v118
	v_exp_f32_e32 v151, v119
	s_waitcnt lgkmcnt(0)
	v_mfma_f32_32x32x16_bf16 v[48:63], v[132:135], v[164:167], v[48:63]
	ds_read_b128 v[116:119], v213 offset:32768
	v_exp_f32_e32 v152, v120
	v_exp_f32_e32 v153, v121
	v_exp_f32_e32 v154, v122
	v_exp_f32_e32 v155, v123
	v_mfma_f32_32x32x16_bf16 v[32:47], v[136:139], v[164:167], v[32:47]
	ds_read_b128 v[120:123], v213 offset:40960
	v_exp_f32_e32 v156, v124
	v_exp_f32_e32 v157, v125
	v_exp_f32_e32 v158, v126
	v_exp_f32_e32 v159, v127
	v_mfma_f32_32x32x16_bf16 v[48:63], v[140:143], v[168:171], v[48:63]
	ds_read_b128 v[124:127], v236 offset:32768
	v_exp_f32_e32 v136, v96
	v_exp_f32_e32 v137, v97
	v_exp_f32_e32 v138, v98
	v_exp_f32_e32 v139, v99
	v_mfma_f32_32x32x16_bf16 v[32:47], v[112:115], v[168:171], v[32:47]
	ds_read_b128 v[96:99], v236 offset:36864
	v_exp_f32_e32 v140, v100
	v_exp_f32_e32 v141, v101
	v_exp_f32_e32 v142, v102
	v_exp_f32_e32 v143, v103
	s_waitcnt lgkmcnt(0)
	v_mfma_f32_32x32x16_bf16 v[48:63], v[116:119], v[172:175], v[48:63]
	ds_read_b128 v[100:103], v236 offset:40960
	v_exp_f32_e32 v178, v104
	v_exp_f32_e32 v179, v105
	v_exp_f32_e32 v180, v106
	v_exp_f32_e32 v181, v107
	v_mfma_f32_32x32x16_bf16 v[32:47], v[120:123], v[172:175], v[32:47]
	ds_read_b128 v[104:107], v236 offset:45056
	v_exp_f32_e32 v182, v108
	v_exp_f32_e32 v183, v109
	v_exp_f32_e32 v184, v110
	v_exp_f32_e32 v185, v111
	v_cvt_pk_bf16_f32 v108, v144, v145
	v_cvt_pk_bf16_f32 v109, v146, v147
	v_cvt_pk_bf16_f32 v110, v148, v149
	v_cvt_pk_bf16_f32 v111, v150, v151
	s_nop 1
	v_mfma_f32_32x32x16_bf16 v[80:95], v[124:127], v[108:111], v[80:95]
	ds_read_b128 v[112:115], v237 offset:32768
	v_cvt_pk_bf16_f32 v116, v152, v153
	v_cvt_pk_bf16_f32 v117, v154, v155
	v_cvt_pk_bf16_f32 v118, v156, v157
	v_cvt_pk_bf16_f32 v119, v158, v159
	v_mfma_f32_32x32x16_bf16 v[64:79], v[96:99], v[108:111], v[64:79]
	ds_read_b128 v[120:123], v237 offset:36864
	v_pk_add_f32 v[126:127], v[150:151], v[146:147]
	v_pk_add_f32 v[124:125], v[148:149], v[144:145]
	s_waitcnt lgkmcnt(0)
	v_mfma_f32_32x32x16_bf16 v[16:31], v[100:103], v[108:111], v[16:31]
	ds_read_b128 v[132:135], v237 offset:40960
	v_add_f32_e64 v98, v154, v126
	v_add_f32_e64 v99, v155, v127
	v_add_f32_e64 v96, v152, v124
	v_add_f32_e64 v97, v153, v125
	v_pk_add_f32 v[98:99], v[158:159], v[98:99]
	v_pk_add_f32 v[96:97], v[156:157], v[96:97]
	v_mfma_f32_32x32x16_bf16 v[0:15], v[104:107], v[108:111], v[0:15]
	ds_read_b128 v[100:103], v237 offset:45056
	v_mfma_f32_32x32x16_bf16 v[80:95], v[112:115], v[116:119], v[80:95]
	ds_read_b128 v[104:107], v238 offset:32768
	v_cvt_pk_bf16_f32 v108, v136, v137
	v_cvt_pk_bf16_f32 v109, v138, v139
	v_cvt_pk_bf16_f32 v110, v140, v141
	v_cvt_pk_bf16_f32 v111, v142, v143
	v_mfma_f32_32x32x16_bf16 v[64:79], v[120:123], v[116:119], v[64:79]
	ds_read_b128 v[112:115], v238 offset:36864
	v_add_f32_e64 v98, v138, v98
	v_add_f32_e64 v99, v139, v99
	v_add_f32_e64 v96, v136, v96
	v_add_f32_e64 v97, v137, v97
	v_pk_add_f32 v[98:99], v[142:143], v[98:99]
	v_pk_add_f32 v[96:97], v[140:141], v[96:97]
	s_waitcnt lgkmcnt(0)
	v_mfma_f32_32x32x16_bf16 v[16:31], v[132:135], v[116:119], v[16:31]
	ds_read_b128 v[120:123], v238 offset:40960
	v_add_f32_e64 v98, v180, v98
	v_add_f32_e64 v99, v181, v99
	v_add_f32_e64 v96, v178, v96
	v_add_f32_e64 v97, v179, v97
	v_pk_add_f32 v[98:99], v[184:185], v[98:99]
	v_pk_add_f32 v[96:97], v[182:183], v[96:97]
	v_mfma_f32_32x32x16_bf16 v[0:15], v[100:103], v[116:119], v[0:15]
	ds_read_b128 v[124:127], v238 offset:45056
	v_mfma_f32_32x32x16_bf16 v[80:95], v[104:107], v[108:111], v[80:95]
	ds_read_b128 v[100:103], v239 offset:32768
	v_cvt_pk_bf16_f32 v116, v178, v179
	v_cvt_pk_bf16_f32 v117, v180, v181
	v_cvt_pk_bf16_f32 v118, v182, v183
	v_cvt_pk_bf16_f32 v119, v184, v185
	v_mfma_f32_32x32x16_bf16 v[64:79], v[112:115], v[108:111], v[64:79]
	ds_read_b128 v[104:107], v239 offset:36864
	s_waitcnt lgkmcnt(0)
	v_mfma_f32_32x32x16_bf16 v[16:31], v[120:123], v[108:111], v[16:31]
	ds_read_b128 v[112:115], v239 offset:40960
	v_mfma_f32_32x32x16_bf16 v[0:15], v[124:127], v[108:111], v[0:15]
	ds_read_b128 v[120:123], v239 offset:45056
	v_mfma_f32_32x32x16_bf16 v[80:95], v[100:103], v[116:119], v[80:95]
	v_mfma_f32_32x32x16_bf16 v[64:79], v[104:107], v[116:119], v[64:79]
	s_waitcnt lgkmcnt(0)
	v_mfma_f32_32x32x16_bf16 v[16:31], v[112:115], v[116:119], v[16:31]
	v_mfma_f32_32x32x16_bf16 v[0:15], v[120:123], v[116:119], v[0:15]
	s_waitcnt vmcnt(4) lgkmcnt(0)
	v_add_f32_e32 v100, v128, v129
	v_add_f32_e32 v101, v130, v131
	v_add_f32_e32 v100, v100, v101
	v_add_f32_e32 v96, v96, v97
	v_add_f32_e32 v97, v98, v99
	s_barrier
	v_add_f32_e32 v100, v177, v100
	v_add_f32_e32 v96, v96, v97
	v_add_f32_e32 v177, v100, v96
	s_add_i32 s21, s21, 2
	s_addk_i32 s15, 0x80
	s_add_i32 s20, s20, 0x8000
	s_add_u32 s98, s98, 0x30000
	s_addc_u32 s99, s99, 0
	s_add_u32 s100, s100, 0x100
	s_addc_u32 s101, s101, 0
	s_lshl_b32 s46, s41, 14
	s_add_i32 s46, s58, s46
	s_mov_b32 m0, s46
	s_nop 0
	global_load_lds_dwordx4 v198, s[98:99]
	s_add_i32 m0, s46, 0x400
	s_nop 0
	global_load_lds_dwordx4 v194, s[98:99]
	s_add_i32 s48, s20, 0xffffc000
	s_and_b32 s48, s48, 0x8000
	s_add_i32 s48, s58, s48
	s_add_i32 m0, s48, 0xc000
	s_nop 0
	global_load_lds_dwordx4 v196, s[100:101]
	s_add_i32 m0, s48, 0xc400
	s_nop 0
	global_load_lds_dwordx4 v192, s[100:101]
	s_add_i32 s46, s41, 1
	s_cmp_lg_u32 s41, 2
	s_cselect_b32 s41, s46, 0
	s_lshl_b32 s46, s41, 14
	s_add_i32 s49, s46, 0
	s_add_i32 s46, s20, 0xffff4000
	ds_read_b128 v[96:99], v205
	ds_read_b128 v[100:103], v205 offset:8192
	s_waitcnt lgkmcnt(0)
	v_mfma_f32_32x32x16_bf16 v[112:127], v[96:99], v[160:163], 0
	ds_read_b128 v[128:131], v211
	ds_read_b128 v[132:135], v211 offset:8192
	ds_read_b128 v[136:139], v212
	s_and_b32 s46, s46, 0x8000
	s_add_i32 s48, s46, 0
	v_exp_f32_e32 v140, v48
	v_exp_f32_e32 v141, v49
	v_exp_f32_e32 v142, v50
	v_exp_f32_e32 v143, v51
	ds_read_b128 v[48:51], v212 offset:8192
	v_mfma_f32_32x32x16_bf16 v[96:111], v[100:103], v[160:163], 0
	v_exp_f32_e32 v144, v52
	v_exp_f32_e32 v145, v53
	v_exp_f32_e32 v146, v54
	v_exp_f32_e32 v147, v55
	s_waitcnt lgkmcnt(0)
	v_mfma_f32_32x32x16_bf16 v[112:127], v[128:131], v[164:167], v[112:127]
	ds_read_b128 v[52:55], v213
	v_exp_f32_e32 v148, v56
	v_exp_f32_e32 v149, v57
	v_exp_f32_e32 v150, v58
	v_exp_f32_e32 v151, v59
	v_mfma_f32_32x32x16_bf16 v[96:111], v[132:135], v[164:167], v[96:111]
	ds_read_b128 v[56:59], v213 offset:8192
	v_exp_f32_e32 v128, v60
	v_exp_f32_e32 v129, v61
	v_exp_f32_e32 v130, v62
	v_exp_f32_e32 v131, v63
	v_mfma_f32_32x32x16_bf16 v[112:127], v[136:139], v[168:171], v[112:127]
	ds_read_b128 v[60:63], v206 offset:49152
	v_exp_f32_e32 v132, v32
	v_exp_f32_e32 v133, v33
	v_exp_f32_e32 v134, v34
	v_exp_f32_e32 v135, v35
	v_mfma_f32_32x32x16_bf16 v[96:111], v[48:51], v[168:171], v[96:111]
	ds_read_b128 v[32:35], v206 offset:53248
	v_exp_f32_e32 v136, v36
	v_exp_f32_e32 v137, v37
	v_exp_f32_e32 v138, v38
	v_exp_f32_e32 v139, v39
	s_waitcnt lgkmcnt(0)
	v_mfma_f32_32x32x16_bf16 v[112:127], v[52:55], v[172:175], v[112:127]
	ds_read_b128 v[36:39], v206 offset:57344
	v_exp_f32_e32 v152, v40
	v_exp_f32_e32 v153, v41
	v_exp_f32_e32 v154, v42
	v_exp_f32_e32 v155, v43
	v_mfma_f32_32x32x16_bf16 v[96:111], v[56:59], v[172:175], v[96:111]
	ds_read_b128 v[40:43], v206 offset:61440
	v_exp_f32_e32 v156, v44
	v_exp_f32_e32 v157, v45
	v_exp_f32_e32 v158, v46
	v_exp_f32_e32 v159, v47
	v_cvt_pk_bf16_f32 v44, v140, v141
	v_cvt_pk_bf16_f32 v45, v142, v143
	v_cvt_pk_bf16_f32 v46, v144, v145
	v_cvt_pk_bf16_f32 v47, v146, v147
	s_nop 1
	v_mfma_f32_32x32x16_bf16 v[80:95], v[60:63], v[44:47], v[80:95]
	ds_read_b128 v[48:51], v207 offset:49152
	v_cvt_pk_bf16_f32 v52, v148, v149
	v_cvt_pk_bf16_f32 v53, v150, v151
	v_cvt_pk_bf16_f32 v54, v128, v129
	v_cvt_pk_bf16_f32 v55, v130, v131
	v_mfma_f32_32x32x16_bf16 v[64:79], v[32:35], v[44:47], v[64:79]
	ds_read_b128 v[56:59], v207 offset:53248
	v_pk_add_f32 v[62:63], v[146:147], v[142:143]
	v_pk_add_f32 v[60:61], v[144:145], v[140:141]
	s_waitcnt lgkmcnt(0)
	v_mfma_f32_32x32x16_bf16 v[16:31], v[36:39], v[44:47], v[16:31]
	ds_read_b128 v[32:35], v207 offset:57344
	v_add_f32_e64 v62, v150, v62
	v_add_f32_e64 v63, v151, v63
	v_add_f32_e64 v60, v148, v60
	v_add_f32_e64 v61, v149, v61
	v_pk_add_f32 v[62:63], v[130:131], v[62:63]
	v_pk_add_f32 v[60:61], v[128:129], v[60:61]
	v_mfma_f32_32x32x16_bf16 v[0:15], v[40:43], v[44:47], v[0:15]
	ds_read_b128 v[36:39], v207 offset:61440
	v_mfma_f32_32x32x16_bf16 v[80:95], v[48:51], v[52:55], v[80:95]
	ds_read_b128 v[40:43], v208 offset:49152
	v_cvt_pk_bf16_f32 v44, v132, v133
	v_cvt_pk_bf16_f32 v45, v134, v135
	v_cvt_pk_bf16_f32 v46, v136, v137
	v_cvt_pk_bf16_f32 v47, v138, v139
	v_mfma_f32_32x32x16_bf16 v[64:79], v[56:59], v[52:55], v[64:79]
	ds_read_b128 v[48:51], v208 offset:53248
	v_add_f32_e64 v62, v134, v62
	v_add_f32_e64 v63, v135, v63
	v_add_f32_e64 v60, v132, v60
	v_add_f32_e64 v61, v133, v61
	v_pk_add_f32 v[62:63], v[138:139], v[62:63]
	v_pk_add_f32 v[60:61], v[136:137], v[60:61]
	s_waitcnt lgkmcnt(0)
	v_mfma_f32_32x32x16_bf16 v[16:31], v[32:35], v[52:55], v[16:31]
	ds_read_b128 v[56:59], v208 offset:57344
	v_add_f32_e64 v62, v154, v62
	v_add_f32_e64 v63, v155, v63
	v_add_f32_e64 v60, v152, v60
	v_add_f32_e64 v61, v153, v61
	v_pk_add_f32 v[130:131], v[158:159], v[62:63]
	v_pk_add_f32 v[128:129], v[156:157], v[60:61]
	v_mfma_f32_32x32x16_bf16 v[0:15], v[36:39], v[52:55], v[0:15]
	ds_read_b128 v[32:35], v208 offset:61440
	v_mfma_f32_32x32x16_bf16 v[80:95], v[40:43], v[44:47], v[80:95]
	ds_read_b128 v[36:39], v209 offset:49152
	v_cvt_pk_bf16_f32 v52, v152, v153
	v_cvt_pk_bf16_f32 v53, v154, v155
	v_cvt_pk_bf16_f32 v54, v156, v157
	v_cvt_pk_bf16_f32 v55, v158, v159
	v_mfma_f32_32x32x16_bf16 v[64:79], v[48:51], v[44:47], v[64:79]
	ds_read_b128 v[40:43], v209 offset:53248
	s_waitcnt lgkmcnt(0)
	v_mfma_f32_32x32x16_bf16 v[16:31], v[56:59], v[44:47], v[16:31]
	ds_read_b128 v[48:51], v209 offset:57344
	v_mfma_f32_32x32x16_bf16 v[0:15], v[32:35], v[44:47], v[0:15]
	ds_read_b128 v[56:59], v209 offset:61440
	v_mfma_f32_32x32x16_bf16 v[80:95], v[36:39], v[52:55], v[80:95]
	v_mfma_f32_32x32x16_bf16 v[64:79], v[40:43], v[52:55], v[64:79]
	s_waitcnt lgkmcnt(0)
	v_mfma_f32_32x32x16_bf16 v[16:31], v[48:51], v[52:55], v[16:31]
	v_mfma_f32_32x32x16_bf16 v[0:15], v[56:59], v[52:55], v[0:15]
	s_waitcnt vmcnt(4) lgkmcnt(0)
	s_barrier
	s_add_u32 s68, s98, 0x18000
	s_addc_u32 s69, s99, 0
	s_add_i32 s49, s49, s57
	s_mov_b32 m0, s49
	s_nop 0
	global_load_lds_dwordx4 v198, s[68:69]
	s_add_i32 m0, s49, 0x400
	s_nop 0
	global_load_lds_dwordx4 v194, s[68:69]
	s_add_u32 s44, s100, 0x80
	s_addc_u32 s45, s101, 0
	s_and_b32 s49, s20, 0xc000
	s_add_i32 s49, s58, s49
	s_add_i32 m0, s49, 0xc000
	s_nop 0
	global_load_lds_dwordx4 v196, s[44:45]
	s_add_i32 m0, s49, 0xc400
	s_nop 0
	global_load_lds_dwordx4 v192, s[44:45]
	s_add_i32 s48, s48, 0xc000
	s_add_i32 s44, s41, 1
	s_cmp_lg_u32 s41, 2
	s_cselect_b32 s41, s44, 0
	s_lshl_b32 s44, s41, 14
	s_add_i32 s44, s44, 0
	v_exp_f32_e32 v144, v112
	ds_read_b128 v[32:35], v205 offset:16384
	ds_read_b128 v[36:39], v205 offset:24576
	s_waitcnt lgkmcnt(0)
	v_mfma_f32_32x32x16_bf16 v[48:63], v[32:35], v[160:163], 0
	ds_read_b128 v[132:135], v211 offset:16384
	ds_read_b128 v[136:139], v211 offset:24576
	ds_read_b128 v[140:143], v212 offset:16384
	v_exp_f32_e32 v145, v113
	v_exp_f32_e32 v146, v114
	v_exp_f32_e32 v147, v115
	ds_read_b128 v[112:115], v212 offset:24576
	v_mfma_f32_32x32x16_bf16 v[32:47], v[36:39], v[160:163], 0
	v_exp_f32_e32 v148, v116
	v_exp_f32_e32 v149, v117
	v_exp_f32_e32 v150, v118
	v_exp_f32_e32 v151, v119
	s_waitcnt lgkmcnt(0)
	v_mfma_f32_32x32x16_bf16 v[48:63], v[132:135], v[164:167], v[48:63]
	ds_read_b128 v[116:119], v213 offset:16384
	v_exp_f32_e32 v152, v120
	v_exp_f32_e32 v153, v121
	v_exp_f32_e32 v154, v122
	v_exp_f32_e32 v155, v123
	v_mfma_f32_32x32x16_bf16 v[32:47], v[136:139], v[164:167], v[32:47]
	ds_read_b128 v[120:123], v213 offset:24576
	v_exp_f32_e32 v156, v124
	v_exp_f32_e32 v157, v125
	v_exp_f32_e32 v158, v126
	v_exp_f32_e32 v159, v127
	v_mfma_f32_32x32x16_bf16 v[48:63], v[140:143], v[168:171], v[48:63]
	ds_read_b128 v[124:127], v236
	v_exp_f32_e32 v136, v96
	v_exp_f32_e32 v137, v97
	v_exp_f32_e32 v138, v98
	v_exp_f32_e32 v139, v99
	v_mfma_f32_32x32x16_bf16 v[32:47], v[112:115], v[168:171], v[32:47]
	ds_read_b128 v[96:99], v236 offset:4096
	v_exp_f32_e32 v140, v100
	v_exp_f32_e32 v141, v101
	v_exp_f32_e32 v142, v102
	v_exp_f32_e32 v143, v103
	s_waitcnt lgkmcnt(0)
	v_mfma_f32_32x32x16_bf16 v[48:63], v[116:119], v[172:175], v[48:63]
	ds_read_b128 v[100:103], v236 offset:8192
	v_exp_f32_e32 v178, v104
	v_exp_f32_e32 v179, v105
	v_exp_f32_e32 v180, v106
	v_exp_f32_e32 v181, v107
	v_mfma_f32_32x32x16_bf16 v[32:47], v[120:123], v[172:175], v[32:47]
	ds_read_b128 v[104:107], v236 offset:12288
	v_exp_f32_e32 v182, v108
	v_exp_f32_e32 v183, v109
	v_exp_f32_e32 v184, v110
	v_exp_f32_e32 v185, v111
	v_cvt_pk_bf16_f32 v108, v144, v145
	v_cvt_pk_bf16_f32 v109, v146, v147
	v_cvt_pk_bf16_f32 v110, v148, v149
	v_cvt_pk_bf16_f32 v111, v150, v151
	s_nop 1
	v_mfma_f32_32x32x16_bf16 v[80:95], v[124:127], v[108:111], v[80:95]
	ds_read_b128 v[112:115], v237
	v_cvt_pk_bf16_f32 v116, v152, v153
	v_cvt_pk_bf16_f32 v117, v154, v155
	v_cvt_pk_bf16_f32 v118, v156, v157
	v_cvt_pk_bf16_f32 v119, v158, v159
	v_mfma_f32_32x32x16_bf16 v[64:79], v[96:99], v[108:111], v[64:79]
	ds_read_b128 v[120:123], v237 offset:4096
	v_pk_add_f32 v[126:127], v[150:151], v[146:147]
	v_pk_add_f32 v[124:125], v[148:149], v[144:145]
	s_waitcnt lgkmcnt(0)
	v_mfma_f32_32x32x16_bf16 v[16:31], v[100:103], v[108:111], v[16:31]
	ds_read_b128 v[132:135], v237 offset:8192
	v_add_f32_e64 v98, v154, v126
	v_add_f32_e64 v99, v155, v127
	v_add_f32_e64 v96, v152, v124
	v_add_f32_e64 v97, v153, v125
	v_pk_add_f32 v[98:99], v[158:159], v[98:99]
	v_pk_add_f32 v[96:97], v[156:157], v[96:97]
	v_mfma_f32_32x32x16_bf16 v[0:15], v[104:107], v[108:111], v[0:15]
	ds_read_b128 v[100:103], v237 offset:12288
	v_mfma_f32_32x32x16_bf16 v[80:95], v[112:115], v[116:119], v[80:95]
	ds_read_b128 v[104:107], v238
	v_cvt_pk_bf16_f32 v108, v136, v137
	v_cvt_pk_bf16_f32 v109, v138, v139
	v_cvt_pk_bf16_f32 v110, v140, v141
	v_cvt_pk_bf16_f32 v111, v142, v143
	v_mfma_f32_32x32x16_bf16 v[64:79], v[120:123], v[116:119], v[64:79]
	ds_read_b128 v[112:115], v238 offset:4096
	v_add_f32_e64 v98, v138, v98
	v_add_f32_e64 v99, v139, v99
	v_add_f32_e64 v96, v136, v96
	v_add_f32_e64 v97, v137, v97
	v_pk_add_f32 v[98:99], v[142:143], v[98:99]
	v_pk_add_f32 v[96:97], v[140:141], v[96:97]
	s_waitcnt lgkmcnt(0)
	v_mfma_f32_32x32x16_bf16 v[16:31], v[132:135], v[116:119], v[16:31]
	ds_read_b128 v[120:123], v238 offset:8192
	v_add_f32_e64 v98, v180, v98
	v_add_f32_e64 v99, v181, v99
	v_add_f32_e64 v96, v178, v96
	v_add_f32_e64 v97, v179, v97
	v_pk_add_f32 v[98:99], v[184:185], v[98:99]
	v_pk_add_f32 v[96:97], v[182:183], v[96:97]
	v_mfma_f32_32x32x16_bf16 v[0:15], v[100:103], v[116:119], v[0:15]
	ds_read_b128 v[124:127], v238 offset:12288
	v_mfma_f32_32x32x16_bf16 v[80:95], v[104:107], v[108:111], v[80:95]
	ds_read_b128 v[100:103], v239
	v_cvt_pk_bf16_f32 v116, v178, v179
	v_cvt_pk_bf16_f32 v117, v180, v181
	v_cvt_pk_bf16_f32 v118, v182, v183
	v_cvt_pk_bf16_f32 v119, v184, v185
	v_mfma_f32_32x32x16_bf16 v[64:79], v[112:115], v[108:111], v[64:79]
	ds_read_b128 v[104:107], v239 offset:4096
	s_waitcnt lgkmcnt(0)
	v_mfma_f32_32x32x16_bf16 v[16:31], v[120:123], v[108:111], v[16:31]
	ds_read_b128 v[112:115], v239 offset:8192
	v_mfma_f32_32x32x16_bf16 v[0:15], v[124:127], v[108:111], v[0:15]
	ds_read_b128 v[120:123], v239 offset:12288
	v_mfma_f32_32x32x16_bf16 v[80:95], v[100:103], v[116:119], v[80:95]
	v_mfma_f32_32x32x16_bf16 v[64:79], v[104:107], v[116:119], v[64:79]
	s_waitcnt lgkmcnt(0)
	v_mfma_f32_32x32x16_bf16 v[16:31], v[112:115], v[116:119], v[16:31]
	v_mfma_f32_32x32x16_bf16 v[0:15], v[120:123], v[116:119], v[0:15]
	s_waitcnt vmcnt(4) lgkmcnt(0)
	v_add_f32_e32 v100, v128, v129
	v_add_f32_e32 v101, v130, v131
	v_add_f32_e32 v100, v100, v101
	v_add_f32_e32 v96, v96, v97
	v_add_f32_e32 v97, v98, v99
	s_barrier
	v_add_f32_e32 v100, v177, v100
	v_add_f32_e32 v96, v96, v97
	v_add_f32_e32 v177, v100, v96
	s_add_i32 s21, s21, 2
	s_addk_i32 s15, 0x80
	s_add_i32 s20, s20, 0x8000
	s_add_u32 s98, s98, 0x30000
	s_addc_u32 s99, s99, 0
	s_add_u32 s100, s100, 0x100
	s_addc_u32 s101, s101, 0
	s_lshl_b32 s46, s41, 14
	s_add_i32 s46, s58, s46
	s_mov_b32 m0, s46
	s_nop 0
	global_load_lds_dwordx4 v198, s[98:99]
	s_add_i32 m0, s46, 0x400
	s_nop 0
	global_load_lds_dwordx4 v194, s[98:99]
	s_add_i32 s48, s20, 0xffffc000
	s_and_b32 s48, s48, 0x8000
	s_add_i32 s48, s58, s48
	s_add_i32 m0, s48, 0xc000
	s_nop 0
	global_load_lds_dwordx4 v196, s[100:101]
	s_add_i32 m0, s48, 0xc400
	s_nop 0
	global_load_lds_dwordx4 v192, s[100:101]
	s_add_i32 s46, s41, 1
	s_cmp_lg_u32 s41, 2
	s_cselect_b32 s41, s46, 0
	s_lshl_b32 s46, s41, 14
	s_add_i32 s49, s46, 0
	s_add_i32 s46, s20, 0xffff4000
	ds_read_b128 v[96:99], v205 offset:32768
	ds_read_b128 v[100:103], v205 offset:40960
	s_waitcnt lgkmcnt(0)
	v_mfma_f32_32x32x16_bf16 v[112:127], v[96:99], v[160:163], 0
	ds_read_b128 v[128:131], v211 offset:32768
	ds_read_b128 v[132:135], v211 offset:40960
	ds_read_b128 v[136:139], v212 offset:32768
	s_and_b32 s46, s46, 0x8000
	s_add_i32 s48, s46, 0
	v_exp_f32_e32 v140, v48
	v_exp_f32_e32 v141, v49
	v_exp_f32_e32 v142, v50
	v_exp_f32_e32 v143, v51
	ds_read_b128 v[48:51], v212 offset:40960
	v_mfma_f32_32x32x16_bf16 v[96:111], v[100:103], v[160:163], 0
	v_exp_f32_e32 v144, v52
	v_exp_f32_e32 v145, v53
	v_exp_f32_e32 v146, v54
	v_exp_f32_e32 v147, v55
	s_waitcnt lgkmcnt(0)
	v_mfma_f32_32x32x16_bf16 v[112:127], v[128:131], v[164:167], v[112:127]
	ds_read_b128 v[52:55], v213 offset:32768
	v_exp_f32_e32 v148, v56
	v_exp_f32_e32 v149, v57
	v_exp_f32_e32 v150, v58
	v_exp_f32_e32 v151, v59
	v_mfma_f32_32x32x16_bf16 v[96:111], v[132:135], v[164:167], v[96:111]
	ds_read_b128 v[56:59], v213 offset:40960
	v_exp_f32_e32 v128, v60
	v_exp_f32_e32 v129, v61
	v_exp_f32_e32 v130, v62
	v_exp_f32_e32 v131, v63
	v_mfma_f32_32x32x16_bf16 v[112:127], v[136:139], v[168:171], v[112:127]
	ds_read_b128 v[60:63], v236 offset:16384
	v_exp_f32_e32 v132, v32
	v_exp_f32_e32 v133, v33
	v_exp_f32_e32 v134, v34
	v_exp_f32_e32 v135, v35
	v_mfma_f32_32x32x16_bf16 v[96:111], v[48:51], v[168:171], v[96:111]
	ds_read_b128 v[32:35], v236 offset:20480
	v_exp_f32_e32 v136, v36
	v_exp_f32_e32 v137, v37
	v_exp_f32_e32 v138, v38
	v_exp_f32_e32 v139, v39
	s_waitcnt lgkmcnt(0)
	v_mfma_f32_32x32x16_bf16 v[112:127], v[52:55], v[172:175], v[112:127]
	ds_read_b128 v[36:39], v236 offset:24576
	v_exp_f32_e32 v152, v40
	v_exp_f32_e32 v153, v41
	v_exp_f32_e32 v154, v42
	v_exp_f32_e32 v155, v43
	v_mfma_f32_32x32x16_bf16 v[96:111], v[56:59], v[172:175], v[96:111]
	ds_read_b128 v[40:43], v236 offset:28672
	v_exp_f32_e32 v156, v44
	v_exp_f32_e32 v157, v45
	v_exp_f32_e32 v158, v46
	v_exp_f32_e32 v159, v47
	v_cvt_pk_bf16_f32 v44, v140, v141
	v_cvt_pk_bf16_f32 v45, v142, v143
	v_cvt_pk_bf16_f32 v46, v144, v145
	v_cvt_pk_bf16_f32 v47, v146, v147
	s_nop 1
	v_mfma_f32_32x32x16_bf16 v[80:95], v[60:63], v[44:47], v[80:95]
	ds_read_b128 v[48:51], v237 offset:16384
	v_cvt_pk_bf16_f32 v52, v148, v149
	v_cvt_pk_bf16_f32 v53, v150, v151
	v_cvt_pk_bf16_f32 v54, v128, v129
	v_cvt_pk_bf16_f32 v55, v130, v131
	v_mfma_f32_32x32x16_bf16 v[64:79], v[32:35], v[44:47], v[64:79]
	ds_read_b128 v[56:59], v237 offset:20480
	v_pk_add_f32 v[62:63], v[146:147], v[142:143]
	v_pk_add_f32 v[60:61], v[144:145], v[140:141]
	s_waitcnt lgkmcnt(0)
	v_mfma_f32_32x32x16_bf16 v[16:31], v[36:39], v[44:47], v[16:31]
	ds_read_b128 v[32:35], v237 offset:24576
	v_add_f32_e64 v62, v150, v62
	v_add_f32_e64 v63, v151, v63
	v_add_f32_e64 v60, v148, v60
	v_add_f32_e64 v61, v149, v61
	v_pk_add_f32 v[62:63], v[130:131], v[62:63]
	v_pk_add_f32 v[60:61], v[128:129], v[60:61]
	v_mfma_f32_32x32x16_bf16 v[0:15], v[40:43], v[44:47], v[0:15]
	ds_read_b128 v[36:39], v237 offset:28672
	v_mfma_f32_32x32x16_bf16 v[80:95], v[48:51], v[52:55], v[80:95]
	ds_read_b128 v[40:43], v238 offset:16384
	v_cvt_pk_bf16_f32 v44, v132, v133
	v_cvt_pk_bf16_f32 v45, v134, v135
	v_cvt_pk_bf16_f32 v46, v136, v137
	v_cvt_pk_bf16_f32 v47, v138, v139
	v_mfma_f32_32x32x16_bf16 v[64:79], v[56:59], v[52:55], v[64:79]
	ds_read_b128 v[48:51], v238 offset:20480
	v_add_f32_e64 v62, v134, v62
	v_add_f32_e64 v63, v135, v63
	v_add_f32_e64 v60, v132, v60
	v_add_f32_e64 v61, v133, v61
	v_pk_add_f32 v[62:63], v[138:139], v[62:63]
	v_pk_add_f32 v[60:61], v[136:137], v[60:61]
	s_waitcnt lgkmcnt(0)
	v_mfma_f32_32x32x16_bf16 v[16:31], v[32:35], v[52:55], v[16:31]
	ds_read_b128 v[56:59], v238 offset:24576
	v_add_f32_e64 v62, v154, v62
	v_add_f32_e64 v63, v155, v63
	v_add_f32_e64 v60, v152, v60
	v_add_f32_e64 v61, v153, v61
	v_pk_add_f32 v[130:131], v[158:159], v[62:63]
	v_pk_add_f32 v[128:129], v[156:157], v[60:61]
	v_mfma_f32_32x32x16_bf16 v[0:15], v[36:39], v[52:55], v[0:15]
	ds_read_b128 v[32:35], v238 offset:28672
	v_mfma_f32_32x32x16_bf16 v[80:95], v[40:43], v[44:47], v[80:95]
	ds_read_b128 v[36:39], v239 offset:16384
	v_cvt_pk_bf16_f32 v52, v152, v153
	v_cvt_pk_bf16_f32 v53, v154, v155
	v_cvt_pk_bf16_f32 v54, v156, v157
	v_cvt_pk_bf16_f32 v55, v158, v159
	v_mfma_f32_32x32x16_bf16 v[64:79], v[48:51], v[44:47], v[64:79]
	ds_read_b128 v[40:43], v239 offset:20480
	s_waitcnt lgkmcnt(0)
	v_mfma_f32_32x32x16_bf16 v[16:31], v[56:59], v[44:47], v[16:31]
	ds_read_b128 v[48:51], v239 offset:24576
	v_mfma_f32_32x32x16_bf16 v[0:15], v[32:35], v[44:47], v[0:15]
	ds_read_b128 v[56:59], v239 offset:28672
	v_mfma_f32_32x32x16_bf16 v[80:95], v[36:39], v[52:55], v[80:95]
	v_mfma_f32_32x32x16_bf16 v[64:79], v[40:43], v[52:55], v[64:79]
	s_waitcnt lgkmcnt(0)
	v_mfma_f32_32x32x16_bf16 v[16:31], v[48:51], v[52:55], v[16:31]
	v_mfma_f32_32x32x16_bf16 v[0:15], v[56:59], v[52:55], v[0:15]
	s_waitcnt vmcnt(4) lgkmcnt(0)
	s_barrier
	s_add_u32 s68, s98, 0x18000
	s_addc_u32 s69, s99, 0
	s_add_i32 s49, s49, s57
	s_mov_b32 m0, s49
	s_nop 0
	global_load_lds_dwordx4 v198, s[68:69]
	s_add_i32 m0, s49, 0x400
	s_nop 0
	global_load_lds_dwordx4 v194, s[68:69]
	s_add_u32 s44, s100, 0x80
	s_addc_u32 s45, s101, 0
	s_and_b32 s49, s20, 0xc000
	s_add_i32 s49, s58, s49
	s_add_i32 m0, s49, 0xc000
	s_nop 0
	global_load_lds_dwordx4 v196, s[44:45]
	s_add_i32 m0, s49, 0xc400
	s_nop 0
	global_load_lds_dwordx4 v192, s[44:45]
	s_add_i32 s48, s48, 0xc000
	s_add_i32 s44, s41, 1
	s_cmp_lg_u32 s41, 2
	s_cselect_b32 s41, s44, 0
	s_lshl_b32 s44, s41, 14
	s_add_i32 s44, s44, 0
	v_exp_f32_e32 v144, v112
	ds_read_b128 v[32:35], v205
	ds_read_b128 v[36:39], v205 offset:8192
	s_waitcnt lgkmcnt(0)
	v_mfma_f32_32x32x16_bf16 v[48:63], v[32:35], v[160:163], 0
	ds_read_b128 v[132:135], v211
	ds_read_b128 v[136:139], v211 offset:8192
	ds_read_b128 v[140:143], v212
	v_exp_f32_e32 v145, v113
	v_exp_f32_e32 v146, v114
	v_exp_f32_e32 v147, v115
	ds_read_b128 v[112:115], v212 offset:8192
	v_mfma_f32_32x32x16_bf16 v[32:47], v[36:39], v[160:163], 0
	v_exp_f32_e32 v148, v116
	v_exp_f32_e32 v149, v117
	v_exp_f32_e32 v150, v118
	v_exp_f32_e32 v151, v119
	s_waitcnt lgkmcnt(0)
	v_mfma_f32_32x32x16_bf16 v[48:63], v[132:135], v[164:167], v[48:63]
	ds_read_b128 v[116:119], v213
	v_exp_f32_e32 v152, v120
	v_exp_f32_e32 v153, v121
	v_exp_f32_e32 v154, v122
	v_exp_f32_e32 v155, v123
	v_mfma_f32_32x32x16_bf16 v[32:47], v[136:139], v[164:167], v[32:47]
	ds_read_b128 v[120:123], v213 offset:8192
	v_exp_f32_e32 v156, v124
	v_exp_f32_e32 v157, v125
	v_exp_f32_e32 v158, v126
	v_exp_f32_e32 v159, v127
	v_mfma_f32_32x32x16_bf16 v[48:63], v[140:143], v[168:171], v[48:63]
	ds_read_b128 v[124:127], v236 offset:32768
	v_exp_f32_e32 v136, v96
	v_exp_f32_e32 v137, v97
	v_exp_f32_e32 v138, v98
	v_exp_f32_e32 v139, v99
	v_mfma_f32_32x32x16_bf16 v[32:47], v[112:115], v[168:171], v[32:47]
	ds_read_b128 v[96:99], v236 offset:36864
	v_exp_f32_e32 v140, v100
	v_exp_f32_e32 v141, v101
	v_exp_f32_e32 v142, v102
	v_exp_f32_e32 v143, v103
	s_waitcnt lgkmcnt(0)
	v_mfma_f32_32x32x16_bf16 v[48:63], v[116:119], v[172:175], v[48:63]
	ds_read_b128 v[100:103], v236 offset:40960
	v_exp_f32_e32 v178, v104
	v_exp_f32_e32 v179, v105
	v_exp_f32_e32 v180, v106
	v_exp_f32_e32 v181, v107
	v_mfma_f32_32x32x16_bf16 v[32:47], v[120:123], v[172:175], v[32:47]
	ds_read_b128 v[104:107], v236 offset:45056
	v_exp_f32_e32 v182, v108
	v_exp_f32_e32 v183, v109
	v_exp_f32_e32 v184, v110
	v_exp_f32_e32 v185, v111
	v_cvt_pk_bf16_f32 v108, v144, v145
	v_cvt_pk_bf16_f32 v109, v146, v147
	v_cvt_pk_bf16_f32 v110, v148, v149
	v_cvt_pk_bf16_f32 v111, v150, v151
	s_nop 1
	v_mfma_f32_32x32x16_bf16 v[80:95], v[124:127], v[108:111], v[80:95]
	ds_read_b128 v[112:115], v237 offset:32768
	v_cvt_pk_bf16_f32 v116, v152, v153
	v_cvt_pk_bf16_f32 v117, v154, v155
	v_cvt_pk_bf16_f32 v118, v156, v157
	v_cvt_pk_bf16_f32 v119, v158, v159
	v_mfma_f32_32x32x16_bf16 v[64:79], v[96:99], v[108:111], v[64:79]
	ds_read_b128 v[120:123], v237 offset:36864
	v_pk_add_f32 v[126:127], v[150:151], v[146:147]
	v_pk_add_f32 v[124:125], v[148:149], v[144:145]
	s_waitcnt lgkmcnt(0)
	v_mfma_f32_32x32x16_bf16 v[16:31], v[100:103], v[108:111], v[16:31]
	ds_read_b128 v[132:135], v237 offset:40960
	v_add_f32_e64 v98, v154, v126
	v_add_f32_e64 v99, v155, v127
	v_add_f32_e64 v96, v152, v124
	v_add_f32_e64 v97, v153, v125
	v_pk_add_f32 v[98:99], v[158:159], v[98:99]
	v_pk_add_f32 v[96:97], v[156:157], v[96:97]
	v_mfma_f32_32x32x16_bf16 v[0:15], v[104:107], v[108:111], v[0:15]
	ds_read_b128 v[100:103], v237 offset:45056
	v_mfma_f32_32x32x16_bf16 v[80:95], v[112:115], v[116:119], v[80:95]
	ds_read_b128 v[104:107], v238 offset:32768
	v_cvt_pk_bf16_f32 v108, v136, v137
	v_cvt_pk_bf16_f32 v109, v138, v139
	v_cvt_pk_bf16_f32 v110, v140, v141
	v_cvt_pk_bf16_f32 v111, v142, v143
	v_mfma_f32_32x32x16_bf16 v[64:79], v[120:123], v[116:119], v[64:79]
	ds_read_b128 v[112:115], v238 offset:36864
	v_add_f32_e64 v98, v138, v98
	v_add_f32_e64 v99, v139, v99
	v_add_f32_e64 v96, v136, v96
	v_add_f32_e64 v97, v137, v97
	v_pk_add_f32 v[98:99], v[142:143], v[98:99]
	v_pk_add_f32 v[96:97], v[140:141], v[96:97]
	s_waitcnt lgkmcnt(0)
	v_mfma_f32_32x32x16_bf16 v[16:31], v[132:135], v[116:119], v[16:31]
	ds_read_b128 v[120:123], v238 offset:40960
	v_add_f32_e64 v98, v180, v98
	v_add_f32_e64 v99, v181, v99
	v_add_f32_e64 v96, v178, v96
	v_add_f32_e64 v97, v179, v97
	v_pk_add_f32 v[98:99], v[184:185], v[98:99]
	v_pk_add_f32 v[96:97], v[182:183], v[96:97]
	v_mfma_f32_32x32x16_bf16 v[0:15], v[100:103], v[116:119], v[0:15]
	ds_read_b128 v[124:127], v238 offset:45056
	v_mfma_f32_32x32x16_bf16 v[80:95], v[104:107], v[108:111], v[80:95]
	ds_read_b128 v[100:103], v239 offset:32768
	v_cvt_pk_bf16_f32 v116, v178, v179
	v_cvt_pk_bf16_f32 v117, v180, v181
	v_cvt_pk_bf16_f32 v118, v182, v183
	v_cvt_pk_bf16_f32 v119, v184, v185
	v_mfma_f32_32x32x16_bf16 v[64:79], v[112:115], v[108:111], v[64:79]
	ds_read_b128 v[104:107], v239 offset:36864
	s_waitcnt lgkmcnt(0)
	v_mfma_f32_32x32x16_bf16 v[16:31], v[120:123], v[108:111], v[16:31]
	ds_read_b128 v[112:115], v239 offset:40960
	v_mfma_f32_32x32x16_bf16 v[0:15], v[124:127], v[108:111], v[0:15]
	ds_read_b128 v[120:123], v239 offset:45056
	v_mfma_f32_32x32x16_bf16 v[80:95], v[100:103], v[116:119], v[80:95]
	v_mfma_f32_32x32x16_bf16 v[64:79], v[104:107], v[116:119], v[64:79]
	s_waitcnt lgkmcnt(0)
	v_mfma_f32_32x32x16_bf16 v[16:31], v[112:115], v[116:119], v[16:31]
	v_mfma_f32_32x32x16_bf16 v[0:15], v[120:123], v[116:119], v[0:15]
	s_waitcnt vmcnt(4) lgkmcnt(0)
	v_add_f32_e32 v100, v128, v129
	v_add_f32_e32 v101, v130, v131
	v_add_f32_e32 v100, v100, v101
	v_add_f32_e32 v96, v96, v97
	v_add_f32_e32 v97, v98, v99
	s_barrier
	v_add_f32_e32 v100, v177, v100
	v_add_f32_e32 v96, v96, v97
	v_add_f32_e32 v177, v100, v96
	s_add_i32 s21, s21, 2
	s_addk_i32 s15, 0x80
	s_add_i32 s20, s20, 0x8000
	s_add_u32 s98, s98, 0x30000
	s_addc_u32 s99, s99, 0
	s_add_u32 s100, s100, 0x100
	s_addc_u32 s101, s101, 0
	s_cmp_lt_u32 s21, 50
	s_cbranch_scc1 .Lst0_u6_loop
	s_cmp_lt_u32 s21, 60
	s_cbranch_scc1 .Lst0_single

.Lst1_loop:
	s_cmp_lg_u32 s48, 0
	s_cbranch_scc1 .Lst1_single
	s_and_b32 s2, s46, 0xffff
	s_cmp_lg_u32 s2, 0x8000
	s_cbranch_scc1 .Lst1_single
	s_cmp_lt_u32 s47, 50
	s_cbranch_scc1 .Lst1_u6

.Lst1_u6_loop:
	s_lshl_b32 s49, s48, 14
	s_add_i32 s49, s58, s49
	s_mov_b32 m0, s49
	s_nop 0
	global_load_lds_dwordx4 v198, s[98:99]
	s_add_i32 m0, s49, 0x400
	s_nop 0
	global_load_lds_dwordx4 v194, s[98:99]
	s_add_i32 s49, s46, 0xffffc000
	s_and_b32 s49, s49, 0xc000
	s_add_i32 s49, s58, s49
	s_add_i32 m0, s49, 0xc000
	s_nop 0
	global_load_lds_dwordx4 v196, s[100:101]
	s_add_i32 m0, s49, 0xc400
	s_add_i32 s44, s48, 1
	global_load_lds_dwordx4 v192, s[100:101]
	s_cmp_lg_u32 s48, 2
	s_cselect_b32 s48, s44, 0
	s_lshl_b32 s44, s48, 14
	s_and_b32 s49, s46, 0xc000
	s_add_i32 s68, s44, 0
	s_add_i32 s44, s49, 0
	ds_read_b128 v[140:143], v236 offset:16384
	ds_read_b128 v[148:151], v236 offset:20480
	ds_read_b128 v[152:155], v236 offset:24576
	ds_read_b128 v[156:159], v236 offset:28672
	s_waitcnt lgkmcnt(0)
	v_mfma_f32_32x32x16_bf16 v[80:95], v[140:143], v[144:147], v[80:95]
	ds_read_b128 v[140:143], v237 offset:16384
	v_mfma_f32_32x32x16_bf16 v[64:79], v[148:151], v[144:147], v[64:79]
	ds_read_b128 v[148:151], v237 offset:20480
	v_mfma_f32_32x32x16_bf16 v[16:31], v[152:155], v[144:147], v[16:31]
	ds_read_b128 v[152:155], v237 offset:24576
	v_mfma_f32_32x32x16_bf16 v[0:15], v[156:159], v[144:147], v[0:15]
	ds_read_b128 v[144:147], v237 offset:28672
	s_waitcnt lgkmcnt(0)
	v_mfma_f32_32x32x16_bf16 v[80:95], v[140:143], v[128:131], v[80:95]
	ds_read_b128 v[140:143], v238 offset:16384
	v_mfma_f32_32x32x16_bf16 v[64:79], v[148:151], v[128:131], v[64:79]
	ds_read_b128 v[148:151], v238 offset:20480
	v_mfma_f32_32x32x16_bf16 v[16:31], v[152:155], v[128:131], v[16:31]
	ds_read_b128 v[152:155], v238 offset:24576
	v_mfma_f32_32x32x16_bf16 v[0:15], v[144:147], v[128:131], v[0:15]
	ds_read_b128 v[128:131], v238 offset:28672
	s_waitcnt lgkmcnt(0)
	v_mfma_f32_32x32x16_bf16 v[80:95], v[140:143], v[132:135], v[80:95]
	ds_read_b128 v[140:143], v239 offset:16384
	v_mfma_f32_32x32x16_bf16 v[64:79], v[148:151], v[132:135], v[64:79]
	ds_read_b128 v[144:147], v239 offset:20480
	v_mfma_f32_32x32x16_bf16 v[16:31], v[152:155], v[132:135], v[16:31]
	ds_read_b128 v[148:151], v239 offset:24576
	v_mfma_f32_32x32x16_bf16 v[0:15], v[128:131], v[132:135], v[0:15]
	ds_read_b128 v[128:131], v239 offset:28672
	s_waitcnt lgkmcnt(0)
	v_mfma_f32_32x32x16_bf16 v[80:95], v[140:143], v[136:139], v[80:95]
	ds_read_b128 v[132:135], v205 offset:16384
	v_mfma_f32_32x32x16_bf16 v[64:79], v[144:147], v[136:139], v[64:79]
	ds_read_b128 v[140:143], v205 offset:24576
	v_mfma_f32_32x32x16_bf16 v[16:31], v[148:151], v[136:139], v[16:31]
	ds_read_b128 v[176:179], v211 offset:16384
	v_mfma_f32_32x32x16_bf16 v[0:15], v[128:131], v[136:139], v[0:15]
	ds_read_b128 v[182:185], v211 offset:24576
	s_waitcnt lgkmcnt(0)
	v_mfma_f32_32x32x16_bf16 v[144:159], v[132:135], v[160:163], 0
	ds_read_b128 v[186:189], v212 offset:16384
	v_exp_f32_e32 v220, v112
	v_exp_f32_e32 v221, v113
	v_exp_f32_e32 v222, v114
	v_exp_f32_e32 v223, v115
	v_mfma_f32_32x32x16_bf16 v[128:143], v[140:143], v[160:163], 0
	ds_read_b128 v[216:219], v212 offset:24576
	v_exp_f32_e32 v224, v116
	v_exp_f32_e32 v225, v117
	v_exp_f32_e32 v226, v118
	v_exp_f32_e32 v227, v119
	v_mfma_f32_32x32x16_bf16 v[144:159], v[176:179], v[164:167], v[144:159]
	ds_read_b128 v[116:119], v213 offset:16384
	v_exp_f32_e32 v228, v120
	v_exp_f32_e32 v229, v121
	v_exp_f32_e32 v230, v122
	v_exp_f32_e32 v231, v123
	v_cvt_pk_bf16_f32 v112, v220, v221
	v_cvt_pk_bf16_f32 v113, v222, v223
	v_cvt_pk_bf16_f32 v114, v224, v225
	v_cvt_pk_bf16_f32 v115, v226, v227
	v_pk_add_f32 v[122:123], v[226:227], v[222:223]
	v_pk_add_f32 v[120:121], v[224:225], v[220:221]
	v_mfma_f32_32x32x16_bf16 v[128:143], v[182:185], v[164:167], v[128:143]
	ds_read_b128 v[176:179], v213 offset:24576
	v_exp_f32_e32 v124, v124
	v_exp_f32_e32 v125, v125
	v_exp_f32_e32 v126, v126
	v_exp_f32_e32 v127, v127
	s_waitcnt lgkmcnt(0)
	v_mfma_f32_32x32x16_bf16 v[144:159], v[186:189], v[168:171], v[144:159]
	v_add_f32_e64 v122, v230, v122
	v_add_f32_e64 v123, v231, v123
	v_add_f32_e64 v120, v228, v120
	v_add_f32_e64 v121, v229, v121
	v_exp_f32_e32 v182, v96
	v_exp_f32_e32 v183, v97
	v_exp_f32_e32 v184, v98
	v_exp_f32_e32 v185, v99
	v_cvt_pk_bf16_f32 v96, v228, v229
	v_cvt_pk_bf16_f32 v97, v230, v231
	v_cvt_pk_bf16_f32 v98, v124, v125
	v_cvt_pk_bf16_f32 v99, v126, v127
	v_pk_add_f32 v[122:123], v[126:127], v[122:123]
	v_pk_add_f32 v[120:121], v[124:125], v[120:121]
	v_mfma_f32_32x32x16_bf16 v[128:143], v[216:219], v[168:171], v[128:143]
	v_exp_f32_e32 v124, v100
	v_exp_f32_e32 v125, v101
	v_exp_f32_e32 v126, v102
	v_exp_f32_e32 v127, v103
	v_mfma_f32_32x32x16_bf16 v[144:159], v[116:119], v[172:175], v[144:159]
	v_exp_f32_e32 v186, v104
	v_exp_f32_e32 v187, v105
	v_exp_f32_e32 v188, v106
	v_exp_f32_e32 v189, v107
	v_pk_add_f32 v[106:107], v[184:185], v[122:123]
	v_pk_add_f32 v[104:105], v[182:183], v[120:121]
	v_cvt_pk_bf16_f32 v100, v182, v183
	v_cvt_pk_bf16_f32 v101, v184, v185
	v_cvt_pk_bf16_f32 v102, v124, v125
	v_cvt_pk_bf16_f32 v103, v126, v127
	v_pk_add_f32 v[118:119], v[126:127], v[106:107]
	v_pk_add_f32 v[116:117], v[124:125], v[104:105]
	v_mfma_f32_32x32x16_bf16 v[128:143], v[176:179], v[172:175], v[128:143]
	v_exp_f32_e32 v120, v108
	v_exp_f32_e32 v121, v109
	v_exp_f32_e32 v122, v110
	v_exp_f32_e32 v123, v111
	v_pk_add_f32 v[110:111], v[188:189], v[118:119]
	v_pk_add_f32 v[108:109], v[186:187], v[116:117]
	v_cvt_pk_bf16_f32 v104, v186, v187
	v_cvt_pk_bf16_f32 v105, v188, v189
	v_cvt_pk_bf16_f32 v106, v120, v121
	v_cvt_pk_bf16_f32 v107, v122, v123
	v_pk_add_f32 v[178:179], v[122:123], v[110:111]
	v_pk_add_f32 v[176:177], v[120:121], v[108:109]
	s_waitcnt vmcnt(4) lgkmcnt(0)
	s_barrier
	s_add_u32 s70, s98, 0x18000
	s_addc_u32 s71, s99, 0
	s_add_i32 s68, s68, s57
	s_mov_b32 m0, s68
	s_nop 0
	global_load_lds_dwordx4 v198, s[70:71]
	s_add_i32 m0, s68, 0x400
	s_nop 0
	global_load_lds_dwordx4 v194, s[70:71]
	s_add_u32 s2, s100, 0x80
	s_addc_u32 s3, s101, 0
	s_add_i32 s49, s58, s49
	s_add_i32 m0, s49, 0xc000
	s_nop 0
	global_load_lds_dwordx4 v196, s[2:3]
	s_add_i32 m0, s49, 0xc400
	s_nop 0
	global_load_lds_dwordx4 v192, s[2:3]
	s_add_i32 s2, s46, 0xffff4000
	s_add_i32 s3, s48, 1
	s_cmp_lg_u32 s48, 2
	s_cselect_b32 s48, s3, 0
	s_and_b32 s2, s2, 0xc000
	s_add_i32 s2, s2, 0
	s_lshl_b32 s3, s48, 14
	ds_read_b128 v[108:111], v236 offset:32768
	ds_read_b128 v[116:119], v236 offset:36864
	ds_read_b128 v[120:123], v236 offset:40960
	ds_read_b128 v[124:127], v236 offset:45056
	s_waitcnt lgkmcnt(0)
	v_mfma_f32_32x32x16_bf16 v[80:95], v[108:111], v[112:115], v[80:95]
	ds_read_b128 v[108:111], v237 offset:32768
	s_add_i32 s3, s3, 0
	v_mfma_f32_32x32x16_bf16 v[64:79], v[116:119], v[112:115], v[64:79]
	ds_read_b128 v[116:119], v237 offset:36864
	v_mfma_f32_32x32x16_bf16 v[16:31], v[120:123], v[112:115], v[16:31]
	ds_read_b128 v[120:123], v237 offset:40960
	v_mfma_f32_32x32x16_bf16 v[0:15], v[124:127], v[112:115], v[0:15]
	ds_read_b128 v[112:115], v237 offset:45056
	s_waitcnt lgkmcnt(0)
	v_mfma_f32_32x32x16_bf16 v[80:95], v[108:111], v[96:99], v[80:95]
	ds_read_b128 v[108:111], v238 offset:32768
	v_mfma_f32_32x32x16_bf16 v[64:79], v[116:119], v[96:99], v[64:79]
	ds_read_b128 v[116:119], v238 offset:36864
	v_mfma_f32_32x32x16_bf16 v[16:31], v[120:123], v[96:99], v[16:31]
	ds_read_b128 v[120:123], v238 offset:40960
	v_mfma_f32_32x32x16_bf16 v[0:15], v[112:115], v[96:99], v[0:15]
	ds_read_b128 v[96:99], v238 offset:45056
	s_waitcnt lgkmcnt(0)
	v_mfma_f32_32x32x16_bf16 v[80:95], v[108:111], v[100:103], v[80:95]
	ds_read_b128 v[108:111], v239 offset:32768
	v_mfma_f32_32x32x16_bf16 v[64:79], v[116:119], v[100:103], v[64:79]
	ds_read_b128 v[112:115], v239 offset:36864
	v_mfma_f32_32x32x16_bf16 v[16:31], v[120:123], v[100:103], v[16:31]
	ds_read_b128 v[116:119], v239 offset:40960
	v_mfma_f32_32x32x16_bf16 v[0:15], v[96:99], v[100:103], v[0:15]
	ds_read_b128 v[120:123], v239 offset:45056
	s_waitcnt lgkmcnt(0)
	v_mfma_f32_32x32x16_bf16 v[80:95], v[108:111], v[104:107], v[80:95]
	ds_read_b128 v[96:99], v205 offset:32768
	v_mfma_f32_32x32x16_bf16 v[64:79], v[112:115], v[104:107], v[64:79]
	ds_read_b128 v[100:103], v205 offset:40960
	v_mfma_f32_32x32x16_bf16 v[16:31], v[116:119], v[104:107], v[16:31]
	ds_read_b128 v[182:185], v211 offset:32768
	v_mfma_f32_32x32x16_bf16 v[0:15], v[120:123], v[104:107], v[0:15]
	ds_read_b128 v[186:189], v211 offset:40960
	s_waitcnt lgkmcnt(0)
	v_mfma_f32_32x32x16_bf16 v[112:127], v[96:99], v[160:163], 0
	ds_read_b128 v[216:219], v212 offset:32768
	v_exp_f32_e32 v224, v144
	v_exp_f32_e32 v225, v145
	v_exp_f32_e32 v226, v146
	v_exp_f32_e32 v227, v147
	ds_read_b128 v[220:223], v212 offset:40960
	v_mfma_f32_32x32x16_bf16 v[96:111], v[100:103], v[160:163], 0
	v_exp_f32_e32 v228, v148
	v_exp_f32_e32 v229, v149
	v_exp_f32_e32 v230, v150
	v_exp_f32_e32 v231, v151
	v_mfma_f32_32x32x16_bf16 v[112:127], v[182:185], v[164:167], v[112:127]
	ds_read_b128 v[148:151], v213 offset:32768
	v_exp_f32_e32 v232, v152
	v_exp_f32_e32 v233, v153
	v_exp_f32_e32 v234, v154
	v_exp_f32_e32 v235, v155
	v_cvt_pk_bf16_f32 v144, v224, v225
	v_cvt_pk_bf16_f32 v145, v226, v227
	v_cvt_pk_bf16_f32 v146, v228, v229
	v_cvt_pk_bf16_f32 v147, v230, v231
	v_pk_add_f32 v[154:155], v[230:231], v[226:227]
	v_pk_add_f32 v[152:153], v[228:229], v[224:225]
	v_mfma_f32_32x32x16_bf16 v[96:111], v[186:189], v[164:167], v[96:111]
	ds_read_b128 v[182:185], v213 offset:40960
	v_exp_f32_e32 v156, v156
	v_exp_f32_e32 v157, v157
	v_exp_f32_e32 v158, v158
	v_exp_f32_e32 v159, v159
	s_waitcnt lgkmcnt(0)
	v_mfma_f32_32x32x16_bf16 v[112:127], v[216:219], v[168:171], v[112:127]
	v_add_f32_e64 v154, v234, v154
	v_add_f32_e64 v155, v235, v155
	v_add_f32_e64 v152, v232, v152
	v_add_f32_e64 v153, v233, v153
	v_exp_f32_e32 v186, v128
	v_exp_f32_e32 v187, v129
	v_exp_f32_e32 v188, v130
	v_exp_f32_e32 v189, v131
	v_cvt_pk_bf16_f32 v128, v232, v233
	v_cvt_pk_bf16_f32 v129, v234, v235
	v_cvt_pk_bf16_f32 v130, v156, v157
	v_cvt_pk_bf16_f32 v131, v158, v159
	v_pk_add_f32 v[154:155], v[158:159], v[154:155]
	v_pk_add_f32 v[152:153], v[156:157], v[152:153]
	v_mfma_f32_32x32x16_bf16 v[96:111], v[220:223], v[168:171], v[96:111]
	v_exp_f32_e32 v156, v132
	v_exp_f32_e32 v157, v133
	v_exp_f32_e32 v158, v134
	v_exp_f32_e32 v159, v135
	v_mfma_f32_32x32x16_bf16 v[112:127], v[148:151], v[172:175], v[112:127]
	v_exp_f32_e32 v216, v136
	v_exp_f32_e32 v217, v137
	v_exp_f32_e32 v218, v138
	v_exp_f32_e32 v219, v139
	v_pk_add_f32 v[138:139], v[188:189], v[154:155]
	v_pk_add_f32 v[136:137], v[186:187], v[152:153]
	v_cvt_pk_bf16_f32 v132, v186, v187
	v_cvt_pk_bf16_f32 v133, v188, v189
	v_cvt_pk_bf16_f32 v134, v156, v157
	v_cvt_pk_bf16_f32 v135, v158, v159
	v_pk_add_f32 v[150:151], v[158:159], v[138:139]
	v_pk_add_f32 v[148:149], v[156:157], v[136:137]
	v_mfma_f32_32x32x16_bf16 v[96:111], v[182:185], v[172:175], v[96:111]
	v_exp_f32_e32 v152, v140
	v_exp_f32_e32 v153, v141
	v_exp_f32_e32 v154, v142
	v_exp_f32_e32 v155, v143
	v_pk_add_f32 v[142:143], v[218:219], v[150:151]
	v_pk_add_f32 v[140:141], v[216:217], v[148:149]
	v_cvt_pk_bf16_f32 v136, v216, v217
	v_cvt_pk_bf16_f32 v137, v218, v219
	v_cvt_pk_bf16_f32 v138, v152, v153
	v_cvt_pk_bf16_f32 v139, v154, v155
	v_pk_add_f32 v[142:143], v[154:155], v[142:143]
	v_pk_add_f32 v[140:141], v[152:153], v[140:141]
	s_waitcnt vmcnt(4) lgkmcnt(0)
	v_add_f32_e32 v148, v176, v177
	v_add_f32_e32 v149, v178, v179
	v_add_f32_e32 v148, v148, v149
	v_add_f32_e32 v140, v140, v141
	v_add_f32_e32 v141, v142, v143
	s_barrier
	v_add_f32_e32 v148, v180, v148
	v_add_f32_e32 v140, v140, v141
	v_add_f32_e32 v180, v148, v140
	s_add_i32 s47, s47, 2
	s_addk_i32 s41, 0x80
	s_add_i32 s46, s46, 0x8000
	s_add_u32 s98, s98, 0x30000
	s_addc_u32 s99, s99, 0
	s_add_u32 s100, s100, 0x100
	s_addc_u32 s101, s101, 0
	s_lshl_b32 s49, s48, 14
	s_add_i32 s49, s58, s49
	s_mov_b32 m0, s49
	s_nop 0
	global_load_lds_dwordx4 v198, s[98:99]
	s_add_i32 m0, s49, 0x400
	s_nop 0
	global_load_lds_dwordx4 v194, s[98:99]
	s_add_i32 s49, s46, 0xffffc000
	s_and_b32 s49, s49, 0xc000
	s_add_i32 s49, s58, s49
	s_add_i32 m0, s49, 0xc000
	s_nop 0
	global_load_lds_dwordx4 v196, s[100:101]
	s_add_i32 m0, s49, 0xc400
	s_add_i32 s44, s48, 1
	global_load_lds_dwordx4 v192, s[100:101]
	s_cmp_lg_u32 s48, 2
	s_cselect_b32 s48, s44, 0
	s_lshl_b32 s44, s48, 14
	s_and_b32 s49, s46, 0xc000
	s_add_i32 s68, s44, 0
	s_add_i32 s44, s49, 0
	ds_read_b128 v[140:143], v206 offset:49152
	ds_read_b128 v[148:151], v206 offset:53248
	ds_read_b128 v[152:155], v206 offset:57344
	ds_read_b128 v[156:159], v206 offset:61440
	s_waitcnt lgkmcnt(0)
	v_mfma_f32_32x32x16_bf16 v[80:95], v[140:143], v[144:147], v[80:95]
	ds_read_b128 v[140:143], v207 offset:49152
	v_mfma_f32_32x32x16_bf16 v[64:79], v[148:151], v[144:147], v[64:79]
	ds_read_b128 v[148:151], v207 offset:53248
	v_mfma_f32_32x32x16_bf16 v[16:31], v[152:155], v[144:147], v[16:31]
	ds_read_b128 v[152:155], v207 offset:57344
	v_mfma_f32_32x32x16_bf16 v[0:15], v[156:159], v[144:147], v[0:15]
	ds_read_b128 v[144:147], v207 offset:61440
	s_waitcnt lgkmcnt(0)
	v_mfma_f32_32x32x16_bf16 v[80:95], v[140:143], v[128:131], v[80:95]
	ds_read_b128 v[140:143], v208 offset:49152
	v_mfma_f32_32x32x16_bf16 v[64:79], v[148:151], v[128:131], v[64:79]
	ds_read_b128 v[148:151], v208 offset:53248
	v_mfma_f32_32x32x16_bf16 v[16:31], v[152:155], v[128:131], v[16:31]
	ds_read_b128 v[152:155], v208 offset:57344
	v_mfma_f32_32x32x16_bf16 v[0:15], v[144:147], v[128:131], v[0:15]
	ds_read_b128 v[128:131], v208 offset:61440
	s_waitcnt lgkmcnt(0)
	v_mfma_f32_32x32x16_bf16 v[80:95], v[140:143], v[132:135], v[80:95]
	ds_read_b128 v[140:143], v209 offset:49152
	v_mfma_f32_32x32x16_bf16 v[64:79], v[148:151], v[132:135], v[64:79]
	ds_read_b128 v[144:147], v209 offset:53248
	v_mfma_f32_32x32x16_bf16 v[16:31], v[152:155], v[132:135], v[16:31]
	ds_read_b128 v[148:151], v209 offset:57344
	v_mfma_f32_32x32x16_bf16 v[0:15], v[128:131], v[132:135], v[0:15]
	ds_read_b128 v[128:131], v209 offset:61440
	s_waitcnt lgkmcnt(0)
	v_mfma_f32_32x32x16_bf16 v[80:95], v[140:143], v[136:139], v[80:95]
	ds_read_b128 v[132:135], v205
	v_mfma_f32_32x32x16_bf16 v[64:79], v[144:147], v[136:139], v[64:79]
	ds_read_b128 v[140:143], v205 offset:8192
	v_mfma_f32_32x32x16_bf16 v[16:31], v[148:151], v[136:139], v[16:31]
	ds_read_b128 v[176:179], v211
	v_mfma_f32_32x32x16_bf16 v[0:15], v[128:131], v[136:139], v[0:15]
	ds_read_b128 v[182:185], v211 offset:8192
	s_waitcnt lgkmcnt(0)
	v_mfma_f32_32x32x16_bf16 v[144:159], v[132:135], v[160:163], 0
	ds_read_b128 v[186:189], v212
	v_exp_f32_e32 v220, v112
	v_exp_f32_e32 v221, v113
	v_exp_f32_e32 v222, v114
	v_exp_f32_e32 v223, v115
	v_mfma_f32_32x32x16_bf16 v[128:143], v[140:143], v[160:163], 0
	ds_read_b128 v[216:219], v212 offset:8192
	v_exp_f32_e32 v224, v116
	v_exp_f32_e32 v225, v117
	v_exp_f32_e32 v226, v118
	v_exp_f32_e32 v227, v119
	v_mfma_f32_32x32x16_bf16 v[144:159], v[176:179], v[164:167], v[144:159]
	ds_read_b128 v[116:119], v213
	v_exp_f32_e32 v228, v120
	v_exp_f32_e32 v229, v121
	v_exp_f32_e32 v230, v122
	v_exp_f32_e32 v231, v123
	v_cvt_pk_bf16_f32 v112, v220, v221
	v_cvt_pk_bf16_f32 v113, v222, v223
	v_cvt_pk_bf16_f32 v114, v224, v225
	v_cvt_pk_bf16_f32 v115, v226, v227
	v_pk_add_f32 v[122:123], v[226:227], v[222:223]
	v_pk_add_f32 v[120:121], v[224:225], v[220:221]
	v_mfma_f32_32x32x16_bf16 v[128:143], v[182:185], v[164:167], v[128:143]
	ds_read_b128 v[176:179], v213 offset:8192
	v_exp_f32_e32 v124, v124
	v_exp_f32_e32 v125, v125
	v_exp_f32_e32 v126, v126
	v_exp_f32_e32 v127, v127
	s_waitcnt lgkmcnt(0)
	v_mfma_f32_32x32x16_bf16 v[144:159], v[186:189], v[168:171], v[144:159]
	v_add_f32_e64 v122, v230, v122
	v_add_f32_e64 v123, v231, v123
	v_add_f32_e64 v120, v228, v120
	v_add_f32_e64 v121, v229, v121
	v_exp_f32_e32 v182, v96
	v_exp_f32_e32 v183, v97
	v_exp_f32_e32 v184, v98
	v_exp_f32_e32 v185, v99
	v_cvt_pk_bf16_f32 v96, v228, v229
	v_cvt_pk_bf16_f32 v97, v230, v231
	v_cvt_pk_bf16_f32 v98, v124, v125
	v_cvt_pk_bf16_f32 v99, v126, v127
	v_pk_add_f32 v[122:123], v[126:127], v[122:123]
	v_pk_add_f32 v[120:121], v[124:125], v[120:121]
	v_mfma_f32_32x32x16_bf16 v[128:143], v[216:219], v[168:171], v[128:143]
	v_exp_f32_e32 v124, v100
	v_exp_f32_e32 v125, v101
	v_exp_f32_e32 v126, v102
	v_exp_f32_e32 v127, v103
	v_mfma_f32_32x32x16_bf16 v[144:159], v[116:119], v[172:175], v[144:159]
	v_exp_f32_e32 v186, v104
	v_exp_f32_e32 v187, v105
	v_exp_f32_e32 v188, v106
	v_exp_f32_e32 v189, v107
	v_pk_add_f32 v[106:107], v[184:185], v[122:123]
	v_pk_add_f32 v[104:105], v[182:183], v[120:121]
	v_cvt_pk_bf16_f32 v100, v182, v183
	v_cvt_pk_bf16_f32 v101, v184, v185
	v_cvt_pk_bf16_f32 v102, v124, v125
	v_cvt_pk_bf16_f32 v103, v126, v127
	v_pk_add_f32 v[118:119], v[126:127], v[106:107]
	v_pk_add_f32 v[116:117], v[124:125], v[104:105]
	v_mfma_f32_32x32x16_bf16 v[128:143], v[176:179], v[172:175], v[128:143]
	v_exp_f32_e32 v120, v108
	v_exp_f32_e32 v121, v109
	v_exp_f32_e32 v122, v110
	v_exp_f32_e32 v123, v111
	v_pk_add_f32 v[110:111], v[188:189], v[118:119]
	v_pk_add_f32 v[108:109], v[186:187], v[116:117]
	v_cvt_pk_bf16_f32 v104, v186, v187
	v_cvt_pk_bf16_f32 v105, v188, v189
	v_cvt_pk_bf16_f32 v106, v120, v121
	v_cvt_pk_bf16_f32 v107, v122, v123
	v_pk_add_f32 v[178:179], v[122:123], v[110:111]
	v_pk_add_f32 v[176:177], v[120:121], v[108:109]
	s_waitcnt vmcnt(4) lgkmcnt(0)
	s_barrier
	s_add_u32 s70, s98, 0x18000
	s_addc_u32 s71, s99, 0
	s_add_i32 s68, s68, s57
	s_mov_b32 m0, s68
	s_nop 0
	global_load_lds_dwordx4 v198, s[70:71]
	s_add_i32 m0, s68, 0x400
	s_nop 0
	global_load_lds_dwordx4 v194, s[70:71]
	s_add_u32 s2, s100, 0x80
	s_addc_u32 s3, s101, 0
	s_add_i32 s49, s58, s49
	s_add_i32 m0, s49, 0xc000
	s_nop 0
	global_load_lds_dwordx4 v196, s[2:3]
	s_add_i32 m0, s49, 0xc400
	s_nop 0
	global_load_lds_dwordx4 v192, s[2:3]
	s_add_i32 s2, s46, 0xffff4000
	s_add_i32 s3, s48, 1
	s_cmp_lg_u32 s48, 2
	s_cselect_b32 s48, s3, 0
	s_and_b32 s2, s2, 0xc000
	s_add_i32 s2, s2, 0
	s_lshl_b32 s3, s48, 14
	ds_read_b128 v[108:111], v236
	ds_read_b128 v[116:119], v236 offset:4096
	ds_read_b128 v[120:123], v236 offset:8192
	ds_read_b128 v[124:127], v236 offset:12288
	s_waitcnt lgkmcnt(0)
	v_mfma_f32_32x32x16_bf16 v[80:95], v[108:111], v[112:115], v[80:95]
	ds_read_b128 v[108:111], v237
	s_add_i32 s3, s3, 0
	v_mfma_f32_32x32x16_bf16 v[64:79], v[116:119], v[112:115], v[64:79]
	ds_read_b128 v[116:119], v237 offset:4096
	v_mfma_f32_32x32x16_bf16 v[16:31], v[120:123], v[112:115], v[16:31]
	ds_read_b128 v[120:123], v237 offset:8192
	v_mfma_f32_32x32x16_bf16 v[0:15], v[124:127], v[112:115], v[0:15]
	ds_read_b128 v[112:115], v237 offset:12288
	s_waitcnt lgkmcnt(0)
	v_mfma_f32_32x32x16_bf16 v[80:95], v[108:111], v[96:99], v[80:95]
	ds_read_b128 v[108:111], v238
	v_mfma_f32_32x32x16_bf16 v[64:79], v[116:119], v[96:99], v[64:79]
	ds_read_b128 v[116:119], v238 offset:4096
	v_mfma_f32_32x32x16_bf16 v[16:31], v[120:123], v[96:99], v[16:31]
	ds_read_b128 v[120:123], v238 offset:8192
	v_mfma_f32_32x32x16_bf16 v[0:15], v[112:115], v[96:99], v[0:15]
	ds_read_b128 v[96:99], v238 offset:12288
	s_waitcnt lgkmcnt(0)
	v_mfma_f32_32x32x16_bf16 v[80:95], v[108:111], v[100:103], v[80:95]
	ds_read_b128 v[108:111], v239
	v_mfma_f32_32x32x16_bf16 v[64:79], v[116:119], v[100:103], v[64:79]
	ds_read_b128 v[112:115], v239 offset:4096
	v_mfma_f32_32x32x16_bf16 v[16:31], v[120:123], v[100:103], v[16:31]
	ds_read_b128 v[116:119], v239 offset:8192
	v_mfma_f32_32x32x16_bf16 v[0:15], v[96:99], v[100:103], v[0:15]
	ds_read_b128 v[120:123], v239 offset:12288
	s_waitcnt lgkmcnt(0)
	v_mfma_f32_32x32x16_bf16 v[80:95], v[108:111], v[104:107], v[80:95]
	ds_read_b128 v[96:99], v205 offset:16384
	v_mfma_f32_32x32x16_bf16 v[64:79], v[112:115], v[104:107], v[64:79]
	ds_read_b128 v[100:103], v205 offset:24576
	v_mfma_f32_32x32x16_bf16 v[16:31], v[116:119], v[104:107], v[16:31]
	ds_read_b128 v[182:185], v211 offset:16384
	v_mfma_f32_32x32x16_bf16 v[0:15], v[120:123], v[104:107], v[0:15]
	ds_read_b128 v[186:189], v211 offset:24576
	s_waitcnt lgkmcnt(0)
	v_mfma_f32_32x32x16_bf16 v[112:127], v[96:99], v[160:163], 0
	ds_read_b128 v[216:219], v212 offset:16384
	v_exp_f32_e32 v224, v144
	v_exp_f32_e32 v225, v145
	v_exp_f32_e32 v226, v146
	v_exp_f32_e32 v227, v147
	ds_read_b128 v[220:223], v212 offset:24576
	v_mfma_f32_32x32x16_bf16 v[96:111], v[100:103], v[160:163], 0
	v_exp_f32_e32 v228, v148
	v_exp_f32_e32 v229, v149
	v_exp_f32_e32 v230, v150
	v_exp_f32_e32 v231, v151
	v_mfma_f32_32x32x16_bf16 v[112:127], v[182:185], v[164:167], v[112:127]
	ds_read_b128 v[148:151], v213 offset:16384
	v_exp_f32_e32 v232, v152
	v_exp_f32_e32 v233, v153
	v_exp_f32_e32 v234, v154
	v_exp_f32_e32 v235, v155
	v_cvt_pk_bf16_f32 v144, v224, v225
	v_cvt_pk_bf16_f32 v145, v226, v227
	v_cvt_pk_bf16_f32 v146, v228, v229
	v_cvt_pk_bf16_f32 v147, v230, v231
	v_pk_add_f32 v[154:155], v[230:231], v[226:227]
	v_pk_add_f32 v[152:153], v[228:229], v[224:225]
	v_mfma_f32_32x32x16_bf16 v[96:111], v[186:189], v[164:167], v[96:111]
	ds_read_b128 v[182:185], v213 offset:24576
	v_exp_f32_e32 v156, v156
	v_exp_f32_e32 v157, v157
	v_exp_f32_e32 v158, v158
	v_exp_f32_e32 v159, v159
	s_waitcnt lgkmcnt(0)
	v_mfma_f32_32x32x16_bf16 v[112:127], v[216:219], v[168:171], v[112:127]
	v_add_f32_e64 v154, v234, v154
	v_add_f32_e64 v155, v235, v155
	v_add_f32_e64 v152, v232, v152
	v_add_f32_e64 v153, v233, v153
	v_exp_f32_e32 v186, v128
	v_exp_f32_e32 v187, v129
	v_exp_f32_e32 v188, v130
	v_exp_f32_e32 v189, v131
	v_cvt_pk_bf16_f32 v128, v232, v233
	v_cvt_pk_bf16_f32 v129, v234, v235
	v_cvt_pk_bf16_f32 v130, v156, v157
	v_cvt_pk_bf16_f32 v131, v158, v159
	v_pk_add_f32 v[154:155], v[158:159], v[154:155]
	v_pk_add_f32 v[152:153], v[156:157], v[152:153]
	v_mfma_f32_32x32x16_bf16 v[96:111], v[220:223], v[168:171], v[96:111]
	v_exp_f32_e32 v156, v132
	v_exp_f32_e32 v157, v133
	v_exp_f32_e32 v158, v134
	v_exp_f32_e32 v159, v135
	v_mfma_f32_32x32x16_bf16 v[112:127], v[148:151], v[172:175], v[112:127]
	v_exp_f32_e32 v216, v136
	v_exp_f32_e32 v217, v137
	v_exp_f32_e32 v218, v138
	v_exp_f32_e32 v219, v139
	v_pk_add_f32 v[138:139], v[188:189], v[154:155]
	v_pk_add_f32 v[136:137], v[186:187], v[152:153]
	v_cvt_pk_bf16_f32 v132, v186, v187
	v_cvt_pk_bf16_f32 v133, v188, v189
	v_cvt_pk_bf16_f32 v134, v156, v157
	v_cvt_pk_bf16_f32 v135, v158, v159
	v_pk_add_f32 v[150:151], v[158:159], v[138:139]
	v_pk_add_f32 v[148:149], v[156:157], v[136:137]
	v_mfma_f32_32x32x16_bf16 v[96:111], v[182:185], v[172:175], v[96:111]
	v_exp_f32_e32 v152, v140
	v_exp_f32_e32 v153, v141
	v_exp_f32_e32 v154, v142
	v_exp_f32_e32 v155, v143
	v_pk_add_f32 v[142:143], v[218:219], v[150:151]
	v_pk_add_f32 v[140:141], v[216:217], v[148:149]
	v_cvt_pk_bf16_f32 v136, v216, v217
	v_cvt_pk_bf16_f32 v137, v218, v219
	v_cvt_pk_bf16_f32 v138, v152, v153
	v_cvt_pk_bf16_f32 v139, v154, v155
	v_pk_add_f32 v[142:143], v[154:155], v[142:143]
	v_pk_add_f32 v[140:141], v[152:153], v[140:141]
	s_waitcnt vmcnt(4) lgkmcnt(0)
	v_add_f32_e32 v148, v176, v177
	v_add_f32_e32 v149, v178, v179
	v_add_f32_e32 v148, v148, v149
	v_add_f32_e32 v140, v140, v141
	v_add_f32_e32 v141, v142, v143
	s_barrier
	v_add_f32_e32 v148, v180, v148
	v_add_f32_e32 v140, v140, v141
	v_add_f32_e32 v180, v148, v140
	s_add_i32 s47, s47, 2
	s_addk_i32 s41, 0x80
	s_add_i32 s46, s46, 0x8000
	s_add_u32 s98, s98, 0x30000
	s_addc_u32 s99, s99, 0
	s_add_u32 s100, s100, 0x100
	s_addc_u32 s101, s101, 0
	s_lshl_b32 s49, s48, 14
	s_add_i32 s49, s58, s49
	s_mov_b32 m0, s49
	s_nop 0
	global_load_lds_dwordx4 v198, s[98:99]
	s_add_i32 m0, s49, 0x400
	s_nop 0
	global_load_lds_dwordx4 v194, s[98:99]
	s_add_i32 s49, s46, 0xffffc000
	s_and_b32 s49, s49, 0xc000
	s_add_i32 s49, s58, s49
	s_add_i32 m0, s49, 0xc000
	s_nop 0
	global_load_lds_dwordx4 v196, s[100:101]
	s_add_i32 m0, s49, 0xc400
	s_add_i32 s44, s48, 1
	global_load_lds_dwordx4 v192, s[100:101]
	s_cmp_lg_u32 s48, 2
	s_cselect_b32 s48, s44, 0
	s_lshl_b32 s44, s48, 14
	s_and_b32 s49, s46, 0xc000
	s_add_i32 s68, s44, 0
	s_add_i32 s44, s49, 0
	ds_read_b128 v[140:143], v236 offset:16384
	ds_read_b128 v[148:151], v236 offset:20480
	ds_read_b128 v[152:155], v236 offset:24576
	ds_read_b128 v[156:159], v236 offset:28672
	s_waitcnt lgkmcnt(0)
	v_mfma_f32_32x32x16_bf16 v[80:95], v[140:143], v[144:147], v[80:95]
	ds_read_b128 v[140:143], v237 offset:16384
	v_mfma_f32_32x32x16_bf16 v[64:79], v[148:151], v[144:147], v[64:79]
	ds_read_b128 v[148:151], v237 offset:20480
	v_mfma_f32_32x32x16_bf16 v[16:31], v[152:155], v[144:147], v[16:31]
	ds_read_b128 v[152:155], v237 offset:24576
	v_mfma_f32_32x32x16_bf16 v[0:15], v[156:159], v[144:147], v[0:15]
	ds_read_b128 v[144:147], v237 offset:28672
	s_waitcnt lgkmcnt(0)
	v_mfma_f32_32x32x16_bf16 v[80:95], v[140:143], v[128:131], v[80:95]
	ds_read_b128 v[140:143], v238 offset:16384
	v_mfma_f32_32x32x16_bf16 v[64:79], v[148:151], v[128:131], v[64:79]
	ds_read_b128 v[148:151], v238 offset:20480
	v_mfma_f32_32x32x16_bf16 v[16:31], v[152:155], v[128:131], v[16:31]
	ds_read_b128 v[152:155], v238 offset:24576
	v_mfma_f32_32x32x16_bf16 v[0:15], v[144:147], v[128:131], v[0:15]
	ds_read_b128 v[128:131], v238 offset:28672
	s_waitcnt lgkmcnt(0)
	v_mfma_f32_32x32x16_bf16 v[80:95], v[140:143], v[132:135], v[80:95]
	ds_read_b128 v[140:143], v239 offset:16384
	v_mfma_f32_32x32x16_bf16 v[64:79], v[148:151], v[132:135], v[64:79]
	ds_read_b128 v[144:147], v239 offset:20480
	v_mfma_f32_32x32x16_bf16 v[16:31], v[152:155], v[132:135], v[16:31]
	ds_read_b128 v[148:151], v239 offset:24576
	v_mfma_f32_32x32x16_bf16 v[0:15], v[128:131], v[132:135], v[0:15]
	ds_read_b128 v[128:131], v239 offset:28672
	s_waitcnt lgkmcnt(0)
	v_mfma_f32_32x32x16_bf16 v[80:95], v[140:143], v[136:139], v[80:95]
	ds_read_b128 v[132:135], v205 offset:32768
	v_mfma_f32_32x32x16_bf16 v[64:79], v[144:147], v[136:139], v[64:79]
	ds_read_b128 v[140:143], v205 offset:40960
	v_mfma_f32_32x32x16_bf16 v[16:31], v[148:151], v[136:139], v[16:31]
	ds_read_b128 v[176:179], v211 offset:32768
	v_mfma_f32_32x32x16_bf16 v[0:15], v[128:131], v[136:139], v[0:15]
	ds_read_b128 v[182:185], v211 offset:40960
	s_waitcnt lgkmcnt(0)
	v_mfma_f32_32x32x16_bf16 v[144:159], v[132:135], v[160:163], 0
	ds_read_b128 v[186:189], v212 offset:32768
	v_exp_f32_e32 v220, v112
	v_exp_f32_e32 v221, v113
	v_exp_f32_e32 v222, v114
	v_exp_f32_e32 v223, v115
	v_mfma_f32_32x32x16_bf16 v[128:143], v[140:143], v[160:163], 0
	ds_read_b128 v[216:219], v212 offset:40960
	v_exp_f32_e32 v224, v116
	v_exp_f32_e32 v225, v117
	v_exp_f32_e32 v226, v118
	v_exp_f32_e32 v227, v119
	v_mfma_f32_32x32x16_bf16 v[144:159], v[176:179], v[164:167], v[144:159]
	ds_read_b128 v[116:119], v213 offset:32768
	v_exp_f32_e32 v228, v120
	v_exp_f32_e32 v229, v121
	v_exp_f32_e32 v230, v122
	v_exp_f32_e32 v231, v123
	v_cvt_pk_bf16_f32 v112, v220, v221
	v_cvt_pk_bf16_f32 v113, v222, v223
	v_cvt_pk_bf16_f32 v114, v224, v225
	v_cvt_pk_bf16_f32 v115, v226, v227
	v_pk_add_f32 v[122:123], v[226:227], v[222:223]
	v_pk_add_f32 v[120:121], v[224:225], v[220:221]
	v_mfma_f32_32x32x16_bf16 v[128:143], v[182:185], v[164:167], v[128:143]
	ds_read_b128 v[176:179], v213 offset:40960
	v_exp_f32_e32 v124, v124
	v_exp_f32_e32 v125, v125
	v_exp_f32_e32 v126, v126
	v_exp_f32_e32 v127, v127
	s_waitcnt lgkmcnt(0)
	v_mfma_f32_32x32x16_bf16 v[144:159], v[186:189], v[168:171], v[144:159]
	v_add_f32_e64 v122, v230, v122
	v_add_f32_e64 v123, v231, v123
	v_add_f32_e64 v120, v228, v120
	v_add_f32_e64 v121, v229, v121
	v_exp_f32_e32 v182, v96
	v_exp_f32_e32 v183, v97
	v_exp_f32_e32 v184, v98
	v_exp_f32_e32 v185, v99
	v_cvt_pk_bf16_f32 v96, v228, v229
	v_cvt_pk_bf16_f32 v97, v230, v231
	v_cvt_pk_bf16_f32 v98, v124, v125
	v_cvt_pk_bf16_f32 v99, v126, v127
	v_pk_add_f32 v[122:123], v[126:127], v[122:123]
	v_pk_add_f32 v[120:121], v[124:125], v[120:121]
	v_mfma_f32_32x32x16_bf16 v[128:143], v[216:219], v[168:171], v[128:143]
	v_exp_f32_e32 v124, v100
	v_exp_f32_e32 v125, v101
	v_exp_f32_e32 v126, v102
	v_exp_f32_e32 v127, v103
	v_mfma_f32_32x32x16_bf16 v[144:159], v[116:119], v[172:175], v[144:159]
	v_exp_f32_e32 v186, v104
	v_exp_f32_e32 v187, v105
	v_exp_f32_e32 v188, v106
	v_exp_f32_e32 v189, v107
	v_pk_add_f32 v[106:107], v[184:185], v[122:123]
	v_pk_add_f32 v[104:105], v[182:183], v[120:121]
	v_cvt_pk_bf16_f32 v100, v182, v183
	v_cvt_pk_bf16_f32 v101, v184, v185
	v_cvt_pk_bf16_f32 v102, v124, v125
	v_cvt_pk_bf16_f32 v103, v126, v127
	v_pk_add_f32 v[118:119], v[126:127], v[106:107]
	v_pk_add_f32 v[116:117], v[124:125], v[104:105]
	v_mfma_f32_32x32x16_bf16 v[128:143], v[176:179], v[172:175], v[128:143]
	v_exp_f32_e32 v120, v108
	v_exp_f32_e32 v121, v109
	v_exp_f32_e32 v122, v110
	v_exp_f32_e32 v123, v111
	v_pk_add_f32 v[110:111], v[188:189], v[118:119]
	v_pk_add_f32 v[108:109], v[186:187], v[116:117]
	v_cvt_pk_bf16_f32 v104, v186, v187
	v_cvt_pk_bf16_f32 v105, v188, v189
	v_cvt_pk_bf16_f32 v106, v120, v121
	v_cvt_pk_bf16_f32 v107, v122, v123
	v_pk_add_f32 v[178:179], v[122:123], v[110:111]
	v_pk_add_f32 v[176:177], v[120:121], v[108:109]
	s_waitcnt vmcnt(4) lgkmcnt(0)
	s_barrier
	s_add_u32 s70, s98, 0x18000
	s_addc_u32 s71, s99, 0
	s_add_i32 s68, s68, s57
	s_mov_b32 m0, s68
	s_nop 0
	global_load_lds_dwordx4 v198, s[70:71]
	s_add_i32 m0, s68, 0x400
	s_nop 0
	global_load_lds_dwordx4 v194, s[70:71]
	s_add_u32 s2, s100, 0x80
	s_addc_u32 s3, s101, 0
	s_add_i32 s49, s58, s49
	s_add_i32 m0, s49, 0xc000
	s_nop 0
	global_load_lds_dwordx4 v196, s[2:3]
	s_add_i32 m0, s49, 0xc400
	s_nop 0
	global_load_lds_dwordx4 v192, s[2:3]
	s_add_i32 s2, s46, 0xffff4000
	s_add_i32 s3, s48, 1
	s_cmp_lg_u32 s48, 2
	s_cselect_b32 s48, s3, 0
	s_and_b32 s2, s2, 0xc000
	s_add_i32 s2, s2, 0
	s_lshl_b32 s3, s48, 14
	ds_read_b128 v[108:111], v236 offset:32768
	ds_read_b128 v[116:119], v236 offset:36864
	ds_read_b128 v[120:123], v236 offset:40960
	ds_read_b128 v[124:127], v236 offset:45056
	s_waitcnt lgkmcnt(0)
	v_mfma_f32_32x32x16_bf16 v[80:95], v[108:111], v[112:115], v[80:95]
	ds_read_b128 v[108:111], v237 offset:32768
	s_add_i32 s3, s3, 0
	v_mfma_f32_32x32x16_bf16 v[64:79], v[116:119], v[112:115], v[64:79]
	ds_read_b128 v[116:119], v237 offset:36864
	v_mfma_f32_32x32x16_bf16 v[16:31], v[120:123], v[112:115], v[16:31]
	ds_read_b128 v[120:123], v237 offset:40960
	v_mfma_f32_32x32x16_bf16 v[0:15], v[124:127], v[112:115], v[0:15]
	ds_read_b128 v[112:115], v237 offset:45056
	s_waitcnt lgkmcnt(0)
	v_mfma_f32_32x32x16_bf16 v[80:95], v[108:111], v[96:99], v[80:95]
	ds_read_b128 v[108:111], v238 offset:32768
	v_mfma_f32_32x32x16_bf16 v[64:79], v[116:119], v[96:99], v[64:79]
	ds_read_b128 v[116:119], v238 offset:36864
	v_mfma_f32_32x32x16_bf16 v[16:31], v[120:123], v[96:99], v[16:31]
	ds_read_b128 v[120:123], v238 offset:40960
	v_mfma_f32_32x32x16_bf16 v[0:15], v[112:115], v[96:99], v[0:15]
	ds_read_b128 v[96:99], v238 offset:45056
	s_waitcnt lgkmcnt(0)
	v_mfma_f32_32x32x16_bf16 v[80:95], v[108:111], v[100:103], v[80:95]
	ds_read_b128 v[108:111], v239 offset:32768
	v_mfma_f32_32x32x16_bf16 v[64:79], v[116:119], v[100:103], v[64:79]
	ds_read_b128 v[112:115], v239 offset:36864
	v_mfma_f32_32x32x16_bf16 v[16:31], v[120:123], v[100:103], v[16:31]
	ds_read_b128 v[116:119], v239 offset:40960
	v_mfma_f32_32x32x16_bf16 v[0:15], v[96:99], v[100:103], v[0:15]
	ds_read_b128 v[120:123], v239 offset:45056
	s_waitcnt lgkmcnt(0)
	v_mfma_f32_32x32x16_bf16 v[80:95], v[108:111], v[104:107], v[80:95]
	ds_read_b128 v[96:99], v205
	v_mfma_f32_32x32x16_bf16 v[64:79], v[112:115], v[104:107], v[64:79]
	ds_read_b128 v[100:103], v205 offset:8192
	v_mfma_f32_32x32x16_bf16 v[16:31], v[116:119], v[104:107], v[16:31]
	ds_read_b128 v[182:185], v211
	v_mfma_f32_32x32x16_bf16 v[0:15], v[120:123], v[104:107], v[0:15]
	ds_read_b128 v[186:189], v211 offset:8192
	s_waitcnt lgkmcnt(0)
	v_mfma_f32_32x32x16_bf16 v[112:127], v[96:99], v[160:163], 0
	ds_read_b128 v[216:219], v212
	v_exp_f32_e32 v224, v144
	v_exp_f32_e32 v225, v145
	v_exp_f32_e32 v226, v146
	v_exp_f32_e32 v227, v147
	ds_read_b128 v[220:223], v212 offset:8192
	v_mfma_f32_32x32x16_bf16 v[96:111], v[100:103], v[160:163], 0
	v_exp_f32_e32 v228, v148
	v_exp_f32_e32 v229, v149
	v_exp_f32_e32 v230, v150
	v_exp_f32_e32 v231, v151
	v_mfma_f32_32x32x16_bf16 v[112:127], v[182:185], v[164:167], v[112:127]
	ds_read_b128 v[148:151], v213
	v_exp_f32_e32 v232, v152
	v_exp_f32_e32 v233, v153
	v_exp_f32_e32 v234, v154
	v_exp_f32_e32 v235, v155
	v_cvt_pk_bf16_f32 v144, v224, v225
	v_cvt_pk_bf16_f32 v145, v226, v227
	v_cvt_pk_bf16_f32 v146, v228, v229
	v_cvt_pk_bf16_f32 v147, v230, v231
	v_pk_add_f32 v[154:155], v[230:231], v[226:227]
	v_pk_add_f32 v[152:153], v[228:229], v[224:225]
	v_mfma_f32_32x32x16_bf16 v[96:111], v[186:189], v[164:167], v[96:111]
	ds_read_b128 v[182:185], v213 offset:8192
	v_exp_f32_e32 v156, v156
	v_exp_f32_e32 v157, v157
	v_exp_f32_e32 v158, v158
	v_exp_f32_e32 v159, v159
	s_waitcnt lgkmcnt(0)
	v_mfma_f32_32x32x16_bf16 v[112:127], v[216:219], v[168:171], v[112:127]
	v_add_f32_e64 v154, v234, v154
	v_add_f32_e64 v155, v235, v155
	v_add_f32_e64 v152, v232, v152
	v_add_f32_e64 v153, v233, v153
	v_exp_f32_e32 v186, v128
	v_exp_f32_e32 v187, v129
	v_exp_f32_e32 v188, v130
	v_exp_f32_e32 v189, v131
	v_cvt_pk_bf16_f32 v128, v232, v233
	v_cvt_pk_bf16_f32 v129, v234, v235
	v_cvt_pk_bf16_f32 v130, v156, v157
	v_cvt_pk_bf16_f32 v131, v158, v159
	v_pk_add_f32 v[154:155], v[158:159], v[154:155]
	v_pk_add_f32 v[152:153], v[156:157], v[152:153]
	v_mfma_f32_32x32x16_bf16 v[96:111], v[220:223], v[168:171], v[96:111]
	v_exp_f32_e32 v156, v132
	v_exp_f32_e32 v157, v133
	v_exp_f32_e32 v158, v134
	v_exp_f32_e32 v159, v135
	v_mfma_f32_32x32x16_bf16 v[112:127], v[148:151], v[172:175], v[112:127]
	v_exp_f32_e32 v216, v136
	v_exp_f32_e32 v217, v137
	v_exp_f32_e32 v218, v138
	v_exp_f32_e32 v219, v139
	v_pk_add_f32 v[138:139], v[188:189], v[154:155]
	v_pk_add_f32 v[136:137], v[186:187], v[152:153]
	v_cvt_pk_bf16_f32 v132, v186, v187
	v_cvt_pk_bf16_f32 v133, v188, v189
	v_cvt_pk_bf16_f32 v134, v156, v157
	v_cvt_pk_bf16_f32 v135, v158, v159
	v_pk_add_f32 v[150:151], v[158:159], v[138:139]
	v_pk_add_f32 v[148:149], v[156:157], v[136:137]
	v_mfma_f32_32x32x16_bf16 v[96:111], v[182:185], v[172:175], v[96:111]
	v_exp_f32_e32 v152, v140
	v_exp_f32_e32 v153, v141
	v_exp_f32_e32 v154, v142
	v_exp_f32_e32 v155, v143
	v_pk_add_f32 v[142:143], v[218:219], v[150:151]
	v_pk_add_f32 v[140:141], v[216:217], v[148:149]
	v_cvt_pk_bf16_f32 v136, v216, v217
	v_cvt_pk_bf16_f32 v137, v218, v219
	v_cvt_pk_bf16_f32 v138, v152, v153
	v_cvt_pk_bf16_f32 v139, v154, v155
	v_pk_add_f32 v[142:143], v[154:155], v[142:143]
	v_pk_add_f32 v[140:141], v[152:153], v[140:141]
	s_waitcnt vmcnt(4) lgkmcnt(0)
	v_add_f32_e32 v148, v176, v177
	v_add_f32_e32 v149, v178, v179
	v_add_f32_e32 v148, v148, v149
	v_add_f32_e32 v140, v140, v141
	v_add_f32_e32 v141, v142, v143
	s_barrier
	v_add_f32_e32 v148, v180, v148
	v_add_f32_e32 v140, v140, v141
	v_add_f32_e32 v180, v148, v140
	s_add_i32 s47, s47, 2
	s_addk_i32 s41, 0x80
	s_add_i32 s46, s46, 0x8000
	s_add_u32 s98, s98, 0x30000
	s_addc_u32 s99, s99, 0
	s_add_u32 s100, s100, 0x100
	s_addc_u32 s101, s101, 0
	s_lshl_b32 s49, s48, 14
	s_add_i32 s49, s58, s49
	s_mov_b32 m0, s49
	s_nop 0
	global_load_lds_dwordx4 v198, s[98:99]
	s_add_i32 m0, s49, 0x400
	s_nop 0
	global_load_lds_dwordx4 v194, s[98:99]
	s_add_i32 s49, s46, 0xffffc000
	s_and_b32 s49, s49, 0xc000
	s_add_i32 s49, s58, s49
	s_add_i32 m0, s49, 0xc000
	s_nop 0
	global_load_lds_dwordx4 v196, s[100:101]
	s_add_i32 m0, s49, 0xc400
	s_add_i32 s44, s48, 1
	global_load_lds_dwordx4 v192, s[100:101]
	s_cmp_lg_u32 s48, 2
	s_cselect_b32 s48, s44, 0
	s_lshl_b32 s44, s48, 14
	s_and_b32 s49, s46, 0xc000
	s_add_i32 s68, s44, 0
	s_add_i32 s44, s49, 0
	ds_read_b128 v[140:143], v206 offset:49152
	ds_read_b128 v[148:151], v206 offset:53248
	ds_read_b128 v[152:155], v206 offset:57344
	ds_read_b128 v[156:159], v206 offset:61440
	s_waitcnt lgkmcnt(0)
	v_mfma_f32_32x32x16_bf16 v[80:95], v[140:143], v[144:147], v[80:95]
	ds_read_b128 v[140:143], v207 offset:49152
	v_mfma_f32_32x32x16_bf16 v[64:79], v[148:151], v[144:147], v[64:79]
	ds_read_b128 v[148:151], v207 offset:53248
	v_mfma_f32_32x32x16_bf16 v[16:31], v[152:155], v[144:147], v[16:31]
	ds_read_b128 v[152:155], v207 offset:57344
	v_mfma_f32_32x32x16_bf16 v[0:15], v[156:159], v[144:147], v[0:15]
	ds_read_b128 v[144:147], v207 offset:61440
	s_waitcnt lgkmcnt(0)
	v_mfma_f32_32x32x16_bf16 v[80:95], v[140:143], v[128:131], v[80:95]
	ds_read_b128 v[140:143], v208 offset:49152
	v_mfma_f32_32x32x16_bf16 v[64:79], v[148:151], v[128:131], v[64:79]
	ds_read_b128 v[148:151], v208 offset:53248
	v_mfma_f32_32x32x16_bf16 v[16:31], v[152:155], v[128:131], v[16:31]
	ds_read_b128 v[152:155], v208 offset:57344
	v_mfma_f32_32x32x16_bf16 v[0:15], v[144:147], v[128:131], v[0:15]
	ds_read_b128 v[128:131], v208 offset:61440
	s_waitcnt lgkmcnt(0)
	v_mfma_f32_32x32x16_bf16 v[80:95], v[140:143], v[132:135], v[80:95]
	ds_read_b128 v[140:143], v209 offset:49152
	v_mfma_f32_32x32x16_bf16 v[64:79], v[148:151], v[132:135], v[64:79]
	ds_read_b128 v[144:147], v209 offset:53248
	v_mfma_f32_32x32x16_bf16 v[16:31], v[152:155], v[132:135], v[16:31]
	ds_read_b128 v[148:151], v209 offset:57344
	v_mfma_f32_32x32x16_bf16 v[0:15], v[128:131], v[132:135], v[0:15]
	ds_read_b128 v[128:131], v209 offset:61440
	s_waitcnt lgkmcnt(0)
	v_mfma_f32_32x32x16_bf16 v[80:95], v[140:143], v[136:139], v[80:95]
	ds_read_b128 v[132:135], v205 offset:16384
	v_mfma_f32_32x32x16_bf16 v[64:79], v[144:147], v[136:139], v[64:79]
	ds_read_b128 v[140:143], v205 offset:24576
	v_mfma_f32_32x32x16_bf16 v[16:31], v[148:151], v[136:139], v[16:31]
	ds_read_b128 v[176:179], v211 offset:16384
	v_mfma_f32_32x32x16_bf16 v[0:15], v[128:131], v[136:139], v[0:15]
	ds_read_b128 v[182:185], v211 offset:24576
	s_waitcnt lgkmcnt(0)
	v_mfma_f32_32x32x16_bf16 v[144:159], v[132:135], v[160:163], 0
	ds_read_b128 v[186:189], v212 offset:16384
	v_exp_f32_e32 v220, v112
	v_exp_f32_e32 v221, v113
	v_exp_f32_e32 v222, v114
	v_exp_f32_e32 v223, v115
	v_mfma_f32_32x32x16_bf16 v[128:143], v[140:143], v[160:163], 0
	ds_read_b128 v[216:219], v212 offset:24576
	v_exp_f32_e32 v224, v116
	v_exp_f32_e32 v225, v117
	v_exp_f32_e32 v226, v118
	v_exp_f32_e32 v227, v119
	v_mfma_f32_32x32x16_bf16 v[144:159], v[176:179], v[164:167], v[144:159]
	ds_read_b128 v[116:119], v213 offset:16384
	v_exp_f32_e32 v228, v120
	v_exp_f32_e32 v229, v121
	v_exp_f32_e32 v230, v122
	v_exp_f32_e32 v231, v123
	v_cvt_pk_bf16_f32 v112, v220, v221
	v_cvt_pk_bf16_f32 v113, v222, v223
	v_cvt_pk_bf16_f32 v114, v224, v225
	v_cvt_pk_bf16_f32 v115, v226, v227
	v_pk_add_f32 v[122:123], v[226:227], v[222:223]
	v_pk_add_f32 v[120:121], v[224:225], v[220:221]
	v_mfma_f32_32x32x16_bf16 v[128:143], v[182:185], v[164:167], v[128:143]
	ds_read_b128 v[176:179], v213 offset:24576
	v_exp_f32_e32 v124, v124
	v_exp_f32_e32 v125, v125
	v_exp_f32_e32 v126, v126
	v_exp_f32_e32 v127, v127
	s_waitcnt lgkmcnt(0)
	v_mfma_f32_32x32x16_bf16 v[144:159], v[186:189], v[168:171], v[144:159]
	v_add_f32_e64 v122, v230, v122
	v_add_f32_e64 v123, v231, v123
	v_add_f32_e64 v120, v228, v120
	v_add_f32_e64 v121, v229, v121
	v_exp_f32_e32 v182, v96
	v_exp_f32_e32 v183, v97
	v_exp_f32_e32 v184, v98
	v_exp_f32_e32 v185, v99
	v_cvt_pk_bf16_f32 v96, v228, v229
	v_cvt_pk_bf16_f32 v97, v230, v231
	v_cvt_pk_bf16_f32 v98, v124, v125
	v_cvt_pk_bf16_f32 v99, v126, v127
	v_pk_add_f32 v[122:123], v[126:127], v[122:123]
	v_pk_add_f32 v[120:121], v[124:125], v[120:121]
	v_mfma_f32_32x32x16_bf16 v[128:143], v[216:219], v[168:171], v[128:143]
	v_exp_f32_e32 v124, v100
	v_exp_f32_e32 v125, v101
	v_exp_f32_e32 v126, v102
	v_exp_f32_e32 v127, v103
	v_mfma_f32_32x32x16_bf16 v[144:159], v[116:119], v[172:175], v[144:159]
	v_exp_f32_e32 v186, v104
	v_exp_f32_e32 v187, v105
	v_exp_f32_e32 v188, v106
	v_exp_f32_e32 v189, v107
	v_pk_add_f32 v[106:107], v[184:185], v[122:123]
	v_pk_add_f32 v[104:105], v[182:183], v[120:121]
	v_cvt_pk_bf16_f32 v100, v182, v183
	v_cvt_pk_bf16_f32 v101, v184, v185
	v_cvt_pk_bf16_f32 v102, v124, v125
	v_cvt_pk_bf16_f32 v103, v126, v127
	v_pk_add_f32 v[118:119], v[126:127], v[106:107]
	v_pk_add_f32 v[116:117], v[124:125], v[104:105]
	v_mfma_f32_32x32x16_bf16 v[128:143], v[176:179], v[172:175], v[128:143]
	v_exp_f32_e32 v120, v108
	v_exp_f32_e32 v121, v109
	v_exp_f32_e32 v122, v110
	v_exp_f32_e32 v123, v111
	v_pk_add_f32 v[110:111], v[188:189], v[118:119]
	v_pk_add_f32 v[108:109], v[186:187], v[116:117]
	v_cvt_pk_bf16_f32 v104, v186, v187
	v_cvt_pk_bf16_f32 v105, v188, v189
	v_cvt_pk_bf16_f32 v106, v120, v121
	v_cvt_pk_bf16_f32 v107, v122, v123
	v_pk_add_f32 v[178:179], v[122:123], v[110:111]
	v_pk_add_f32 v[176:177], v[120:121], v[108:109]
	s_waitcnt vmcnt(4) lgkmcnt(0)
	s_barrier
	s_add_u32 s70, s98, 0x18000
	s_addc_u32 s71, s99, 0
	s_add_i32 s68, s68, s57
	s_mov_b32 m0, s68
	s_nop 0
	global_load_lds_dwordx4 v198, s[70:71]
	s_add_i32 m0, s68, 0x400
	s_nop 0
	global_load_lds_dwordx4 v194, s[70:71]
	s_add_u32 s2, s100, 0x80
	s_addc_u32 s3, s101, 0
	s_add_i32 s49, s58, s49
	s_add_i32 m0, s49, 0xc000
	s_nop 0
	global_load_lds_dwordx4 v196, s[2:3]
	s_add_i32 m0, s49, 0xc400
	s_nop 0
	global_load_lds_dwordx4 v192, s[2:3]
	s_add_i32 s2, s46, 0xffff4000
	s_add_i32 s3, s48, 1
	s_cmp_lg_u32 s48, 2
	s_cselect_b32 s48, s3, 0
	s_and_b32 s2, s2, 0xc000
	s_add_i32 s2, s2, 0
	s_lshl_b32 s3, s48, 14
	ds_read_b128 v[108:111], v236
	ds_read_b128 v[116:119], v236 offset:4096
	ds_read_b128 v[120:123], v236 offset:8192
	ds_read_b128 v[124:127], v236 offset:12288
	s_waitcnt lgkmcnt(0)
	v_mfma_f32_32x32x16_bf16 v[80:95], v[108:111], v[112:115], v[80:95]
	ds_read_b128 v[108:111], v237
	s_add_i32 s3, s3, 0
	v_mfma_f32_32x32x16_bf16 v[64:79], v[116:119], v[112:115], v[64:79]
	ds_read_b128 v[116:119], v237 offset:4096
	v_mfma_f32_32x32x16_bf16 v[16:31], v[120:123], v[112:115], v[16:31]
	ds_read_b128 v[120:123], v237 offset:8192
	v_mfma_f32_32x32x16_bf16 v[0:15], v[124:127], v[112:115], v[0:15]
	ds_read_b128 v[112:115], v237 offset:12288
	s_waitcnt lgkmcnt(0)
	v_mfma_f32_32x32x16_bf16 v[80:95], v[108:111], v[96:99], v[80:95]
	ds_read_b128 v[108:111], v238
	v_mfma_f32_32x32x16_bf16 v[64:79], v[116:119], v[96:99], v[64:79]
	ds_read_b128 v[116:119], v238 offset:4096
	v_mfma_f32_32x32x16_bf16 v[16:31], v[120:123], v[96:99], v[16:31]
	ds_read_b128 v[120:123], v238 offset:8192
	v_mfma_f32_32x32x16_bf16 v[0:15], v[112:115], v[96:99], v[0:15]
	ds_read_b128 v[96:99], v238 offset:12288
	s_waitcnt lgkmcnt(0)
	v_mfma_f32_32x32x16_bf16 v[80:95], v[108:111], v[100:103], v[80:95]
	ds_read_b128 v[108:111], v239
	v_mfma_f32_32x32x16_bf16 v[64:79], v[116:119], v[100:103], v[64:79]
	ds_read_b128 v[112:115], v239 offset:4096
	v_mfma_f32_32x32x16_bf16 v[16:31], v[120:123], v[100:103], v[16:31]
	ds_read_b128 v[116:119], v239 offset:8192
	v_mfma_f32_32x32x16_bf16 v[0:15], v[96:99], v[100:103], v[0:15]
	ds_read_b128 v[120:123], v239 offset:12288
	s_waitcnt lgkmcnt(0)
	v_mfma_f32_32x32x16_bf16 v[80:95], v[108:111], v[104:107], v[80:95]
	ds_read_b128 v[96:99], v205 offset:32768
	v_mfma_f32_32x32x16_bf16 v[64:79], v[112:115], v[104:107], v[64:79]
	ds_read_b128 v[100:103], v205 offset:40960
	v_mfma_f32_32x32x16_bf16 v[16:31], v[116:119], v[104:107], v[16:31]
	ds_read_b128 v[182:185], v211 offset:32768
	v_mfma_f32_32x32x16_bf16 v[0:15], v[120:123], v[104:107], v[0:15]
	ds_read_b128 v[186:189], v211 offset:40960
	s_waitcnt lgkmcnt(0)
	v_mfma_f32_32x32x16_bf16 v[112:127], v[96:99], v[160:163], 0
	ds_read_b128 v[216:219], v212 offset:32768
	v_exp_f32_e32 v224, v144
	v_exp_f32_e32 v225, v145
	v_exp_f32_e32 v226, v146
	v_exp_f32_e32 v227, v147
	ds_read_b128 v[220:223], v212 offset:40960
	v_mfma_f32_32x32x16_bf16 v[96:111], v[100:103], v[160:163], 0
	v_exp_f32_e32 v228, v148
	v_exp_f32_e32 v229, v149
	v_exp_f32_e32 v230, v150
	v_exp_f32_e32 v231, v151
	v_mfma_f32_32x32x16_bf16 v[112:127], v[182:185], v[164:167], v[112:127]
	ds_read_b128 v[148:151], v213 offset:32768
	v_exp_f32_e32 v232, v152
	v_exp_f32_e32 v233, v153
	v_exp_f32_e32 v234, v154
	v_exp_f32_e32 v235, v155
	v_cvt_pk_bf16_f32 v144, v224, v225
	v_cvt_pk_bf16_f32 v145, v226, v227
	v_cvt_pk_bf16_f32 v146, v228, v229
	v_cvt_pk_bf16_f32 v147, v230, v231
	v_pk_add_f32 v[154:155], v[230:231], v[226:227]
	v_pk_add_f32 v[152:153], v[228:229], v[224:225]
	v_mfma_f32_32x32x16_bf16 v[96:111], v[186:189], v[164:167], v[96:111]
	ds_read_b128 v[182:185], v213 offset:40960
	v_exp_f32_e32 v156, v156
	v_exp_f32_e32 v157, v157
	v_exp_f32_e32 v158, v158
	v_exp_f32_e32 v159, v159
	s_waitcnt lgkmcnt(0)
	v_mfma_f32_32x32x16_bf16 v[112:127], v[216:219], v[168:171], v[112:127]
	v_add_f32_e64 v154, v234, v154
	v_add_f32_e64 v155, v235, v155
	v_add_f32_e64 v152, v232, v152
	v_add_f32_e64 v153, v233, v153
	v_exp_f32_e32 v186, v128
	v_exp_f32_e32 v187, v129
	v_exp_f32_e32 v188, v130
	v_exp_f32_e32 v189, v131
	v_cvt_pk_bf16_f32 v128, v232, v233
	v_cvt_pk_bf16_f32 v129, v234, v235
	v_cvt_pk_bf16_f32 v130, v156, v157
	v_cvt_pk_bf16_f32 v131, v158, v159
	v_pk_add_f32 v[154:155], v[158:159], v[154:155]
	v_pk_add_f32 v[152:153], v[156:157], v[152:153]
	v_mfma_f32_32x32x16_bf16 v[96:111], v[220:223], v[168:171], v[96:111]
	v_exp_f32_e32 v156, v132
	v_exp_f32_e32 v157, v133
	v_exp_f32_e32 v158, v134
	v_exp_f32_e32 v159, v135
	v_mfma_f32_32x32x16_bf16 v[112:127], v[148:151], v[172:175], v[112:127]
	v_exp_f32_e32 v216, v136
	v_exp_f32_e32 v217, v137
	v_exp_f32_e32 v218, v138
	v_exp_f32_e32 v219, v139
	v_pk_add_f32 v[138:139], v[188:189], v[154:155]
	v_pk_add_f32 v[136:137], v[186:187], v[152:153]
	v_cvt_pk_bf16_f32 v132, v186, v187
	v_cvt_pk_bf16_f32 v133, v188, v189
	v_cvt_pk_bf16_f32 v134, v156, v157
	v_cvt_pk_bf16_f32 v135, v158, v159
	v_pk_add_f32 v[150:151], v[158:159], v[138:139]
	v_pk_add_f32 v[148:149], v[156:157], v[136:137]
	v_mfma_f32_32x32x16_bf16 v[96:111], v[182:185], v[172:175], v[96:111]
	v_exp_f32_e32 v152, v140
	v_exp_f32_e32 v153, v141
	v_exp_f32_e32 v154, v142
	v_exp_f32_e32 v155, v143
	v_pk_add_f32 v[142:143], v[218:219], v[150:151]
	v_pk_add_f32 v[140:141], v[216:217], v[148:149]
	v_cvt_pk_bf16_f32 v136, v216, v217
	v_cvt_pk_bf16_f32 v137, v218, v219
	v_cvt_pk_bf16_f32 v138, v152, v153
	v_cvt_pk_bf16_f32 v139, v154, v155
	v_pk_add_f32 v[142:143], v[154:155], v[142:143]
	v_pk_add_f32 v[140:141], v[152:153], v[140:141]
	s_waitcnt vmcnt(4) lgkmcnt(0)
	v_add_f32_e32 v148, v176, v177
	v_add_f32_e32 v149, v178, v179
	v_add_f32_e32 v148, v148, v149
	v_add_f32_e32 v140, v140, v141
	v_add_f32_e32 v141, v142, v143
	s_barrier
	v_add_f32_e32 v148, v180, v148
	v_add_f32_e32 v140, v140, v141
	v_add_f32_e32 v180, v148, v140
	s_add_i32 s47, s47, 2
	s_addk_i32 s41, 0x80
	s_add_i32 s46, s46, 0x8000
	s_add_u32 s98, s98, 0x30000
	s_addc_u32 s99, s99, 0
	s_add_u32 s100, s100, 0x100
	s_addc_u32 s101, s101, 0
	s_lshl_b32 s49, s48, 14
	s_add_i32 s49, s58, s49
	s_mov_b32 m0, s49
	s_nop 0
	global_load_lds_dwordx4 v198, s[98:99]
	s_add_i32 m0, s49, 0x400
	s_nop 0
	global_load_lds_dwordx4 v194, s[98:99]
	s_add_i32 s49, s46, 0xffffc000
	s_and_b32 s49, s49, 0xc000
	s_add_i32 s49, s58, s49
	s_add_i32 m0, s49, 0xc000
	s_nop 0
	global_load_lds_dwordx4 v196, s[100:101]
	s_add_i32 m0, s49, 0xc400
	s_add_i32 s44, s48, 1
	global_load_lds_dwordx4 v192, s[100:101]
	s_cmp_lg_u32 s48, 2
	s_cselect_b32 s48, s44, 0
	s_lshl_b32 s44, s48, 14
	s_and_b32 s49, s46, 0xc000
	s_add_i32 s68, s44, 0
	s_add_i32 s44, s49, 0
	ds_read_b128 v[140:143], v236 offset:16384
	ds_read_b128 v[148:151], v236 offset:20480
	ds_read_b128 v[152:155], v236 offset:24576
	ds_read_b128 v[156:159], v236 offset:28672
	s_waitcnt lgkmcnt(0)
	v_mfma_f32_32x32x16_bf16 v[80:95], v[140:143], v[144:147], v[80:95]
	ds_read_b128 v[140:143], v237 offset:16384
	v_mfma_f32_32x32x16_bf16 v[64:79], v[148:151], v[144:147], v[64:79]
	ds_read_b128 v[148:151], v237 offset:20480
	v_mfma_f32_32x32x16_bf16 v[16:31], v[152:155], v[144:147], v[16:31]
	ds_read_b128 v[152:155], v237 offset:24576
	v_mfma_f32_32x32x16_bf16 v[0:15], v[156:159], v[144:147], v[0:15]
	ds_read_b128 v[144:147], v237 offset:28672
	s_waitcnt lgkmcnt(0)
	v_mfma_f32_32x32x16_bf16 v[80:95], v[140:143], v[128:131], v[80:95]
	ds_read_b128 v[140:143], v238 offset:16384
	v_mfma_f32_32x32x16_bf16 v[64:79], v[148:151], v[128:131], v[64:79]
	ds_read_b128 v[148:151], v238 offset:20480
	v_mfma_f32_32x32x16_bf16 v[16:31], v[152:155], v[128:131], v[16:31]
	ds_read_b128 v[152:155], v238 offset:24576
	v_mfma_f32_32x32x16_bf16 v[0:15], v[144:147], v[128:131], v[0:15]
	ds_read_b128 v[128:131], v238 offset:28672
	s_waitcnt lgkmcnt(0)
	v_mfma_f32_32x32x16_bf16 v[80:95], v[140:143], v[132:135], v[80:95]
	ds_read_b128 v[140:143], v239 offset:16384
	v_mfma_f32_32x32x16_bf16 v[64:79], v[148:151], v[132:135], v[64:79]
	ds_read_b128 v[144:147], v239 offset:20480
	v_mfma_f32_32x32x16_bf16 v[16:31], v[152:155], v[132:135], v[16:31]
	ds_read_b128 v[148:151], v239 offset:24576
	v_mfma_f32_32x32x16_bf16 v[0:15], v[128:131], v[132:135], v[0:15]
	ds_read_b128 v[128:131], v239 offset:28672
	s_waitcnt lgkmcnt(0)
	v_mfma_f32_32x32x16_bf16 v[80:95], v[140:143], v[136:139], v[80:95]
	ds_read_b128 v[132:135], v205
	v_mfma_f32_32x32x16_bf16 v[64:79], v[144:147], v[136:139], v[64:79]
	ds_read_b128 v[140:143], v205 offset:8192
	v_mfma_f32_32x32x16_bf16 v[16:31], v[148:151], v[136:139], v[16:31]
	ds_read_b128 v[176:179], v211
	v_mfma_f32_32x32x16_bf16 v[0:15], v[128:131], v[136:139], v[0:15]
	ds_read_b128 v[182:185], v211 offset:8192
	s_waitcnt lgkmcnt(0)
	v_mfma_f32_32x32x16_bf16 v[144:159], v[132:135], v[160:163], 0
	ds_read_b128 v[186:189], v212
	v_exp_f32_e32 v220, v112
	v_exp_f32_e32 v221, v113
	v_exp_f32_e32 v222, v114
	v_exp_f32_e32 v223, v115
	v_mfma_f32_32x32x16_bf16 v[128:143], v[140:143], v[160:163], 0
	ds_read_b128 v[216:219], v212 offset:8192
	v_exp_f32_e32 v224, v116
	v_exp_f32_e32 v225, v117
	v_exp_f32_e32 v226, v118
	v_exp_f32_e32 v227, v119
	v_mfma_f32_32x32x16_bf16 v[144:159], v[176:179], v[164:167], v[144:159]
	ds_read_b128 v[116:119], v213
	v_exp_f32_e32 v228, v120
	v_exp_f32_e32 v229, v121
	v_exp_f32_e32 v230, v122
	v_exp_f32_e32 v231, v123
	v_cvt_pk_bf16_f32 v112, v220, v221
	v_cvt_pk_bf16_f32 v113, v222, v223
	v_cvt_pk_bf16_f32 v114, v224, v225
	v_cvt_pk_bf16_f32 v115, v226, v227
	v_pk_add_f32 v[122:123], v[226:227], v[222:223]
	v_pk_add_f32 v[120:121], v[224:225], v[220:221]
	v_mfma_f32_32x32x16_bf16 v[128:143], v[182:185], v[164:167], v[128:143]
	ds_read_b128 v[176:179], v213 offset:8192
	v_exp_f32_e32 v124, v124
	v_exp_f32_e32 v125, v125
	v_exp_f32_e32 v126, v126
	v_exp_f32_e32 v127, v127
	s_waitcnt lgkmcnt(0)
	v_mfma_f32_32x32x16_bf16 v[144:159], v[186:189], v[168:171], v[144:159]
	v_add_f32_e64 v122, v230, v122
	v_add_f32_e64 v123, v231, v123
	v_add_f32_e64 v120, v228, v120
	v_add_f32_e64 v121, v229, v121
	v_exp_f32_e32 v182, v96
	v_exp_f32_e32 v183, v97
	v_exp_f32_e32 v184, v98
	v_exp_f32_e32 v185, v99
	v_cvt_pk_bf16_f32 v96, v228, v229
	v_cvt_pk_bf16_f32 v97, v230, v231
	v_cvt_pk_bf16_f32 v98, v124, v125
	v_cvt_pk_bf16_f32 v99, v126, v127
	v_pk_add_f32 v[122:123], v[126:127], v[122:123]
	v_pk_add_f32 v[120:121], v[124:125], v[120:121]
	v_mfma_f32_32x32x16_bf16 v[128:143], v[216:219], v[168:171], v[128:143]
	v_exp_f32_e32 v124, v100
	v_exp_f32_e32 v125, v101
	v_exp_f32_e32 v126, v102
	v_exp_f32_e32 v127, v103
	v_mfma_f32_32x32x16_bf16 v[144:159], v[116:119], v[172:175], v[144:159]
	v_exp_f32_e32 v186, v104
	v_exp_f32_e32 v187, v105
	v_exp_f32_e32 v188, v106
	v_exp_f32_e32 v189, v107
	v_pk_add_f32 v[106:107], v[184:185], v[122:123]
	v_pk_add_f32 v[104:105], v[182:183], v[120:121]
	v_cvt_pk_bf16_f32 v100, v182, v183
	v_cvt_pk_bf16_f32 v101, v184, v185
	v_cvt_pk_bf16_f32 v102, v124, v125
	v_cvt_pk_bf16_f32 v103, v126, v127
	v_pk_add_f32 v[118:119], v[126:127], v[106:107]
	v_pk_add_f32 v[116:117], v[124:125], v[104:105]
	v_mfma_f32_32x32x16_bf16 v[128:143], v[176:179], v[172:175], v[128:143]
	v_exp_f32_e32 v120, v108
	v_exp_f32_e32 v121, v109
	v_exp_f32_e32 v122, v110
	v_exp_f32_e32 v123, v111
	v_pk_add_f32 v[110:111], v[188:189], v[118:119]
	v_pk_add_f32 v[108:109], v[186:187], v[116:117]
	v_cvt_pk_bf16_f32 v104, v186, v187
	v_cvt_pk_bf16_f32 v105, v188, v189
	v_cvt_pk_bf16_f32 v106, v120, v121
	v_cvt_pk_bf16_f32 v107, v122, v123
	v_pk_add_f32 v[178:179], v[122:123], v[110:111]
	v_pk_add_f32 v[176:177], v[120:121], v[108:109]
	s_waitcnt vmcnt(4) lgkmcnt(0)
	s_barrier
	s_add_u32 s70, s98, 0x18000
	s_addc_u32 s71, s99, 0
	s_add_i32 s68, s68, s57
	s_mov_b32 m0, s68
	s_nop 0
	global_load_lds_dwordx4 v198, s[70:71]
	s_add_i32 m0, s68, 0x400
	s_nop 0
	global_load_lds_dwordx4 v194, s[70:71]
	s_add_u32 s2, s100, 0x80
	s_addc_u32 s3, s101, 0
	s_add_i32 s49, s58, s49
	s_add_i32 m0, s49, 0xc000
	s_nop 0
	global_load_lds_dwordx4 v196, s[2:3]
	s_add_i32 m0, s49, 0xc400
	s_nop 0
	global_load_lds_dwordx4 v192, s[2:3]
	s_add_i32 s2, s46, 0xffff4000
	s_add_i32 s3, s48, 1
	s_cmp_lg_u32 s48, 2
	s_cselect_b32 s48, s3, 0
	s_and_b32 s2, s2, 0xc000
	s_add_i32 s2, s2, 0
	s_lshl_b32 s3, s48, 14
	ds_read_b128 v[108:111], v236 offset:32768
	ds_read_b128 v[116:119], v236 offset:36864
	ds_read_b128 v[120:123], v236 offset:40960
	ds_read_b128 v[124:127], v236 offset:45056
	s_waitcnt lgkmcnt(0)
	v_mfma_f32_32x32x16_bf16 v[80:95], v[108:111], v[112:115], v[80:95]
	ds_read_b128 v[108:111], v237 offset:32768
	s_add_i32 s3, s3, 0
	v_mfma_f32_32x32x16_bf16 v[64:79], v[116:119], v[112:115], v[64:79]
	ds_read_b128 v[116:119], v237 offset:36864
	v_mfma_f32_32x32x16_bf16 v[16:31], v[120:123], v[112:115], v[16:31]
	ds_read_b128 v[120:123], v237 offset:40960
	v_mfma_f32_32x32x16_bf16 v[0:15], v[124:127], v[112:115], v[0:15]
	ds_read_b128 v[112:115], v237 offset:45056
	s_waitcnt lgkmcnt(0)
	v_mfma_f32_32x32x16_bf16 v[80:95], v[108:111], v[96:99], v[80:95]
	ds_read_b128 v[108:111], v238 offset:32768
	v_mfma_f32_32x32x16_bf16 v[64:79], v[116:119], v[96:99], v[64:79]
	ds_read_b128 v[116:119], v238 offset:36864
	v_mfma_f32_32x32x16_bf16 v[16:31], v[120:123], v[96:99], v[16:31]
	ds_read_b128 v[120:123], v238 offset:40960
	v_mfma_f32_32x32x16_bf16 v[0:15], v[112:115], v[96:99], v[0:15]
	ds_read_b128 v[96:99], v238 offset:45056
	s_waitcnt lgkmcnt(0)
	v_mfma_f32_32x32x16_bf16 v[80:95], v[108:111], v[100:103], v[80:95]
	ds_read_b128 v[108:111], v239 offset:32768
	v_mfma_f32_32x32x16_bf16 v[64:79], v[116:119], v[100:103], v[64:79]
	ds_read_b128 v[112:115], v239 offset:36864
	v_mfma_f32_32x32x16_bf16 v[16:31], v[120:123], v[100:103], v[16:31]
	ds_read_b128 v[116:119], v239 offset:40960
	v_mfma_f32_32x32x16_bf16 v[0:15], v[96:99], v[100:103], v[0:15]
	ds_read_b128 v[120:123], v239 offset:45056
	s_waitcnt lgkmcnt(0)
	v_mfma_f32_32x32x16_bf16 v[80:95], v[108:111], v[104:107], v[80:95]
	ds_read_b128 v[96:99], v205 offset:16384
	v_mfma_f32_32x32x16_bf16 v[64:79], v[112:115], v[104:107], v[64:79]
	ds_read_b128 v[100:103], v205 offset:24576
	v_mfma_f32_32x32x16_bf16 v[16:31], v[116:119], v[104:107], v[16:31]
	ds_read_b128 v[182:185], v211 offset:16384
	v_mfma_f32_32x32x16_bf16 v[0:15], v[120:123], v[104:107], v[0:15]
	ds_read_b128 v[186:189], v211 offset:24576
	s_waitcnt lgkmcnt(0)
	v_mfma_f32_32x32x16_bf16 v[112:127], v[96:99], v[160:163], 0
	ds_read_b128 v[216:219], v212 offset:16384
	v_exp_f32_e32 v224, v144
	v_exp_f32_e32 v225, v145
	v_exp_f32_e32 v226, v146
	v_exp_f32_e32 v227, v147
	ds_read_b128 v[220:223], v212 offset:24576
	v_mfma_f32_32x32x16_bf16 v[96:111], v[100:103], v[160:163], 0
	v_exp_f32_e32 v228, v148
	v_exp_f32_e32 v229, v149
	v_exp_f32_e32 v230, v150
	v_exp_f32_e32 v231, v151
	v_mfma_f32_32x32x16_bf16 v[112:127], v[182:185], v[164:167], v[112:127]
	ds_read_b128 v[148:151], v213 offset:16384
	v_exp_f32_e32 v232, v152
	v_exp_f32_e32 v233, v153
	v_exp_f32_e32 v234, v154
	v_exp_f32_e32 v235, v155
	v_cvt_pk_bf16_f32 v144, v224, v225
	v_cvt_pk_bf16_f32 v145, v226, v227
	v_cvt_pk_bf16_f32 v146, v228, v229
	v_cvt_pk_bf16_f32 v147, v230, v231
	v_pk_add_f32 v[154:155], v[230:231], v[226:227]
	v_pk_add_f32 v[152:153], v[228:229], v[224:225]
	v_mfma_f32_32x32x16_bf16 v[96:111], v[186:189], v[164:167], v[96:111]
	ds_read_b128 v[182:185], v213 offset:24576
	v_exp_f32_e32 v156, v156
	v_exp_f32_e32 v157, v157
	v_exp_f32_e32 v158, v158
	v_exp_f32_e32 v159, v159
	s_waitcnt lgkmcnt(0)
	v_mfma_f32_32x32x16_bf16 v[112:127], v[216:219], v[168:171], v[112:127]
	v_add_f32_e64 v154, v234, v154
	v_add_f32_e64 v155, v235, v155
	v_add_f32_e64 v152, v232, v152
	v_add_f32_e64 v153, v233, v153
	v_exp_f32_e32 v186, v128
	v_exp_f32_e32 v187, v129
	v_exp_f32_e32 v188, v130
	v_exp_f32_e32 v189, v131
	v_cvt_pk_bf16_f32 v128, v232, v233
	v_cvt_pk_bf16_f32 v129, v234, v235
	v_cvt_pk_bf16_f32 v130, v156, v157
	v_cvt_pk_bf16_f32 v131, v158, v159
	v_pk_add_f32 v[154:155], v[158:159], v[154:155]
	v_pk_add_f32 v[152:153], v[156:157], v[152:153]
	v_mfma_f32_32x32x16_bf16 v[96:111], v[220:223], v[168:171], v[96:111]
	v_exp_f32_e32 v156, v132
	v_exp_f32_e32 v157, v133
	v_exp_f32_e32 v158, v134
	v_exp_f32_e32 v159, v135
	v_mfma_f32_32x32x16_bf16 v[112:127], v[148:151], v[172:175], v[112:127]
	v_exp_f32_e32 v216, v136
	v_exp_f32_e32 v217, v137
	v_exp_f32_e32 v218, v138
	v_exp_f32_e32 v219, v139
	v_pk_add_f32 v[138:139], v[188:189], v[154:155]
	v_pk_add_f32 v[136:137], v[186:187], v[152:153]
	v_cvt_pk_bf16_f32 v132, v186, v187
	v_cvt_pk_bf16_f32 v133, v188, v189
	v_cvt_pk_bf16_f32 v134, v156, v157
	v_cvt_pk_bf16_f32 v135, v158, v159
	v_pk_add_f32 v[150:151], v[158:159], v[138:139]
	v_pk_add_f32 v[148:149], v[156:157], v[136:137]
	v_mfma_f32_32x32x16_bf16 v[96:111], v[182:185], v[172:175], v[96:111]
	v_exp_f32_e32 v152, v140
	v_exp_f32_e32 v153, v141
	v_exp_f32_e32 v154, v142
	v_exp_f32_e32 v155, v143
	v_pk_add_f32 v[142:143], v[218:219], v[150:151]
	v_pk_add_f32 v[140:141], v[216:217], v[148:149]
	v_cvt_pk_bf16_f32 v136, v216, v217
	v_cvt_pk_bf16_f32 v137, v218, v219
	v_cvt_pk_bf16_f32 v138, v152, v153
	v_cvt_pk_bf16_f32 v139, v154, v155
	v_pk_add_f32 v[142:143], v[154:155], v[142:143]
	v_pk_add_f32 v[140:141], v[152:153], v[140:141]
	s_waitcnt vmcnt(4) lgkmcnt(0)
	v_add_f32_e32 v148, v176, v177
	v_add_f32_e32 v149, v178, v179
	v_add_f32_e32 v148, v148, v149
	v_add_f32_e32 v140, v140, v141
	v_add_f32_e32 v141, v142, v143
	s_barrier
	v_add_f32_e32 v148, v180, v148
	v_add_f32_e32 v140, v140, v141
	v_add_f32_e32 v180, v148, v140
	s_add_i32 s47, s47, 2
	s_addk_i32 s41, 0x80
	s_add_i32 s46, s46, 0x8000
	s_add_u32 s98, s98, 0x30000
	s_addc_u32 s99, s99, 0
	s_add_u32 s100, s100, 0x100
	s_addc_u32 s101, s101, 0
	s_lshl_b32 s49, s48, 14
	s_add_i32 s49, s58, s49
	s_mov_b32 m0, s49
	s_nop 0
	global_load_lds_dwordx4 v198, s[98:99]
	s_add_i32 m0, s49, 0x400
	s_nop 0
	global_load_lds_dwordx4 v194, s[98:99]
	s_add_i32 s49, s46, 0xffffc000
	s_and_b32 s49, s49, 0xc000
	s_add_i32 s49, s58, s49
	s_add_i32 m0, s49, 0xc000
	s_nop 0
	global_load_lds_dwordx4 v196, s[100:101]
	s_add_i32 m0, s49, 0xc400
	s_add_i32 s44, s48, 1
	global_load_lds_dwordx4 v192, s[100:101]
	s_cmp_lg_u32 s48, 2
	s_cselect_b32 s48, s44, 0
	s_lshl_b32 s44, s48, 14
	s_and_b32 s49, s46, 0xc000
	s_add_i32 s68, s44, 0
	s_add_i32 s44, s49, 0
	ds_read_b128 v[140:143], v206 offset:49152
	ds_read_b128 v[148:151], v206 offset:53248
	ds_read_b128 v[152:155], v206 offset:57344
	ds_read_b128 v[156:159], v206 offset:61440
	s_waitcnt lgkmcnt(0)
	v_mfma_f32_32x32x16_bf16 v[80:95], v[140:143], v[144:147], v[80:95]
	ds_read_b128 v[140:143], v207 offset:49152
	v_mfma_f32_32x32x16_bf16 v[64:79], v[148:151], v[144:147], v[64:79]
	ds_read_b128 v[148:151], v207 offset:53248
	v_mfma_f32_32x32x16_bf16 v[16:31], v[152:155], v[144:147], v[16:31]
	ds_read_b128 v[152:155], v207 offset:57344
	v_mfma_f32_32x32x16_bf16 v[0:15], v[156:159], v[144:147], v[0:15]
	ds_read_b128 v[144:147], v207 offset:61440
	s_waitcnt lgkmcnt(0)
	v_mfma_f32_32x32x16_bf16 v[80:95], v[140:143], v[128:131], v[80:95]
	ds_read_b128 v[140:143], v208 offset:49152
	v_mfma_f32_32x32x16_bf16 v[64:79], v[148:151], v[128:131], v[64:79]
	ds_read_b128 v[148:151], v208 offset:53248
	v_mfma_f32_32x32x16_bf16 v[16:31], v[152:155], v[128:131], v[16:31]
	ds_read_b128 v[152:155], v208 offset:57344
	v_mfma_f32_32x32x16_bf16 v[0:15], v[144:147], v[128:131], v[0:15]
	ds_read_b128 v[128:131], v208 offset:61440
	s_waitcnt lgkmcnt(0)
	v_mfma_f32_32x32x16_bf16 v[80:95], v[140:143], v[132:135], v[80:95]
	ds_read_b128 v[140:143], v209 offset:49152
	v_mfma_f32_32x32x16_bf16 v[64:79], v[148:151], v[132:135], v[64:79]
	ds_read_b128 v[144:147], v209 offset:53248
	v_mfma_f32_32x32x16_bf16 v[16:31], v[152:155], v[132:135], v[16:31]
	ds_read_b128 v[148:151], v209 offset:57344
	v_mfma_f32_32x32x16_bf16 v[0:15], v[128:131], v[132:135], v[0:15]
	ds_read_b128 v[128:131], v209 offset:61440
	s_waitcnt lgkmcnt(0)
	v_mfma_f32_32x32x16_bf16 v[80:95], v[140:143], v[136:139], v[80:95]
	ds_read_b128 v[132:135], v205 offset:32768
	v_mfma_f32_32x32x16_bf16 v[64:79], v[144:147], v[136:139], v[64:79]
	ds_read_b128 v[140:143], v205 offset:40960
	v_mfma_f32_32x32x16_bf16 v[16:31], v[148:151], v[136:139], v[16:31]
	ds_read_b128 v[176:179], v211 offset:32768
	v_mfma_f32_32x32x16_bf16 v[0:15], v[128:131], v[136:139], v[0:15]
	ds_read_b128 v[182:185], v211 offset:40960
	s_waitcnt lgkmcnt(0)
	v_mfma_f32_32x32x16_bf16 v[144:159], v[132:135], v[160:163], 0
	ds_read_b128 v[186:189], v212 offset:32768
	v_exp_f32_e32 v220, v112
	v_exp_f32_e32 v221, v113
	v_exp_f32_e32 v222, v114
	v_exp_f32_e32 v223, v115
	v_mfma_f32_32x32x16_bf16 v[128:143], v[140:143], v[160:163], 0
	ds_read_b128 v[216:219], v212 offset:40960
	v_exp_f32_e32 v224, v116
	v_exp_f32_e32 v225, v117
	v_exp_f32_e32 v226, v118
	v_exp_f32_e32 v227, v119
	v_mfma_f32_32x32x16_bf16 v[144:159], v[176:179], v[164:167], v[144:159]
	ds_read_b128 v[116:119], v213 offset:32768
	v_exp_f32_e32 v228, v120
	v_exp_f32_e32 v229, v121
	v_exp_f32_e32 v230, v122
	v_exp_f32_e32 v231, v123
	v_cvt_pk_bf16_f32 v112, v220, v221
	v_cvt_pk_bf16_f32 v113, v222, v223
	v_cvt_pk_bf16_f32 v114, v224, v225
	v_cvt_pk_bf16_f32 v115, v226, v227
	v_pk_add_f32 v[122:123], v[226:227], v[222:223]
	v_pk_add_f32 v[120:121], v[224:225], v[220:221]
	v_mfma_f32_32x32x16_bf16 v[128:143], v[182:185], v[164:167], v[128:143]
	ds_read_b128 v[176:179], v213 offset:40960
	v_exp_f32_e32 v124, v124
	v_exp_f32_e32 v125, v125
	v_exp_f32_e32 v126, v126
	v_exp_f32_e32 v127, v127
	s_waitcnt lgkmcnt(0)
	v_mfma_f32_32x32x16_bf16 v[144:159], v[186:189], v[168:171], v[144:159]
	v_add_f32_e64 v122, v230, v122
	v_add_f32_e64 v123, v231, v123
	v_add_f32_e64 v120, v228, v120
	v_add_f32_e64 v121, v229, v121
	v_exp_f32_e32 v182, v96
	v_exp_f32_e32 v183, v97
	v_exp_f32_e32 v184, v98
	v_exp_f32_e32 v185, v99
	v_cvt_pk_bf16_f32 v96, v228, v229
	v_cvt_pk_bf16_f32 v97, v230, v231
	v_cvt_pk_bf16_f32 v98, v124, v125
	v_cvt_pk_bf16_f32 v99, v126, v127
	v_pk_add_f32 v[122:123], v[126:127], v[122:123]
	v_pk_add_f32 v[120:121], v[124:125], v[120:121]
	v_mfma_f32_32x32x16_bf16 v[128:143], v[216:219], v[168:171], v[128:143]
	v_exp_f32_e32 v124, v100
	v_exp_f32_e32 v125, v101
	v_exp_f32_e32 v126, v102
	v_exp_f32_e32 v127, v103
	v_mfma_f32_32x32x16_bf16 v[144:159], v[116:119], v[172:175], v[144:159]
	v_exp_f32_e32 v186, v104
	v_exp_f32_e32 v187, v105
	v_exp_f32_e32 v188, v106
	v_exp_f32_e32 v189, v107
	v_pk_add_f32 v[106:107], v[184:185], v[122:123]
	v_pk_add_f32 v[104:105], v[182:183], v[120:121]
	v_cvt_pk_bf16_f32 v100, v182, v183
	v_cvt_pk_bf16_f32 v101, v184, v185
	v_cvt_pk_bf16_f32 v102, v124, v125
	v_cvt_pk_bf16_f32 v103, v126, v127
	v_pk_add_f32 v[118:119], v[126:127], v[106:107]
	v_pk_add_f32 v[116:117], v[124:125], v[104:105]
	v_mfma_f32_32x32x16_bf16 v[128:143], v[176:179], v[172:175], v[128:143]
	v_exp_f32_e32 v120, v108
	v_exp_f32_e32 v121, v109
	v_exp_f32_e32 v122, v110
	v_exp_f32_e32 v123, v111
	v_pk_add_f32 v[110:111], v[188:189], v[118:119]
	v_pk_add_f32 v[108:109], v[186:187], v[116:117]
	v_cvt_pk_bf16_f32 v104, v186, v187
	v_cvt_pk_bf16_f32 v105, v188, v189
	v_cvt_pk_bf16_f32 v106, v120, v121
	v_cvt_pk_bf16_f32 v107, v122, v123
	v_pk_add_f32 v[178:179], v[122:123], v[110:111]
	v_pk_add_f32 v[176:177], v[120:121], v[108:109]
	s_waitcnt vmcnt(4) lgkmcnt(0)
	s_barrier
	s_add_u32 s70, s98, 0x18000
	s_addc_u32 s71, s99, 0
	s_add_i32 s68, s68, s57
	s_mov_b32 m0, s68
	s_nop 0
	global_load_lds_dwordx4 v198, s[70:71]
	s_add_i32 m0, s68, 0x400
	s_nop 0
	global_load_lds_dwordx4 v194, s[70:71]
	s_add_u32 s2, s100, 0x80
	s_addc_u32 s3, s101, 0
	s_add_i32 s49, s58, s49
	s_add_i32 m0, s49, 0xc000
	s_nop 0
	global_load_lds_dwordx4 v196, s[2:3]
	s_add_i32 m0, s49, 0xc400
	s_nop 0
	global_load_lds_dwordx4 v192, s[2:3]
	s_add_i32 s2, s46, 0xffff4000
	s_add_i32 s3, s48, 1
	s_cmp_lg_u32 s48, 2
	s_cselect_b32 s48, s3, 0
	s_and_b32 s2, s2, 0xc000
	s_add_i32 s2, s2, 0
	s_lshl_b32 s3, s48, 14
	ds_read_b128 v[108:111], v236
	ds_read_b128 v[116:119], v236 offset:4096
	ds_read_b128 v[120:123], v236 offset:8192
	ds_read_b128 v[124:127], v236 offset:12288
	s_waitcnt lgkmcnt(0)
	v_mfma_f32_32x32x16_bf16 v[80:95], v[108:111], v[112:115], v[80:95]
	ds_read_b128 v[108:111], v237
	s_add_i32 s3, s3, 0
	v_mfma_f32_32x32x16_bf16 v[64:79], v[116:119], v[112:115], v[64:79]
	ds_read_b128 v[116:119], v237 offset:4096
	v_mfma_f32_32x32x16_bf16 v[16:31], v[120:123], v[112:115], v[16:31]
	ds_read_b128 v[120:123], v237 offset:8192
	v_mfma_f32_32x32x16_bf16 v[0:15], v[124:127], v[112:115], v[0:15]
	ds_read_b128 v[112:115], v237 offset:12288
	s_waitcnt lgkmcnt(0)
	v_mfma_f32_32x32x16_bf16 v[80:95], v[108:111], v[96:99], v[80:95]
	ds_read_b128 v[108:111], v238
	v_mfma_f32_32x32x16_bf16 v[64:79], v[116:119], v[96:99], v[64:79]
	ds_read_b128 v[116:119], v238 offset:4096
	v_mfma_f32_32x32x16_bf16 v[16:31], v[120:123], v[96:99], v[16:31]
	ds_read_b128 v[120:123], v238 offset:8192
	v_mfma_f32_32x32x16_bf16 v[0:15], v[112:115], v[96:99], v[0:15]
	ds_read_b128 v[96:99], v238 offset:12288
	s_waitcnt lgkmcnt(0)
	v_mfma_f32_32x32x16_bf16 v[80:95], v[108:111], v[100:103], v[80:95]
	ds_read_b128 v[108:111], v239
	v_mfma_f32_32x32x16_bf16 v[64:79], v[116:119], v[100:103], v[64:79]
	ds_read_b128 v[112:115], v239 offset:4096
	v_mfma_f32_32x32x16_bf16 v[16:31], v[120:123], v[100:103], v[16:31]
	ds_read_b128 v[116:119], v239 offset:8192
	v_mfma_f32_32x32x16_bf16 v[0:15], v[96:99], v[100:103], v[0:15]
	ds_read_b128 v[120:123], v239 offset:12288
	s_waitcnt lgkmcnt(0)
	v_mfma_f32_32x32x16_bf16 v[80:95], v[108:111], v[104:107], v[80:95]
	ds_read_b128 v[96:99], v205
	v_mfma_f32_32x32x16_bf16 v[64:79], v[112:115], v[104:107], v[64:79]
	ds_read_b128 v[100:103], v205 offset:8192
	v_mfma_f32_32x32x16_bf16 v[16:31], v[116:119], v[104:107], v[16:31]
	ds_read_b128 v[182:185], v211
	v_mfma_f32_32x32x16_bf16 v[0:15], v[120:123], v[104:107], v[0:15]
	ds_read_b128 v[186:189], v211 offset:8192
	s_waitcnt lgkmcnt(0)
	v_mfma_f32_32x32x16_bf16 v[112:127], v[96:99], v[160:163], 0
	ds_read_b128 v[216:219], v212
	v_exp_f32_e32 v224, v144
	v_exp_f32_e32 v225, v145
	v_exp_f32_e32 v226, v146
	v_exp_f32_e32 v227, v147
	ds_read_b128 v[220:223], v212 offset:8192
	v_mfma_f32_32x32x16_bf16 v[96:111], v[100:103], v[160:163], 0
	v_exp_f32_e32 v228, v148
	v_exp_f32_e32 v229, v149
	v_exp_f32_e32 v230, v150
	v_exp_f32_e32 v231, v151
	v_mfma_f32_32x32x16_bf16 v[112:127], v[182:185], v[164:167], v[112:127]
	ds_read_b128 v[148:151], v213
	v_exp_f32_e32 v232, v152
	v_exp_f32_e32 v233, v153
	v_exp_f32_e32 v234, v154
	v_exp_f32_e32 v235, v155
	v_cvt_pk_bf16_f32 v144, v224, v225
	v_cvt_pk_bf16_f32 v145, v226, v227
	v_cvt_pk_bf16_f32 v146, v228, v229
	v_cvt_pk_bf16_f32 v147, v230, v231
	v_pk_add_f32 v[154:155], v[230:231], v[226:227]
	v_pk_add_f32 v[152:153], v[228:229], v[224:225]
	v_mfma_f32_32x32x16_bf16 v[96:111], v[186:189], v[164:167], v[96:111]
	ds_read_b128 v[182:185], v213 offset:8192
	v_exp_f32_e32 v156, v156
	v_exp_f32_e32 v157, v157
	v_exp_f32_e32 v158, v158
	v_exp_f32_e32 v159, v159
	s_waitcnt lgkmcnt(0)
	v_mfma_f32_32x32x16_bf16 v[112:127], v[216:219], v[168:171], v[112:127]
	v_add_f32_e64 v154, v234, v154
	v_add_f32_e64 v155, v235, v155
	v_add_f32_e64 v152, v232, v152
	v_add_f32_e64 v153, v233, v153
	v_exp_f32_e32 v186, v128
	v_exp_f32_e32 v187, v129
	v_exp_f32_e32 v188, v130
	v_exp_f32_e32 v189, v131
	v_cvt_pk_bf16_f32 v128, v232, v233
	v_cvt_pk_bf16_f32 v129, v234, v235
	v_cvt_pk_bf16_f32 v130, v156, v157
	v_cvt_pk_bf16_f32 v131, v158, v159
	v_pk_add_f32 v[154:155], v[158:159], v[154:155]
	v_pk_add_f32 v[152:153], v[156:157], v[152:153]
	v_mfma_f32_32x32x16_bf16 v[96:111], v[220:223], v[168:171], v[96:111]
	v_exp_f32_e32 v156, v132
	v_exp_f32_e32 v157, v133
	v_exp_f32_e32 v158, v134
	v_exp_f32_e32 v159, v135
	v_mfma_f32_32x32x16_bf16 v[112:127], v[148:151], v[172:175], v[112:127]
	v_exp_f32_e32 v216, v136
	v_exp_f32_e32 v217, v137
	v_exp_f32_e32 v218, v138
	v_exp_f32_e32 v219, v139
	v_pk_add_f32 v[138:139], v[188:189], v[154:155]
	v_pk_add_f32 v[136:137], v[186:187], v[152:153]
	v_cvt_pk_bf16_f32 v132, v186, v187
	v_cvt_pk_bf16_f32 v133, v188, v189
	v_cvt_pk_bf16_f32 v134, v156, v157
	v_cvt_pk_bf16_f32 v135, v158, v159
	v_pk_add_f32 v[150:151], v[158:159], v[138:139]
	v_pk_add_f32 v[148:149], v[156:157], v[136:137]
	v_mfma_f32_32x32x16_bf16 v[96:111], v[182:185], v[172:175], v[96:111]
	v_exp_f32_e32 v152, v140
	v_exp_f32_e32 v153, v141
	v_exp_f32_e32 v154, v142
	v_exp_f32_e32 v155, v143
	v_pk_add_f32 v[142:143], v[218:219], v[150:151]
	v_pk_add_f32 v[140:141], v[216:217], v[148:149]
	v_cvt_pk_bf16_f32 v136, v216, v217
	v_cvt_pk_bf16_f32 v137, v218, v219
	v_cvt_pk_bf16_f32 v138, v152, v153
	v_cvt_pk_bf16_f32 v139, v154, v155
	v_pk_add_f32 v[142:143], v[154:155], v[142:143]
	v_pk_add_f32 v[140:141], v[152:153], v[140:141]
	s_waitcnt vmcnt(4) lgkmcnt(0)
	v_add_f32_e32 v148, v176, v177
	v_add_f32_e32 v149, v178, v179
	v_add_f32_e32 v148, v148, v149
	v_add_f32_e32 v140, v140, v141
	v_add_f32_e32 v141, v142, v143
	s_barrier
	v_add_f32_e32 v148, v180, v148
	v_add_f32_e32 v140, v140, v141
	v_add_f32_e32 v180, v148, v140
	s_add_i32 s47, s47, 2
	s_addk_i32 s41, 0x80
	s_add_i32 s46, s46, 0x8000
	s_add_u32 s98, s98, 0x30000
	s_addc_u32 s99, s99, 0
	s_add_u32 s100, s100, 0x100
	s_addc_u32 s101, s101, 0
	s_cmp_lt_u32 s47, 50
	s_cbranch_scc1 .Lst1_u6_loop
	s_cmp_lt_u32 s47, 60
	s_cbranch_scc1 .Lst1_single

; __device__ __forceinline__ unsigned cvt_pk_bf16(float lo, float hi) { unsigned r; asm volatile("v_cvt_pk_bf16_f32 %0, %1, %2" : "=v"(r) : "v"(lo), "v"(hi)); return r; }
; __device__ __forceinline__ float silu_f(float g) { return g * __builtin_amdgcn_rcpf(1.0f + __builtin_amdgcn_exp2f(-1.4426950408889634f * g)); }
;     __device__ __forceinline__ void operator()(const f32x4 (&acc)[2][2][4][2], const Unit& u, int wr, int wc, int fr, int fq) const {
;         const int row0 = u.pm * BM + wr * 64 + fr, col0 = u.pn * 128 + wc * 32 + 8 * fq;
; #pragma unroll
;         for (int ai = 0; ai < 2; ++ai)
; #pragma unroll
;             for (int m = 0; m < 4; ++m) {
;                 bf16_t* rowp = H + (size_t)(row0 + ai * HALF + m * 16) * DFF + col0;
;                 const f32x4 g0 = acc[ai][0][m][0], g1 = acc[ai][0][m][1], u0 = acc[ai][1][m][0], u1 = acc[ai][1][m][1];
;                 u32x4 w;
;                 w.x = cvt_pk_bf16(silu_f(g0[0]) * u0[0], silu_f(g0[1]) * u0[1]); w.y = cvt_pk_bf16(silu_f(g0[2]) * u0[2], silu_f(g0[3]) * u0[3]);
;                 w.z = cvt_pk_bf16(silu_f(g1[0]) * u1[0], silu_f(g1[1]) * u1[1]); w.w = cvt_pk_bf16(silu_f(g1[2]) * u1[2], silu_f(g1[3]) * u1[3]);
;                 *(u32x4*)rowp = w;
.LBB0_1274:
	v_exp_f32_e64 v154, -v125
	v_lshl_or_b32 v144, s42, 7, v148
	v_lshl_add_u32 v150, s6, 8, v146
	v_add_f32_e32 v154, 1.0, v154
	v_rcp_f32_e32 v154, v154
	v_exp_f32_e64 v151, -v124
	v_mul_lo_u32 v156, v150, s47
	v_lshl_add_u32 v156, v144, 1, v156
	v_mul_f32_e32 v152, v125, v154
	v_exp_f32_e64 v153, -v126
	v_exp_f32_e64 v154, -v127
	v_add_f32_e32 v151, 1.0, v151
	v_rcp_f32_e32 v151, v151
	v_add_f32_e32 v153, 1.0, v153
	v_add_f32_e32 v154, 1.0, v154
	v_rcp_f32_e32 v153, v153
	v_rcp_f32_e32 v154, v154
	v_mul_f32_e32 v151, v124, v151
	v_mul_f32_e32 v151, v151, v92
	v_mul_f32_e32 v152, v152, v93
	v_cvt_pk_bf16_f32 v152, v151, v152
	v_mul_f32_e32 v151, v126, v153
	v_mul_f32_e32 v153, v127, v154
	v_exp_f32_e64 v154, -v120
	v_exp_f32_e64 v155, -v121
	v_mul_f32_e32 v151, v151, v94
	v_mul_f32_e32 v153, v153, v95
	v_add_f32_e32 v154, 1.0, v154
	v_add_f32_e32 v155, 1.0, v155
	v_rcp_f32_e32 v154, v154
	v_rcp_f32_e32 v155, v155
	v_cvt_pk_bf16_f32 v153, v151, v153
	v_mul_f32_e32 v151, v120, v154
	v_mul_f32_e32 v154, v121, v155
	v_exp_f32_e64 v155, -v122
	v_exp_f32_e64 v158, -v123
	v_mul_f32_e32 v151, v151, v88
	v_mul_f32_e32 v154, v154, v89
	v_add_f32_e32 v155, 1.0, v155
	v_add_f32_e32 v158, 1.0, v158
	v_rcp_f32_e32 v155, v155
	v_rcp_f32_e32 v158, v158
	v_cvt_pk_bf16_f32 v154, v151, v154
	s_add_u32 s36, s27, 0xffffff00
	v_mul_f32_e32 v151, v122, v155
	v_mul_f32_e32 v155, v123, v158
	v_mul_f32_e32 v155, v155, v91
	v_mul_f32_e32 v151, v151, v90
	v_cvt_pk_bf16_f32 v155, v151, v155
	global_store_dwordx4 v156, v[152:155], s[16:17]
	s_nop 1
	v_exp_f32_e64 v154, -v116
	v_exp_f32_e64 v155, -v117
	v_add_f32_e32 v151, 1.0, v154
	v_add_f32_e32 v154, 1.0, v155
	v_rcp_f32_e32 v154, v154
	v_exp_f32_e64 v153, -v118
	v_mul_f32_e32 v152, v117, v154
	v_exp_f32_e64 v154, -v119
	v_rcp_f32_e32 v151, v151
	v_add_f32_e32 v153, 1.0, v153
	v_rcp_f32_e32 v153, v153
	v_add_f32_e32 v154, 1.0, v154
	v_rcp_f32_e32 v154, v154
	v_mul_f32_e32 v151, v116, v151
	v_mul_f32_e32 v151, v151, v84
	v_mul_f32_e32 v152, v152, v85
	v_cvt_pk_bf16_f32 v152, v151, v152
	v_mul_f32_e32 v151, v118, v153
	v_mul_f32_e32 v153, v119, v154
	v_exp_f32_e64 v154, -v112
	v_exp_f32_e64 v155, -v113
	v_mul_f32_e32 v151, v151, v86
	v_mul_f32_e32 v153, v153, v87
	v_add_f32_e32 v154, 1.0, v154
	v_add_f32_e32 v155, 1.0, v155
	v_rcp_f32_e32 v154, v154
	v_rcp_f32_e32 v155, v155
	v_cvt_pk_bf16_f32 v153, v151, v153
	v_exp_f32_e64 v158, -v115
	v_mul_f32_e32 v151, v112, v154
	v_mul_f32_e32 v154, v113, v155
	v_exp_f32_e64 v155, -v114
	v_add_f32_e32 v158, 1.0, v158
	v_rcp_f32_e32 v158, v158
	v_mul_f32_e32 v151, v151, v80
	v_add_f32_e32 v155, 1.0, v155
	v_rcp_f32_e32 v155, v155
	v_mul_f32_e32 v154, v154, v81
	v_cvt_pk_bf16_f32 v154, v151, v154
	s_addc_u32 s37, s51, -1
	v_mul_f32_e32 v151, v114, v155
	v_mul_f32_e32 v155, v115, v158
	v_mul_f32_e32 v155, v155, v83
	v_mul_f32_e32 v151, v151, v82
	v_cvt_pk_bf16_f32 v155, v151, v155
	s_mul_i32 s98, s47, 16
	s_add_u32 s98, s16, s98
	s_addc_u32 s99, s17, 0
	global_store_dwordx4 v156, v[152:155], s[98:99]
	s_nop 1
	v_exp_f32_e64 v154, -v108
	v_exp_f32_e64 v155, -v109
	v_add_f32_e32 v151, 1.0, v154
	v_add_f32_e32 v154, 1.0, v155
	v_rcp_f32_e32 v154, v154
	v_exp_f32_e64 v153, -v110
	v_mul_f32_e32 v152, v109, v154
	v_exp_f32_e64 v154, -v111
	v_rcp_f32_e32 v151, v151
	v_add_f32_e32 v153, 1.0, v153
	v_rcp_f32_e32 v153, v153
	v_add_f32_e32 v154, 1.0, v154
	v_rcp_f32_e32 v154, v154
	v_mul_f32_e32 v151, v108, v151
	v_mul_f32_e32 v151, v151, v76
	v_mul_f32_e32 v152, v152, v77
	v_cvt_pk_bf16_f32 v152, v151, v152
	v_mul_f32_e32 v151, v110, v153
	v_mul_f32_e32 v153, v111, v154
	v_exp_f32_e64 v154, -v104
	v_exp_f32_e64 v155, -v105
	v_mul_f32_e32 v151, v151, v78
	v_mul_f32_e32 v153, v153, v79
	v_add_f32_e32 v154, 1.0, v154
	v_add_f32_e32 v155, 1.0, v155
	v_rcp_f32_e32 v154, v154
	v_rcp_f32_e32 v155, v155
	v_cvt_pk_bf16_f32 v153, v151, v153
	v_exp_f32_e64 v158, -v107
	v_mul_f32_e32 v151, v104, v154
	v_mul_f32_e32 v154, v105, v155
	v_exp_f32_e64 v155, -v106
	v_add_f32_e32 v158, 1.0, v158
	v_rcp_f32_e32 v158, v158
	v_mul_f32_e32 v151, v151, v72
	v_add_f32_e32 v155, 1.0, v155
	v_rcp_f32_e32 v155, v155
	v_mul_f32_e32 v154, v154, v73
	v_cvt_pk_bf16_f32 v154, v151, v154
	s_andn2_b64 vcc, exec, s[38:39]
	v_mul_f32_e32 v151, v106, v155
	v_mul_f32_e32 v155, v107, v158
	v_mul_f32_e32 v155, v155, v75
	v_mul_f32_e32 v151, v151, v74
	v_cvt_pk_bf16_f32 v155, v151, v155
	s_mul_i32 s98, s47, 32
	s_add_u32 s98, s16, s98
	s_addc_u32 s99, s17, 0
	global_store_dwordx4 v156, v[152:155], s[98:99]
	s_nop 1
	v_exp_f32_e64 v154, -v100
	v_exp_f32_e64 v155, -v101
	v_add_f32_e32 v151, 1.0, v154
	v_add_f32_e32 v154, 1.0, v155
	v_rcp_f32_e32 v154, v154
	v_exp_f32_e64 v153, -v102
	v_mul_f32_e32 v152, v101, v154
	v_exp_f32_e64 v154, -v103
	v_rcp_f32_e32 v151, v151
	v_add_f32_e32 v153, 1.0, v153
	v_rcp_f32_e32 v153, v153
	v_add_f32_e32 v154, 1.0, v154
	v_rcp_f32_e32 v154, v154
	v_mul_f32_e32 v151, v100, v151
	v_mul_f32_e32 v151, v151, v68
	v_mul_f32_e32 v152, v152, v69
	v_cvt_pk_bf16_f32 v152, v151, v152
	v_mul_f32_e32 v151, v102, v153
	v_mul_f32_e32 v153, v103, v154
	v_exp_f32_e64 v154, -v96
	v_exp_f32_e64 v155, -v97
	v_mul_f32_e32 v151, v151, v70
	v_mul_f32_e32 v153, v153, v71
	v_add_f32_e32 v154, 1.0, v154
	v_add_f32_e32 v155, 1.0, v155
	v_rcp_f32_e32 v154, v154
	v_rcp_f32_e32 v155, v155
	v_cvt_pk_bf16_f32 v153, v151, v153
	v_exp_f32_e64 v158, -v99
	v_mul_f32_e32 v151, v96, v154
	v_mul_f32_e32 v154, v97, v155
	v_exp_f32_e64 v155, -v98
	v_add_f32_e32 v158, 1.0, v158
	v_rcp_f32_e32 v158, v158
	v_mul_f32_e32 v151, v151, v64
	v_add_f32_e32 v155, 1.0, v155
	v_rcp_f32_e32 v155, v155
	v_mul_f32_e32 v154, v154, v65
; __device__ __forceinline__ unsigned cvt_pk_bf16(float lo, float hi) { unsigned r; asm volatile("v_cvt_pk_bf16_f32 %0, %1, %2" : "=v"(r) : "v"(lo), "v"(hi)); return r; }
; __device__ __forceinline__ float silu_f(float g) { return g * __builtin_amdgcn_rcpf(1.0f + __builtin_amdgcn_exp2f(-1.4426950408889634f * g)); }
; #define PG8_BAR __builtin_amdgcn_s_barrier()
; template <class Epi, bool BSEL = false>
; __device__ __forceinline__ void gemm_phase(LAS unsigned char* lds, const Gemm g, const Order& S, const Epi& E, const int tid) {
;     ...
;         if (!has_next) break;
; #pragma unroll
;         for (int a = 0; a < 2; ++a)
; #pragma unroll
;             for (int b = 0; b < 2; ++b)
; #pragma unroll
;                 for (int m = 0; m < 4; ++m)
; #pragma unroll
;                     for (int n = 0; n < 2; ++n) acc[a][b][m][n] = (f32x4){0.f, 0.f, 0.f, 0.f};
;         cur = nxt; cA = nA; cB = nB; cP = nP; chB = nhB; ++ui;
;         if constexpr (ALIGN_EPI) { if (wr == 1) PG8_BAR; }
;     __device__ __forceinline__ void operator()(const f32x4 (&acc)[2][2][4][2], const Unit& u, int wr, int wc, int fr, int fq) const {
;     ...
;             for (int m = 0; m < 4; ++m) {
;                 bf16_t* rowp = H + (size_t)(row0 + ai * HALF + m * 16) * DFF + col0;
;                 const f32x4 g0 = acc[ai][0][m][0], g1 = acc[ai][0][m][1], u0 = acc[ai][1][m][0], u1 = acc[ai][1][m][1];
;                 u32x4 w;
;                 w.x = cvt_pk_bf16(silu_f(g0[0]) * u0[0], silu_f(g0[1]) * u0[1]); w.y = cvt_pk_bf16(silu_f(g0[2]) * u0[2], silu_f(g0[3]) * u0[3]);
;                 w.z = cvt_pk_bf16(silu_f(g1[0]) * u1[0], silu_f(g1[1]) * u1[1]); w.w = cvt_pk_bf16(silu_f(g1[2]) * u1[2], silu_f(g1[3]) * u1[3]);
;                 *(u32x4*)rowp = w;
	v_cvt_pk_bf16_f32 v154, v151, v154
	v_mul_f32_e32 v151, v98, v155
	v_mul_f32_e32 v155, v99, v158
	v_mul_f32_e32 v155, v155, v67
	v_mul_f32_e32 v151, v151, v66
	v_cvt_pk_bf16_f32 v155, v151, v155
	s_mul_i32 s98, s47, 48
	s_add_u32 s98, s16, s98
	s_addc_u32 s99, s17, 0
	global_store_dwordx4 v156, v[152:155], s[98:99]
	s_nop 1
	v_exp_f32_e64 v154, -v60
	v_exp_f32_e64 v155, -v61
	v_add_f32_e32 v151, 1.0, v154
	v_add_f32_e32 v154, 1.0, v155
	v_rcp_f32_e32 v154, v154
	v_exp_f32_e64 v153, -v62
	v_mul_f32_e32 v152, v61, v154
	v_exp_f32_e64 v154, -v63
	v_rcp_f32_e32 v151, v151
	v_add_f32_e32 v153, 1.0, v153
	v_rcp_f32_e32 v153, v153
	v_add_f32_e32 v154, 1.0, v154
	v_rcp_f32_e32 v154, v154
	v_mul_f32_e32 v151, v60, v151
	v_mul_f32_e32 v151, v151, v28
	v_mul_f32_e32 v152, v152, v29
	v_cvt_pk_bf16_f32 v152, v151, v152
	v_mul_f32_e32 v151, v62, v153
	v_mul_f32_e32 v153, v63, v154
	v_exp_f32_e64 v154, -v56
	v_exp_f32_e64 v155, -v57
	v_mul_f32_e32 v151, v151, v30
	v_mul_f32_e32 v153, v153, v31
	v_add_f32_e32 v154, 1.0, v154
	v_add_f32_e32 v155, 1.0, v155
	v_rcp_f32_e32 v154, v154
	v_rcp_f32_e32 v155, v155
	v_cvt_pk_bf16_f32 v153, v151, v153
	v_exp_f32_e64 v158, -v59
	v_mul_f32_e32 v151, v56, v154
	v_mul_f32_e32 v154, v57, v155
	v_exp_f32_e64 v155, -v58
	v_add_f32_e32 v158, 1.0, v158
	v_rcp_f32_e32 v158, v158
	v_mul_f32_e32 v151, v151, v24
	v_add_f32_e32 v155, 1.0, v155
	v_rcp_f32_e32 v155, v155
	v_mul_f32_e32 v154, v154, v25
	v_cvt_pk_bf16_f32 v154, v151, v154
	v_mul_f32_e32 v151, v58, v155
	v_mul_f32_e32 v155, v59, v158
	v_mul_f32_e32 v155, v155, v27
	v_mul_f32_e32 v151, v151, v26
	v_cvt_pk_bf16_f32 v155, v151, v155
	s_mul_i32 s98, s47, 128
	s_add_u32 s98, s16, s98
	s_addc_u32 s99, s17, 0
	global_store_dwordx4 v156, v[152:155], s[98:99]
	s_nop 1
	v_exp_f32_e64 v154, -v52
	v_exp_f32_e64 v155, -v53
	v_add_f32_e32 v151, 1.0, v154
	v_add_f32_e32 v154, 1.0, v155
	v_rcp_f32_e32 v154, v154
	v_exp_f32_e64 v153, -v54
	v_mul_f32_e32 v152, v53, v154
	v_exp_f32_e64 v154, -v55
	v_rcp_f32_e32 v151, v151
	v_add_f32_e32 v153, 1.0, v153
	v_rcp_f32_e32 v153, v153
	v_add_f32_e32 v154, 1.0, v154
	v_rcp_f32_e32 v154, v154
	v_mul_f32_e32 v151, v52, v151
	v_mul_f32_e32 v151, v151, v20
	v_mul_f32_e32 v152, v152, v21
	v_cvt_pk_bf16_f32 v152, v151, v152
	v_mul_f32_e32 v151, v54, v153
	v_mul_f32_e32 v153, v55, v154
	v_exp_f32_e64 v154, -v48
	v_exp_f32_e64 v155, -v49
	v_mul_f32_e32 v151, v151, v22
	v_mul_f32_e32 v153, v153, v23
	v_add_f32_e32 v154, 1.0, v154
	v_add_f32_e32 v155, 1.0, v155
	v_rcp_f32_e32 v154, v154
	v_rcp_f32_e32 v155, v155
	v_cvt_pk_bf16_f32 v153, v151, v153
	v_exp_f32_e64 v158, -v51
	v_mul_f32_e32 v151, v48, v154
	v_mul_f32_e32 v154, v49, v155
	v_exp_f32_e64 v155, -v50
	v_add_f32_e32 v158, 1.0, v158
	v_rcp_f32_e32 v158, v158
	v_mul_f32_e32 v151, v151, v16
	v_add_f32_e32 v155, 1.0, v155
	v_rcp_f32_e32 v155, v155
	v_mul_f32_e32 v154, v154, v17
	v_cvt_pk_bf16_f32 v154, v151, v154
	v_mul_f32_e32 v151, v50, v155
	v_mul_f32_e32 v155, v51, v158
	v_mul_f32_e32 v155, v155, v19
	v_mul_f32_e32 v151, v151, v18
	v_cvt_pk_bf16_f32 v155, v151, v155
	s_mul_i32 s98, s47, 144
	s_add_u32 s98, s16, s98
	s_addc_u32 s99, s17, 0
	global_store_dwordx4 v156, v[152:155], s[98:99]
	s_nop 1
	v_exp_f32_e64 v154, -v44
	v_exp_f32_e64 v155, -v45
	v_add_f32_e32 v151, 1.0, v154
	v_add_f32_e32 v154, 1.0, v155
	v_rcp_f32_e32 v154, v154
	v_exp_f32_e64 v153, -v46
	v_mul_f32_e32 v152, v45, v154
	v_exp_f32_e64 v154, -v47
	v_rcp_f32_e32 v151, v151
	v_add_f32_e32 v153, 1.0, v153
	v_rcp_f32_e32 v153, v153
	v_add_f32_e32 v154, 1.0, v154
	v_rcp_f32_e32 v154, v154
	v_mul_f32_e32 v151, v44, v151
	v_mul_f32_e32 v151, v151, v12
	v_mul_f32_e32 v152, v152, v13
	v_cvt_pk_bf16_f32 v152, v151, v152
	v_mul_f32_e32 v151, v46, v153
	v_mul_f32_e32 v153, v47, v154
	v_exp_f32_e64 v154, -v40
	v_exp_f32_e64 v155, -v41
	v_mul_f32_e32 v151, v151, v14
	v_mul_f32_e32 v153, v153, v15
	v_add_f32_e32 v154, 1.0, v154
	v_add_f32_e32 v155, 1.0, v155
	v_rcp_f32_e32 v154, v154
	v_rcp_f32_e32 v155, v155
	v_cvt_pk_bf16_f32 v153, v151, v153
	v_exp_f32_e64 v158, -v43
	v_mul_f32_e32 v151, v40, v154
	v_mul_f32_e32 v154, v41, v155
	v_exp_f32_e64 v155, -v42
	v_add_f32_e32 v158, 1.0, v158
	v_rcp_f32_e32 v158, v158
	v_mul_f32_e32 v151, v151, v8
	v_add_f32_e32 v155, 1.0, v155
	v_rcp_f32_e32 v155, v155
	v_mul_f32_e32 v154, v154, v9
	v_cvt_pk_bf16_f32 v154, v151, v154
	v_mul_f32_e32 v151, v42, v155
	v_mul_f32_e32 v155, v43, v158
	v_mul_f32_e32 v151, v151, v10
	v_mul_f32_e32 v155, v155, v11
	v_cvt_pk_bf16_f32 v155, v151, v155
	s_mul_i32 s98, s47, 160
	s_add_u32 s98, s16, s98
	s_addc_u32 s99, s17, 0
	global_store_dwordx4 v156, v[152:155], s[98:99]
	s_nop 0
	v_exp_f32_e64 v151, -v36
	v_exp_f32_e64 v152, -v37
	v_add_f32_e32 v150, 1.0, v151
	v_rcp_f32_e32 v153, v150
	v_add_f32_e32 v150, 1.0, v152
	v_rcp_f32_e32 v152, v150
	v_exp_f32_e64 v144, -v38
	v_exp_f32_e64 v145, -v39
	v_mul_f32_e32 v142, v36, v153
	v_mul_f32_e32 v143, v37, v152
	v_add_f32_e32 v144, 1.0, v144
	v_add_f32_e32 v145, 1.0, v145
	v_rcp_f32_e32 v144, v144
	v_rcp_f32_e32 v145, v145
	v_mul_f32_e32 v142, v142, v4
	v_mul_f32_e32 v143, v143, v5
	v_cvt_pk_bf16_f32 v142, v142, v143
	v_mul_f32_e32 v143, v38, v144
	v_mul_f32_e32 v144, v39, v145
	v_exp_f32_e64 v145, -v32
	v_exp_f32_e64 v152, -v33
	v_mul_f32_e32 v143, v143, v6
	v_mul_f32_e32 v144, v144, v7
	v_add_f32_e32 v145, 1.0, v145
	v_add_f32_e32 v152, 1.0, v152
	v_rcp_f32_e32 v145, v145
	v_rcp_f32_e32 v152, v152
	v_cvt_pk_bf16_f32 v143, v143, v144
	v_mul_f32_e32 v144, v32, v145
	v_mul_f32_e32 v145, v33, v152
	v_exp_f32_e64 v152, -v34
	v_exp_f32_e64 v153, -v35
	v_mul_f32_e32 v144, v144, v0
	v_mul_f32_e32 v145, v145, v1
	v_add_f32_e32 v152, 1.0, v152
	v_rcp_f32_e32 v152, v152
	v_add_f32_e32 v153, 1.0, v153
	v_rcp_f32_e32 v153, v153
	v_cvt_pk_bf16_f32 v144, v144, v145
	v_mul_f32_e32 v145, v34, v152
	v_mul_f32_e32 v145, v145, v2
	v_mul_f32_e32 v152, v35, v153
	v_mul_f32_e32 v152, v152, v3
	v_cvt_pk_bf16_f32 v145, v145, v152
	s_mul_i32 s98, s47, 176
	s_add_u32 s98, s16, s98
	s_addc_u32 s99, s17, 0
	global_store_dwordx4 v156, v[142:145], s[98:99]
	s_cbranch_vccnz .LBB0_1265
	s_andn2_b64 vcc, exec, s[10:11]
	s_cbranch_vccnz .LBB0_1264
	s_barrier
	s_branch .LBB0_1264
